# v11 + 103 LDS-DMA loads in GEMM main loops switched to SGPR-base saddr form (their v_lshl_add_u64 removed)
# baseline (speedup 1.0000x reference)
.LBB0_472:
	ds_read_b128 v[152:155], v148
	ds_read_b128 v[156:159], v148 offset:1024
	ds_read_b128 v[166:169], v148 offset:2048
	ds_read_b128 v[170:173], v148 offset:3072
	ds_read_b128 v[174:177], v149
	ds_read_b128 v[178:181], v149 offset:1024
	ds_read_b128 v[182:185], v149 offset:2048
	ds_read_b128 v[186:189], v149 offset:3072
	s_add_u32 s44, s54, 0xfff00080
	s_addc_u32 s56, s55, -1
	s_cmp_eq_u32 s72, 60
	s_cselect_b32 s59, s17, s56
	s_cselect_b32 s58, s68, s44
	s_cselect_b32 s57, s15, s71
	s_cselect_b32 s56, s69, s70
	s_add_i32 m0, s41, 0xc000
	ds_read_b128 v[190:193], v150
	ds_read_b128 v[194:197], v150 offset:1024
	ds_read_b128 v[198:201], v150 offset:2048
	ds_read_b128 v[202:205], v150 offset:3072
	ds_read_b128 v[206:209], v150 offset:4096
	ds_read_b128 v[210:213], v150 offset:5120
	ds_read_b128 v[214:217], v150 offset:6144
	ds_read_b128 v[218:221], v150 offset:7168
	global_load_lds_dwordx4 v138, s[54:55]
	s_add_i32 m0, s41, 0xe000
	s_nop 0
	global_load_lds_dwordx4 v140, s[54:55]
	s_waitcnt vmcnt(8)
	s_waitcnt lgkmcnt(0)
	s_barrier
	s_setprio 1
	s_waitcnt lgkmcnt(0)
	v_mfma_f32_16x16x32_bf16 v[126:129], v[152:155], v[190:193], v[126:129]
	v_mfma_f32_16x16x32_bf16 v[126:129], v[156:159], v[194:197], v[126:129]
	v_mfma_f32_16x16x32_bf16 v[122:125], v[170:173], v[194:197], v[122:125]
	v_mfma_f32_16x16x32_bf16 v[122:125], v[166:169], v[190:193], v[122:125]
	v_mfma_f32_16x16x32_bf16 v[110:113], v[166:169], v[198:201], v[110:113]
	v_mfma_f32_16x16x32_bf16 v[110:113], v[170:173], v[202:205], v[110:113]
	v_mfma_f32_16x16x32_bf16 v[118:121], v[156:159], v[202:205], v[118:121]
	v_mfma_f32_16x16x32_bf16 v[118:121], v[152:155], v[198:201], v[118:121]
	v_mfma_f32_16x16x32_bf16 v[102:105], v[152:155], v[206:209], v[102:105]
	v_mfma_f32_16x16x32_bf16 v[102:105], v[156:159], v[210:213], v[102:105]
	v_mfma_f32_16x16x32_bf16 v[94:97], v[170:173], v[210:213], v[94:97]
	v_mfma_f32_16x16x32_bf16 v[94:97], v[166:169], v[206:209], v[94:97]
	v_mfma_f32_16x16x32_bf16 v[78:81], v[166:169], v[214:217], v[78:81]
	v_mfma_f32_16x16x32_bf16 v[78:81], v[170:173], v[218:221], v[78:81]
	v_mfma_f32_16x16x32_bf16 v[86:89], v[156:159], v[218:221], v[86:89]
	v_mfma_f32_16x16x32_bf16 v[86:89], v[152:155], v[214:217], v[86:89]
	s_setprio 0
	s_setprio 1
	v_mfma_f32_16x16x32_bf16 v[114:117], v[174:177], v[190:193], v[114:117]
	v_mfma_f32_16x16x32_bf16 v[114:117], v[178:181], v[194:197], v[114:117]
	v_mfma_f32_16x16x32_bf16 v[106:109], v[186:189], v[194:197], v[106:109]
	v_mfma_f32_16x16x32_bf16 v[106:109], v[182:185], v[190:193], v[106:109]
	v_mfma_f32_16x16x32_bf16 v[90:93], v[182:185], v[198:201], v[90:93]
	v_mfma_f32_16x16x32_bf16 v[90:93], v[186:189], v[202:205], v[90:93]
	v_mfma_f32_16x16x32_bf16 v[98:101], v[178:181], v[202:205], v[98:101]
	v_mfma_f32_16x16x32_bf16 v[98:101], v[174:177], v[198:201], v[98:101]
	v_mfma_f32_16x16x32_bf16 v[82:85], v[174:177], v[206:209], v[82:85]
	v_mfma_f32_16x16x32_bf16 v[82:85], v[178:181], v[210:213], v[82:85]
	v_mfma_f32_16x16x32_bf16 v[74:77], v[186:189], v[210:213], v[74:77]
	v_mfma_f32_16x16x32_bf16 v[74:77], v[182:185], v[206:209], v[74:77]
	v_mfma_f32_16x16x32_bf16 v[66:69], v[182:185], v[214:217], v[66:69]
	v_mfma_f32_16x16x32_bf16 v[66:69], v[186:189], v[218:221], v[66:69]
	v_mfma_f32_16x16x32_bf16 v[70:73], v[178:181], v[218:221], v[70:73]
	v_mfma_f32_16x16x32_bf16 v[70:73], v[174:177], v[214:217], v[70:73]
	s_setprio 0
	s_barrier
	s_add_i32 s44, s64, s27
	v_lshl_add_u64 v[160:161], s[56:57], 0, v[134:135]
	s_mov_b32 m0, s44
	ds_read_b128 v[190:193], v150 offset:16384
	ds_read_b128 v[194:197], v150 offset:17408
	ds_read_b128 v[198:201], v150 offset:18432
	ds_read_b128 v[202:205], v150 offset:19456
	ds_read_b128 v[206:209], v150 offset:20480
	ds_read_b128 v[210:213], v150 offset:21504
	ds_read_b128 v[214:217], v150 offset:22528
	ds_read_b128 v[218:221], v150 offset:23552
	global_load_lds_dwordx4 v[160:161], off
	s_add_i32 m0, s44, 0x2000
	s_add_u32 s74, s56, 0x100000
	v_lshl_add_u64 v[222:223], s[56:57], 0, v[130:131]
	s_addc_u32 s75, s57, 0
	s_add_i32 s44, s65, s27
	global_load_lds_dwordx4 v[222:223], off
	s_mov_b32 m0, s44
	v_lshl_add_u64 v[226:227], s[58:59], 0, v[132:133]
	global_load_lds_dwordx4 v134, s[74:75]
	s_add_i32 m0, s44, 0x2000
	s_nop 0
	global_load_lds_dwordx4 v130, s[74:75]
	v_lshl_add_u64 v[224:225], s[58:59], 0, v[136:137]
	s_mov_b32 m0, s41
	s_nop 0
	global_load_lds_dwordx4 v[224:225], off
	s_mov_b32 m0, s43
	s_nop 0
	global_load_lds_dwordx4 v[226:227], off
	s_waitcnt vmcnt(8)
	s_waitcnt lgkmcnt(0)
	s_barrier
	s_setprio 1
	s_waitcnt lgkmcnt(0)
	v_mfma_f32_16x16x32_bf16 v[62:65], v[152:155], v[190:193], v[62:65]
	v_mfma_f32_16x16x32_bf16 v[62:65], v[156:159], v[194:197], v[62:65]
	v_mfma_f32_16x16x32_bf16 v[58:61], v[170:173], v[194:197], v[58:61]
	v_mfma_f32_16x16x32_bf16 v[58:61], v[166:169], v[190:193], v[58:61]
	v_mfma_f32_16x16x32_bf16 v[46:49], v[166:169], v[198:201], v[46:49]
	v_mfma_f32_16x16x32_bf16 v[46:49], v[170:173], v[202:205], v[46:49]
	v_mfma_f32_16x16x32_bf16 v[54:57], v[156:159], v[202:205], v[54:57]
	v_mfma_f32_16x16x32_bf16 v[54:57], v[152:155], v[198:201], v[54:57]
	v_mfma_f32_16x16x32_bf16 v[38:41], v[152:155], v[206:209], v[38:41]
	v_mfma_f32_16x16x32_bf16 v[38:41], v[156:159], v[210:213], v[38:41]
	v_mfma_f32_16x16x32_bf16 v[30:33], v[170:173], v[210:213], v[30:33]
	v_mfma_f32_16x16x32_bf16 v[30:33], v[166:169], v[206:209], v[30:33]
	v_mfma_f32_16x16x32_bf16 v[14:17], v[166:169], v[214:217], v[14:17]
	v_mfma_f32_16x16x32_bf16 v[14:17], v[170:173], v[218:221], v[14:17]
	v_mfma_f32_16x16x32_bf16 v[22:25], v[156:159], v[218:221], v[22:25]
	v_mfma_f32_16x16x32_bf16 v[22:25], v[152:155], v[214:217], v[22:25]
	s_setprio 0
	s_setprio 1
	v_mfma_f32_16x16x32_bf16 v[50:53], v[174:177], v[190:193], v[50:53]
	v_mfma_f32_16x16x32_bf16 v[50:53], v[178:181], v[194:197], v[50:53]
	v_mfma_f32_16x16x32_bf16 v[42:45], v[186:189], v[194:197], v[42:45]
	v_mfma_f32_16x16x32_bf16 v[42:45], v[182:185], v[190:193], v[42:45]
	v_mfma_f32_16x16x32_bf16 v[26:29], v[182:185], v[198:201], v[26:29]
	v_mfma_f32_16x16x32_bf16 v[26:29], v[186:189], v[202:205], v[26:29]
	v_mfma_f32_16x16x32_bf16 v[34:37], v[178:181], v[202:205], v[34:37]
	v_mfma_f32_16x16x32_bf16 v[34:37], v[174:177], v[198:201], v[34:37]
	v_mfma_f32_16x16x32_bf16 v[18:21], v[174:177], v[206:209], v[18:21]
	v_mfma_f32_16x16x32_bf16 v[18:21], v[178:181], v[210:213], v[18:21]
	v_mfma_f32_16x16x32_bf16 v[10:13], v[186:189], v[210:213], v[10:13]
	v_mfma_f32_16x16x32_bf16 v[10:13], v[182:185], v[206:209], v[10:13]
	v_mfma_f32_16x16x32_bf16 v[2:5], v[182:185], v[214:217], v[2:5]
	v_mfma_f32_16x16x32_bf16 v[2:5], v[186:189], v[218:221], v[2:5]
	v_mfma_f32_16x16x32_bf16 v[6:9], v[178:181], v[218:221], v[6:9]
	v_mfma_f32_16x16x32_bf16 v[6:9], v[174:177], v[214:217], v[6:9]
	s_setprio 0
	s_barrier
	s_add_i32 s44, 0, 0x18000
	v_add_u32_e32 v151, s44, v146
	s_add_i32 s73, 0, 0x1c000
	ds_read_b128 v[152:155], v151
	ds_read_b128 v[156:159], v151 offset:1024
	ds_read_b128 v[166:169], v151 offset:2048
	ds_read_b128 v[170:173], v151 offset:3072
	v_add_u32_e32 v151, s73, v146
	ds_read_b128 v[174:177], v151
	ds_read_b128 v[178:181], v151 offset:1024
	ds_read_b128 v[182:185], v151 offset:2048
	ds_read_b128 v[186:189], v151 offset:3072
	s_add_u32 s58, s58, 0x100000
	s_addc_u32 s59, s59, 0
	s_mov_b32 m0, s45
	ds_read_b128 v[190:193], v150 offset:32768
	ds_read_b128 v[194:197], v150 offset:33792
	ds_read_b128 v[198:201], v150 offset:34816
	ds_read_b128 v[202:205], v150 offset:35840
	ds_read_b128 v[206:209], v150 offset:36864
	ds_read_b128 v[210:213], v150 offset:37888
	ds_read_b128 v[214:217], v150 offset:38912
	ds_read_b128 v[218:221], v150 offset:39936
	global_load_lds_dwordx4 v136, s[58:59]
	s_mov_b32 m0, s53
	s_nop 0
	global_load_lds_dwordx4 v132, s[58:59]
	s_waitcnt vmcnt(8)
	s_waitcnt lgkmcnt(0)
	s_barrier
	s_setprio 1
	s_waitcnt lgkmcnt(0)
	v_mfma_f32_16x16x32_bf16 v[126:129], v[152:155], v[190:193], v[126:129]
	v_mfma_f32_16x16x32_bf16 v[126:129], v[156:159], v[194:197], v[126:129]
	v_mfma_f32_16x16x32_bf16 v[122:125], v[170:173], v[194:197], v[122:125]
	v_mfma_f32_16x16x32_bf16 v[122:125], v[166:169], v[190:193], v[122:125]
	v_mfma_f32_16x16x32_bf16 v[110:113], v[166:169], v[198:201], v[110:113]
	v_mfma_f32_16x16x32_bf16 v[110:113], v[170:173], v[202:205], v[110:113]
	v_mfma_f32_16x16x32_bf16 v[118:121], v[156:159], v[202:205], v[118:121]
	v_mfma_f32_16x16x32_bf16 v[118:121], v[152:155], v[198:201], v[118:121]
	v_mfma_f32_16x16x32_bf16 v[102:105], v[152:155], v[206:209], v[102:105]
	v_mfma_f32_16x16x32_bf16 v[102:105], v[156:159], v[210:213], v[102:105]
	v_mfma_f32_16x16x32_bf16 v[94:97], v[170:173], v[210:213], v[94:97]
	v_mfma_f32_16x16x32_bf16 v[94:97], v[166:169], v[206:209], v[94:97]
	v_mfma_f32_16x16x32_bf16 v[78:81], v[166:169], v[214:217], v[78:81]
	v_mfma_f32_16x16x32_bf16 v[78:81], v[170:173], v[218:221], v[78:81]
	v_mfma_f32_16x16x32_bf16 v[86:89], v[156:159], v[218:221], v[86:89]
	v_mfma_f32_16x16x32_bf16 v[86:89], v[152:155], v[214:217], v[86:89]
	s_setprio 0
	s_setprio 1
	v_mfma_f32_16x16x32_bf16 v[114:117], v[174:177], v[190:193], v[114:117]
	v_mfma_f32_16x16x32_bf16 v[114:117], v[178:181], v[194:197], v[114:117]
	v_mfma_f32_16x16x32_bf16 v[106:109], v[186:189], v[194:197], v[106:109]
	v_mfma_f32_16x16x32_bf16 v[106:109], v[182:185], v[190:193], v[106:109]
	v_mfma_f32_16x16x32_bf16 v[90:93], v[182:185], v[198:201], v[90:93]
	v_mfma_f32_16x16x32_bf16 v[90:93], v[186:189], v[202:205], v[90:93]
	v_mfma_f32_16x16x32_bf16 v[98:101], v[178:181], v[202:205], v[98:101]
	v_mfma_f32_16x16x32_bf16 v[98:101], v[174:177], v[198:201], v[98:101]
	v_mfma_f32_16x16x32_bf16 v[82:85], v[174:177], v[206:209], v[82:85]
	v_mfma_f32_16x16x32_bf16 v[82:85], v[178:181], v[210:213], v[82:85]
	v_mfma_f32_16x16x32_bf16 v[74:77], v[186:189], v[210:213], v[74:77]
	v_mfma_f32_16x16x32_bf16 v[74:77], v[182:185], v[206:209], v[74:77]
	v_mfma_f32_16x16x32_bf16 v[66:69], v[182:185], v[214:217], v[66:69]
	v_mfma_f32_16x16x32_bf16 v[66:69], v[186:189], v[218:221], v[66:69]
	v_mfma_f32_16x16x32_bf16 v[70:73], v[178:181], v[218:221], v[70:73]
	v_mfma_f32_16x16x32_bf16 v[70:73], v[174:177], v[214:217], v[70:73]
	s_setprio 0
	s_barrier
	s_add_i32 s44, s44, s27
	v_lshl_add_u64 v[160:161], v[160:161], 0, s[10:11]
	s_mov_b32 m0, s44
	ds_read_b128 v[190:193], v150 offset:49152
	ds_read_b128 v[194:197], v150 offset:50176
	ds_read_b128 v[198:201], v150 offset:51200
	ds_read_b128 v[202:205], v150 offset:52224
	ds_read_b128 v[206:209], v150 offset:53248
	ds_read_b128 v[210:213], v150 offset:54272
	ds_read_b128 v[214:217], v150 offset:55296
	ds_read_b128 v[218:221], v150 offset:56320
	global_load_lds_dwordx4 v[160:161], off
	s_add_i32 m0, s44, 0x2000
	s_add_u32 s56, s56, 0x100080
	v_lshl_add_u64 v[160:161], v[222:223], 0, s[10:11]
	s_addc_u32 s57, s57, 0
	s_add_i32 s44, s73, s27
	global_load_lds_dwordx4 v[160:161], off
	s_mov_b32 m0, s44
	s_nop 0
	global_load_lds_dwordx4 v134, s[56:57]
	s_add_i32 m0, s44, 0x2000
	s_nop 0
	global_load_lds_dwordx4 v130, s[56:57]
	v_lshl_add_u64 v[160:161], v[224:225], 0, s[10:11]
	s_mov_b32 m0, s61
	s_nop 0
	global_load_lds_dwordx4 v[160:161], off
	v_lshl_add_u64 v[160:161], v[226:227], 0, s[10:11]
	s_mov_b32 m0, s62
	s_nop 0
	global_load_lds_dwordx4 v[160:161], off
	s_waitcnt vmcnt(8)
	s_waitcnt lgkmcnt(0)
	s_barrier
	s_setprio 1
	s_waitcnt lgkmcnt(0)
	v_mfma_f32_16x16x32_bf16 v[62:65], v[152:155], v[190:193], v[62:65]
	v_mfma_f32_16x16x32_bf16 v[62:65], v[156:159], v[194:197], v[62:65]
	v_mfma_f32_16x16x32_bf16 v[58:61], v[170:173], v[194:197], v[58:61]
	v_mfma_f32_16x16x32_bf16 v[58:61], v[166:169], v[190:193], v[58:61]
	v_mfma_f32_16x16x32_bf16 v[46:49], v[166:169], v[198:201], v[46:49]
	v_mfma_f32_16x16x32_bf16 v[46:49], v[170:173], v[202:205], v[46:49]
	v_mfma_f32_16x16x32_bf16 v[54:57], v[156:159], v[202:205], v[54:57]
	v_mfma_f32_16x16x32_bf16 v[54:57], v[152:155], v[198:201], v[54:57]
	v_mfma_f32_16x16x32_bf16 v[38:41], v[152:155], v[206:209], v[38:41]
	v_mfma_f32_16x16x32_bf16 v[38:41], v[156:159], v[210:213], v[38:41]
	v_mfma_f32_16x16x32_bf16 v[30:33], v[170:173], v[210:213], v[30:33]
	v_mfma_f32_16x16x32_bf16 v[30:33], v[166:169], v[206:209], v[30:33]
	v_mfma_f32_16x16x32_bf16 v[14:17], v[166:169], v[214:217], v[14:17]
	v_mfma_f32_16x16x32_bf16 v[14:17], v[170:173], v[218:221], v[14:17]
	v_mfma_f32_16x16x32_bf16 v[22:25], v[156:159], v[218:221], v[22:25]
	v_mfma_f32_16x16x32_bf16 v[22:25], v[152:155], v[214:217], v[22:25]
	s_setprio 0
	s_setprio 1
	v_mfma_f32_16x16x32_bf16 v[50:53], v[174:177], v[190:193], v[50:53]
	v_mfma_f32_16x16x32_bf16 v[50:53], v[178:181], v[194:197], v[50:53]
	v_mfma_f32_16x16x32_bf16 v[42:45], v[186:189], v[194:197], v[42:45]
	v_mfma_f32_16x16x32_bf16 v[42:45], v[182:185], v[190:193], v[42:45]
	v_mfma_f32_16x16x32_bf16 v[26:29], v[182:185], v[198:201], v[26:29]
	v_mfma_f32_16x16x32_bf16 v[26:29], v[186:189], v[202:205], v[26:29]
	v_mfma_f32_16x16x32_bf16 v[34:37], v[178:181], v[202:205], v[34:37]
	v_mfma_f32_16x16x32_bf16 v[34:37], v[174:177], v[198:201], v[34:37]
	v_mfma_f32_16x16x32_bf16 v[18:21], v[174:177], v[206:209], v[18:21]
	v_mfma_f32_16x16x32_bf16 v[18:21], v[178:181], v[210:213], v[18:21]
	v_mfma_f32_16x16x32_bf16 v[10:13], v[186:189], v[210:213], v[10:13]
	v_mfma_f32_16x16x32_bf16 v[10:13], v[182:185], v[206:209], v[10:13]
	v_mfma_f32_16x16x32_bf16 v[2:5], v[182:185], v[214:217], v[2:5]
	v_mfma_f32_16x16x32_bf16 v[2:5], v[186:189], v[218:221], v[2:5]
	v_mfma_f32_16x16x32_bf16 v[6:9], v[178:181], v[218:221], v[6:9]
	v_mfma_f32_16x16x32_bf16 v[6:9], v[174:177], v[214:217], v[6:9]
	s_setprio 0
	s_barrier
	s_add_i32 s72, s72, 2
	s_add_u32 s54, s54, 0x100
	s_addc_u32 s55, s55, 0
	s_add_u32 s70, s70, 0x100
	s_addc_u32 s71, s71, 0
	s_cmp_gt_u32 s72, 61
	s_cbranch_scc0 .LBB0_472
	s_and_b64 vcc, exec, s[12:13]
	s_cbranch_vccz .LBB0_475
	s_barrier

.LBB0_706:
	s_add_u32 s72, s60, s44
	s_addc_u32 s73, s61, 0
	s_add_u32 s68, s72, 0x100
	s_addc_u32 s69, s73, 0
	s_and_b64 s[66:67], s[64:65], exec
	s_cselect_b32 s69, s17, s69
	s_cselect_b32 s68, s86, s68
	s_add_u32 s44, s56, s44
	s_addc_u32 s66, s57, 0
	s_add_u32 s44, s44, 0x100
	s_addc_u32 s66, s66, 0
	s_and_b64 s[64:65], s[64:65], exec
	s_cselect_b32 s71, s15, s66
	s_cselect_b32 s70, s87, s44
	s_add_u32 s74, s72, 0x10080
	s_addc_u32 s75, s73, 0
	s_add_i32 vcc_hi, s82, s27
	ds_read_b128 v[150:153], v147
	ds_read_b128 v[154:157], v147 offset:1024
	ds_read_b128 v[158:161], v147 offset:2048
	ds_read_b128 v[166:169], v147 offset:3072
	ds_read_b128 v[170:173], v148
	ds_read_b128 v[174:177], v148 offset:1024
	ds_read_b128 v[178:181], v148 offset:2048
	ds_read_b128 v[182:185], v148 offset:3072
	s_add_i32 m0, s36, 0xc000
	s_add_i32 s45, s36, 0xe000
	s_add_i32 s96, vcc_hi, 0x2000
	s_add_u32 s72, s70, 0x10000
	s_addc_u32 s73, s71, 0
	s_add_i32 vcc_lo, s83, s27
	s_add_i32 s97, vcc_lo, 0x2000
	s_add_i32 s95, 0, 0x18000
	s_add_i32 s94, 0, 0x1c000
	s_add_u32 s66, s68, 0x10000
	s_addc_u32 s67, s69, 0
	s_add_i32 s93, s95, s27
	s_add_i32 s89, s93, 0x2000
	s_add_u32 s64, s70, 0x10080
	s_addc_u32 s65, s71, 0
	s_add_i32 s92, s94, s27
	s_add_i32 s44, s92, 0x2000
	ds_read_b128 v[186:189], v149
	ds_read_b128 v[190:193], v149 offset:1024
	ds_read_b128 v[194:197], v149 offset:2048
	ds_read_b128 v[202:205], v149 offset:3072
	ds_read_b128 v[206:209], v149 offset:4096
	ds_read_b128 v[210:213], v149 offset:5120
	ds_read_b128 v[214:217], v149 offset:6144
	ds_read_b128 v[218:221], v149 offset:7168
	global_load_lds_dwordx4 v130, s[74:75]
	s_mov_b32 m0, s45
	s_nop 0
	global_load_lds_dwordx4 v134, s[74:75]
	s_waitcnt vmcnt(8)
	s_waitcnt lgkmcnt(0)
	s_barrier
	s_setprio 1
	s_waitcnt lgkmcnt(0)
	v_mfma_f32_16x16x32_bf16 v[126:129], v[150:153], v[186:189], v[126:129]
	v_mfma_f32_16x16x32_bf16 v[126:129], v[154:157], v[190:193], v[126:129]
	v_mfma_f32_16x16x32_bf16 v[122:125], v[166:169], v[190:193], v[122:125]
	v_mfma_f32_16x16x32_bf16 v[122:125], v[158:161], v[186:189], v[122:125]
	v_mfma_f32_16x16x32_bf16 v[110:113], v[158:161], v[194:197], v[110:113]
	v_mfma_f32_16x16x32_bf16 v[110:113], v[166:169], v[202:205], v[110:113]
	v_mfma_f32_16x16x32_bf16 v[118:121], v[154:157], v[202:205], v[118:121]
	v_mfma_f32_16x16x32_bf16 v[118:121], v[150:153], v[194:197], v[118:121]
	v_mfma_f32_16x16x32_bf16 v[102:105], v[150:153], v[206:209], v[102:105]
	v_mfma_f32_16x16x32_bf16 v[102:105], v[154:157], v[210:213], v[102:105]
	v_mfma_f32_16x16x32_bf16 v[94:97], v[166:169], v[210:213], v[94:97]
	v_mfma_f32_16x16x32_bf16 v[94:97], v[158:161], v[206:209], v[94:97]
	v_mfma_f32_16x16x32_bf16 v[78:81], v[158:161], v[214:217], v[78:81]
	v_mfma_f32_16x16x32_bf16 v[78:81], v[166:169], v[218:221], v[78:81]
	v_mfma_f32_16x16x32_bf16 v[86:89], v[154:157], v[218:221], v[86:89]
	v_mfma_f32_16x16x32_bf16 v[86:89], v[150:153], v[214:217], v[86:89]
	s_setprio 0
	s_setprio 1
	v_mfma_f32_16x16x32_bf16 v[114:117], v[170:173], v[186:189], v[114:117]
	v_mfma_f32_16x16x32_bf16 v[114:117], v[174:177], v[190:193], v[114:117]
	v_mfma_f32_16x16x32_bf16 v[106:109], v[182:185], v[190:193], v[106:109]
	v_mfma_f32_16x16x32_bf16 v[106:109], v[178:181], v[186:189], v[106:109]
	v_mfma_f32_16x16x32_bf16 v[90:93], v[178:181], v[194:197], v[90:93]
	v_mfma_f32_16x16x32_bf16 v[90:93], v[182:185], v[202:205], v[90:93]
	v_mfma_f32_16x16x32_bf16 v[98:101], v[174:177], v[202:205], v[98:101]
	v_mfma_f32_16x16x32_bf16 v[98:101], v[170:173], v[194:197], v[98:101]
	v_mfma_f32_16x16x32_bf16 v[82:85], v[170:173], v[206:209], v[82:85]
	v_mfma_f32_16x16x32_bf16 v[82:85], v[174:177], v[210:213], v[82:85]
	v_mfma_f32_16x16x32_bf16 v[74:77], v[182:185], v[210:213], v[74:77]
	v_mfma_f32_16x16x32_bf16 v[74:77], v[178:181], v[206:209], v[74:77]
	v_mfma_f32_16x16x32_bf16 v[66:69], v[178:181], v[214:217], v[66:69]
	v_mfma_f32_16x16x32_bf16 v[66:69], v[182:185], v[218:221], v[66:69]
	v_mfma_f32_16x16x32_bf16 v[70:73], v[174:177], v[218:221], v[70:73]
	v_mfma_f32_16x16x32_bf16 v[70:73], v[170:173], v[214:217], v[70:73]
	s_setprio 0
	s_barrier
	s_mov_b32 m0, vcc_hi
	v_lshl_add_u64 v[198:199], s[70:71], 0, v[132:133]
	ds_read_b128 v[186:189], v149 offset:16384
	ds_read_b128 v[190:193], v149 offset:17408
	ds_read_b128 v[194:197], v149 offset:18432
	ds_read_b128 v[202:205], v149 offset:19456
	ds_read_b128 v[206:209], v149 offset:20480
	ds_read_b128 v[210:213], v149 offset:21504
	ds_read_b128 v[214:217], v149 offset:22528
	ds_read_b128 v[218:221], v149 offset:23552
	global_load_lds_dwordx4 v[198:199], off
	v_lshl_add_u64 v[222:223], s[70:71], 0, v[136:137]
	s_mov_b32 m0, s96
	s_nop 0
	global_load_lds_dwordx4 v[222:223], off
	s_mov_b32 m0, vcc_lo
	v_lshl_add_u64 v[226:227], s[68:69], 0, v[134:135]
	global_load_lds_dwordx4 v132, s[72:73]
	s_mov_b32 m0, s97
	s_nop 0
	global_load_lds_dwordx4 v136, s[72:73]
	v_lshl_add_u64 v[224:225], s[68:69], 0, v[130:131]
	s_mov_b32 m0, s36
	s_nop 0
	global_load_lds_dwordx4 v[224:225], off
	s_mov_b32 m0, s55
	s_nop 0
	global_load_lds_dwordx4 v[226:227], off
	s_waitcnt vmcnt(8)
	s_waitcnt lgkmcnt(0)
	s_barrier
	s_setprio 1
	s_waitcnt lgkmcnt(0)
	v_mfma_f32_16x16x32_bf16 v[62:65], v[150:153], v[186:189], v[62:65]
	v_mfma_f32_16x16x32_bf16 v[62:65], v[154:157], v[190:193], v[62:65]
	v_mfma_f32_16x16x32_bf16 v[58:61], v[166:169], v[190:193], v[58:61]
	v_mfma_f32_16x16x32_bf16 v[58:61], v[158:161], v[186:189], v[58:61]
	v_mfma_f32_16x16x32_bf16 v[46:49], v[158:161], v[194:197], v[46:49]
	v_mfma_f32_16x16x32_bf16 v[46:49], v[166:169], v[202:205], v[46:49]
	v_mfma_f32_16x16x32_bf16 v[54:57], v[154:157], v[202:205], v[54:57]
	v_mfma_f32_16x16x32_bf16 v[54:57], v[150:153], v[194:197], v[54:57]
	v_mfma_f32_16x16x32_bf16 v[38:41], v[150:153], v[206:209], v[38:41]
	v_mfma_f32_16x16x32_bf16 v[38:41], v[154:157], v[210:213], v[38:41]
	v_mfma_f32_16x16x32_bf16 v[30:33], v[166:169], v[210:213], v[30:33]
	v_mfma_f32_16x16x32_bf16 v[30:33], v[158:161], v[206:209], v[30:33]
	v_mfma_f32_16x16x32_bf16 v[14:17], v[158:161], v[214:217], v[14:17]
	v_mfma_f32_16x16x32_bf16 v[14:17], v[166:169], v[218:221], v[14:17]
	v_mfma_f32_16x16x32_bf16 v[22:25], v[154:157], v[218:221], v[22:25]
	v_mfma_f32_16x16x32_bf16 v[22:25], v[150:153], v[214:217], v[22:25]
	s_setprio 0
	s_setprio 1
	v_mfma_f32_16x16x32_bf16 v[50:53], v[170:173], v[186:189], v[50:53]
	v_mfma_f32_16x16x32_bf16 v[50:53], v[174:177], v[190:193], v[50:53]
	v_mfma_f32_16x16x32_bf16 v[42:45], v[182:185], v[190:193], v[42:45]
	v_mfma_f32_16x16x32_bf16 v[42:45], v[178:181], v[186:189], v[42:45]
	v_mfma_f32_16x16x32_bf16 v[26:29], v[178:181], v[194:197], v[26:29]
	v_mfma_f32_16x16x32_bf16 v[26:29], v[182:185], v[202:205], v[26:29]
	v_mfma_f32_16x16x32_bf16 v[34:37], v[174:177], v[202:205], v[34:37]
	v_mfma_f32_16x16x32_bf16 v[34:37], v[170:173], v[194:197], v[34:37]
	v_mfma_f32_16x16x32_bf16 v[18:21], v[170:173], v[206:209], v[18:21]
	v_mfma_f32_16x16x32_bf16 v[18:21], v[174:177], v[210:213], v[18:21]
	v_mfma_f32_16x16x32_bf16 v[10:13], v[182:185], v[210:213], v[10:13]
	v_mfma_f32_16x16x32_bf16 v[10:13], v[178:181], v[206:209], v[10:13]
	v_mfma_f32_16x16x32_bf16 v[2:5], v[178:181], v[214:217], v[2:5]
	v_mfma_f32_16x16x32_bf16 v[2:5], v[182:185], v[218:221], v[2:5]
	v_mfma_f32_16x16x32_bf16 v[6:9], v[174:177], v[218:221], v[6:9]
	v_mfma_f32_16x16x32_bf16 v[6:9], v[170:173], v[214:217], v[6:9]
	s_setprio 0
	s_barrier
	v_add_u32_e32 v166, s95, v145
	v_add_u32_e32 v182, s94, v145
	ds_read_b128 v[150:153], v166
	ds_read_b128 v[154:157], v166 offset:1024
	ds_read_b128 v[158:161], v166 offset:2048
	ds_read_b128 v[166:169], v166 offset:3072
	ds_read_b128 v[170:173], v182
	ds_read_b128 v[174:177], v182 offset:1024
	ds_read_b128 v[178:181], v182 offset:2048
	ds_read_b128 v[182:185], v182 offset:3072
	s_mov_b32 m0, s76
	ds_read_b128 v[186:189], v149 offset:32768
	ds_read_b128 v[190:193], v149 offset:33792
	ds_read_b128 v[194:197], v149 offset:34816
	ds_read_b128 v[202:205], v149 offset:35840
	ds_read_b128 v[206:209], v149 offset:36864
	ds_read_b128 v[210:213], v149 offset:37888
	ds_read_b128 v[214:217], v149 offset:38912
	ds_read_b128 v[218:221], v149 offset:39936
	global_load_lds_dwordx4 v130, s[66:67]
	s_mov_b32 m0, s77
	s_nop 0
	global_load_lds_dwordx4 v134, s[66:67]
	s_waitcnt vmcnt(8)
	s_waitcnt lgkmcnt(0)
	s_barrier
	s_setprio 1
	s_waitcnt lgkmcnt(0)
	v_mfma_f32_16x16x32_bf16 v[126:129], v[150:153], v[186:189], v[126:129]
	v_mfma_f32_16x16x32_bf16 v[126:129], v[154:157], v[190:193], v[126:129]
	v_mfma_f32_16x16x32_bf16 v[122:125], v[166:169], v[190:193], v[122:125]
	v_mfma_f32_16x16x32_bf16 v[122:125], v[158:161], v[186:189], v[122:125]
	v_mfma_f32_16x16x32_bf16 v[110:113], v[158:161], v[194:197], v[110:113]
	v_mfma_f32_16x16x32_bf16 v[110:113], v[166:169], v[202:205], v[110:113]
	v_mfma_f32_16x16x32_bf16 v[118:121], v[154:157], v[202:205], v[118:121]
	v_mfma_f32_16x16x32_bf16 v[118:121], v[150:153], v[194:197], v[118:121]
	v_mfma_f32_16x16x32_bf16 v[102:105], v[150:153], v[206:209], v[102:105]
	v_mfma_f32_16x16x32_bf16 v[102:105], v[154:157], v[210:213], v[102:105]
	v_mfma_f32_16x16x32_bf16 v[94:97], v[166:169], v[210:213], v[94:97]
	v_mfma_f32_16x16x32_bf16 v[94:97], v[158:161], v[206:209], v[94:97]
	v_mfma_f32_16x16x32_bf16 v[78:81], v[158:161], v[214:217], v[78:81]
	v_mfma_f32_16x16x32_bf16 v[78:81], v[166:169], v[218:221], v[78:81]
	v_mfma_f32_16x16x32_bf16 v[86:89], v[154:157], v[218:221], v[86:89]
	v_mfma_f32_16x16x32_bf16 v[86:89], v[150:153], v[214:217], v[86:89]
	s_setprio 0
	s_setprio 1
	v_mfma_f32_16x16x32_bf16 v[114:117], v[170:173], v[186:189], v[114:117]
	v_mfma_f32_16x16x32_bf16 v[114:117], v[174:177], v[190:193], v[114:117]
	v_mfma_f32_16x16x32_bf16 v[106:109], v[182:185], v[190:193], v[106:109]
	v_mfma_f32_16x16x32_bf16 v[106:109], v[178:181], v[186:189], v[106:109]
	v_mfma_f32_16x16x32_bf16 v[90:93], v[178:181], v[194:197], v[90:93]
	v_mfma_f32_16x16x32_bf16 v[90:93], v[182:185], v[202:205], v[90:93]
	v_mfma_f32_16x16x32_bf16 v[98:101], v[174:177], v[202:205], v[98:101]
	v_mfma_f32_16x16x32_bf16 v[98:101], v[170:173], v[194:197], v[98:101]
	v_mfma_f32_16x16x32_bf16 v[82:85], v[170:173], v[206:209], v[82:85]
	v_mfma_f32_16x16x32_bf16 v[82:85], v[174:177], v[210:213], v[82:85]
	v_mfma_f32_16x16x32_bf16 v[74:77], v[182:185], v[210:213], v[74:77]
	v_mfma_f32_16x16x32_bf16 v[74:77], v[178:181], v[206:209], v[74:77]
	v_mfma_f32_16x16x32_bf16 v[66:69], v[178:181], v[214:217], v[66:69]
	v_mfma_f32_16x16x32_bf16 v[66:69], v[182:185], v[218:221], v[66:69]
	v_mfma_f32_16x16x32_bf16 v[70:73], v[174:177], v[218:221], v[70:73]
	v_mfma_f32_16x16x32_bf16 v[70:73], v[170:173], v[214:217], v[70:73]
	s_setprio 0
	s_barrier
	s_mov_b32 m0, s93
	v_lshl_add_u64 v[198:199], v[198:199], 0, s[10:11]
	ds_read_b128 v[186:189], v149 offset:49152
	ds_read_b128 v[190:193], v149 offset:50176
	ds_read_b128 v[194:197], v149 offset:51200
	ds_read_b128 v[202:205], v149 offset:52224
	ds_read_b128 v[206:209], v149 offset:53248
	ds_read_b128 v[210:213], v149 offset:54272
	ds_read_b128 v[214:217], v149 offset:55296
	ds_read_b128 v[218:221], v149 offset:56320
	global_load_lds_dwordx4 v[198:199], off
	v_lshl_add_u64 v[198:199], v[222:223], 0, s[10:11]
	s_mov_b32 m0, s89
	s_nop 0
	global_load_lds_dwordx4 v[198:199], off
	s_mov_b32 m0, s92
	s_nop 0
	global_load_lds_dwordx4 v132, s[64:65]
	s_mov_b32 m0, s44
	s_nop 0
	global_load_lds_dwordx4 v136, s[64:65]
	v_lshl_add_u64 v[198:199], v[224:225], 0, s[10:11]
	s_mov_b32 m0, s79
	s_nop 0
	global_load_lds_dwordx4 v[198:199], off
	v_lshl_add_u64 v[198:199], v[226:227], 0, s[10:11]
	s_mov_b32 m0, s80
	s_nop 0
	global_load_lds_dwordx4 v[198:199], off
	s_waitcnt vmcnt(8)
	s_waitcnt lgkmcnt(0)
	s_barrier
	s_setprio 1
	s_waitcnt lgkmcnt(0)
	v_mfma_f32_16x16x32_bf16 v[62:65], v[150:153], v[186:189], v[62:65]
	v_mfma_f32_16x16x32_bf16 v[62:65], v[154:157], v[190:193], v[62:65]
	v_mfma_f32_16x16x32_bf16 v[58:61], v[166:169], v[190:193], v[58:61]
	v_mfma_f32_16x16x32_bf16 v[58:61], v[158:161], v[186:189], v[58:61]
	v_mfma_f32_16x16x32_bf16 v[46:49], v[158:161], v[194:197], v[46:49]
	v_mfma_f32_16x16x32_bf16 v[46:49], v[166:169], v[202:205], v[46:49]
	v_mfma_f32_16x16x32_bf16 v[54:57], v[154:157], v[202:205], v[54:57]
	v_mfma_f32_16x16x32_bf16 v[54:57], v[150:153], v[194:197], v[54:57]
	v_mfma_f32_16x16x32_bf16 v[38:41], v[150:153], v[206:209], v[38:41]
	v_mfma_f32_16x16x32_bf16 v[38:41], v[154:157], v[210:213], v[38:41]
	v_mfma_f32_16x16x32_bf16 v[30:33], v[166:169], v[210:213], v[30:33]
	v_mfma_f32_16x16x32_bf16 v[30:33], v[158:161], v[206:209], v[30:33]
	v_mfma_f32_16x16x32_bf16 v[14:17], v[158:161], v[214:217], v[14:17]
	v_mfma_f32_16x16x32_bf16 v[14:17], v[166:169], v[218:221], v[14:17]
	v_mfma_f32_16x16x32_bf16 v[22:25], v[154:157], v[218:221], v[22:25]
	v_mfma_f32_16x16x32_bf16 v[22:25], v[150:153], v[214:217], v[22:25]
	s_setprio 0
	s_setprio 1
	v_mfma_f32_16x16x32_bf16 v[50:53], v[170:173], v[186:189], v[50:53]
	v_mfma_f32_16x16x32_bf16 v[50:53], v[174:177], v[190:193], v[50:53]
	v_mfma_f32_16x16x32_bf16 v[42:45], v[182:185], v[190:193], v[42:45]
	v_mfma_f32_16x16x32_bf16 v[42:45], v[178:181], v[186:189], v[42:45]
	v_mfma_f32_16x16x32_bf16 v[26:29], v[178:181], v[194:197], v[26:29]
	v_mfma_f32_16x16x32_bf16 v[26:29], v[182:185], v[202:205], v[26:29]
	v_mfma_f32_16x16x32_bf16 v[34:37], v[174:177], v[202:205], v[34:37]
	v_mfma_f32_16x16x32_bf16 v[34:37], v[170:173], v[194:197], v[34:37]
	v_mfma_f32_16x16x32_bf16 v[18:21], v[170:173], v[206:209], v[18:21]
	v_mfma_f32_16x16x32_bf16 v[18:21], v[174:177], v[210:213], v[18:21]
	v_mfma_f32_16x16x32_bf16 v[10:13], v[182:185], v[210:213], v[10:13]
	v_mfma_f32_16x16x32_bf16 v[10:13], v[178:181], v[206:209], v[10:13]
	v_mfma_f32_16x16x32_bf16 v[2:5], v[178:181], v[214:217], v[2:5]
	v_mfma_f32_16x16x32_bf16 v[2:5], v[182:185], v[218:221], v[2:5]
	v_mfma_f32_16x16x32_bf16 v[6:9], v[174:177], v[218:221], v[6:9]
	v_mfma_f32_16x16x32_bf16 v[6:9], v[170:173], v[214:217], v[6:9]
	s_setprio 0
	s_barrier
	s_movk_i32 s44, 0x100
	s_andn2_b64 vcc, exec, s[62:63]
	s_mov_b64 s[64:65], -1
	s_mov_b64 s[62:63], 0
	s_cbranch_vccz .LBB0_706
	s_and_b64 vcc, exec, s[12:13]
	s_cbranch_vccz .LBB0_709
	s_barrier

.LBB0_722:
	s_add_u32 s36, s56, s44
	s_addc_u32 s37, s57, 0
	s_add_u32 s66, s36, 0x100
	s_addc_u32 s67, s37, 0
	s_and_b64 s[64:65], s[62:63], exec
	s_cselect_b32 s67, s17, s67
	s_cselect_b32 s66, s83, s66
	s_add_u32 s44, s54, s44
	s_addc_u32 s64, s55, 0
	s_add_u32 s44, s44, 0x100
	s_addc_u32 s64, s64, 0
	s_and_b64 s[62:63], s[62:63], exec
	s_cselect_b32 s69, s15, s64
	s_cselect_b32 s68, s84, s44
	s_add_u32 s72, s36, 0x10080
	s_addc_u32 s73, s37, 0
	s_add_i32 s96, s79, s27
	ds_read_b128 v[148:151], v143
	ds_read_b128 v[152:155], v143 offset:1024
	ds_read_b128 v[156:159], v143 offset:2048
	ds_read_b128 v[166:169], v143 offset:3072
	ds_read_b128 v[170:173], v145
	ds_read_b128 v[174:177], v145 offset:1024
	ds_read_b128 v[178:181], v145 offset:2048
	ds_read_b128 v[182:185], v145 offset:3072
	s_add_i32 m0, s43, 0xc000
	s_add_i32 s97, s43, 0xe000
	s_add_i32 s93, s96, 0x2000
	s_add_u32 s70, s68, 0x10000
	s_addc_u32 s71, s69, 0
	s_add_i32 s95, s80, s27
	s_add_i32 s94, s95, 0x2000
	s_add_i32 s92, 0, 0x18000
	s_add_i32 s89, 0, 0x1c000
	s_add_u32 s64, s66, 0x10000
	s_addc_u32 s65, s67, 0
	s_add_i32 s87, s92, s27
	s_add_i32 s85, s87, 0x2000
	s_add_u32 s62, s68, 0x10080
	s_addc_u32 s63, s69, 0
	s_add_i32 s86, s89, s27
	s_add_i32 s44, s86, 0x2000
	ds_read_b128 v[186:189], v146
	ds_read_b128 v[190:193], v146 offset:1024
	ds_read_b128 v[194:197], v146 offset:2048
	ds_read_b128 v[202:205], v146 offset:3072
	ds_read_b128 v[206:209], v146 offset:4096
	ds_read_b128 v[210:213], v146 offset:5120
	ds_read_b128 v[214:217], v146 offset:6144
	ds_read_b128 v[218:221], v146 offset:7168
	global_load_lds_dwordx4 v130, s[72:73]
	s_mov_b32 m0, s97
	s_nop 0
	global_load_lds_dwordx4 v134, s[72:73]
	s_waitcnt vmcnt(8)
	s_waitcnt lgkmcnt(0)
	s_barrier
	s_setprio 1
	s_waitcnt lgkmcnt(0)
	v_mfma_f32_16x16x32_bf16 v[126:129], v[148:151], v[186:189], v[126:129]
	v_mfma_f32_16x16x32_bf16 v[126:129], v[152:155], v[190:193], v[126:129]
	v_mfma_f32_16x16x32_bf16 v[122:125], v[166:169], v[190:193], v[122:125]
	v_mfma_f32_16x16x32_bf16 v[122:125], v[156:159], v[186:189], v[122:125]
	v_mfma_f32_16x16x32_bf16 v[110:113], v[156:159], v[194:197], v[110:113]
	v_mfma_f32_16x16x32_bf16 v[110:113], v[166:169], v[202:205], v[110:113]
	v_mfma_f32_16x16x32_bf16 v[118:121], v[152:155], v[202:205], v[118:121]
	v_mfma_f32_16x16x32_bf16 v[118:121], v[148:151], v[194:197], v[118:121]
	v_mfma_f32_16x16x32_bf16 v[102:105], v[148:151], v[206:209], v[102:105]
	v_mfma_f32_16x16x32_bf16 v[102:105], v[152:155], v[210:213], v[102:105]
	v_mfma_f32_16x16x32_bf16 v[94:97], v[166:169], v[210:213], v[94:97]
	v_mfma_f32_16x16x32_bf16 v[94:97], v[156:159], v[206:209], v[94:97]
	v_mfma_f32_16x16x32_bf16 v[78:81], v[156:159], v[214:217], v[78:81]
	v_mfma_f32_16x16x32_bf16 v[78:81], v[166:169], v[218:221], v[78:81]
	v_mfma_f32_16x16x32_bf16 v[86:89], v[152:155], v[218:221], v[86:89]
	v_mfma_f32_16x16x32_bf16 v[86:89], v[148:151], v[214:217], v[86:89]
	s_setprio 0
	s_setprio 1
	v_mfma_f32_16x16x32_bf16 v[114:117], v[170:173], v[186:189], v[114:117]
	v_mfma_f32_16x16x32_bf16 v[114:117], v[174:177], v[190:193], v[114:117]
	v_mfma_f32_16x16x32_bf16 v[106:109], v[182:185], v[190:193], v[106:109]
	v_mfma_f32_16x16x32_bf16 v[106:109], v[178:181], v[186:189], v[106:109]
	v_mfma_f32_16x16x32_bf16 v[90:93], v[178:181], v[194:197], v[90:93]
	v_mfma_f32_16x16x32_bf16 v[90:93], v[182:185], v[202:205], v[90:93]
	v_mfma_f32_16x16x32_bf16 v[98:101], v[174:177], v[202:205], v[98:101]
	v_mfma_f32_16x16x32_bf16 v[98:101], v[170:173], v[194:197], v[98:101]
	v_mfma_f32_16x16x32_bf16 v[82:85], v[170:173], v[206:209], v[82:85]
	v_mfma_f32_16x16x32_bf16 v[82:85], v[174:177], v[210:213], v[82:85]
	v_mfma_f32_16x16x32_bf16 v[74:77], v[182:185], v[210:213], v[74:77]
	v_mfma_f32_16x16x32_bf16 v[74:77], v[178:181], v[206:209], v[74:77]
	v_mfma_f32_16x16x32_bf16 v[66:69], v[178:181], v[214:217], v[66:69]
	v_mfma_f32_16x16x32_bf16 v[66:69], v[182:185], v[218:221], v[66:69]
	v_mfma_f32_16x16x32_bf16 v[70:73], v[174:177], v[218:221], v[70:73]
	v_mfma_f32_16x16x32_bf16 v[70:73], v[170:173], v[214:217], v[70:73]
	s_setprio 0
	s_barrier
	s_mov_b32 m0, s96
	v_lshl_add_u64 v[160:161], s[68:69], 0, v[132:133]
	ds_read_b128 v[186:189], v146 offset:16384
	ds_read_b128 v[190:193], v146 offset:17408
	ds_read_b128 v[194:197], v146 offset:18432
	ds_read_b128 v[202:205], v146 offset:19456
	ds_read_b128 v[206:209], v146 offset:20480
	ds_read_b128 v[210:213], v146 offset:21504
	ds_read_b128 v[214:217], v146 offset:22528
	ds_read_b128 v[218:221], v146 offset:23552
	global_load_lds_dwordx4 v[160:161], off
	v_lshl_add_u64 v[198:199], s[68:69], 0, v[136:137]
	s_mov_b32 m0, s93
	s_nop 0
	global_load_lds_dwordx4 v[198:199], off
	s_mov_b32 m0, s95
	v_lshl_add_u64 v[224:225], s[66:67], 0, v[134:135]
	global_load_lds_dwordx4 v132, s[70:71]
	s_mov_b32 m0, s94
	s_nop 0
	global_load_lds_dwordx4 v136, s[70:71]
	v_lshl_add_u64 v[222:223], s[66:67], 0, v[130:131]
	s_mov_b32 m0, s43
	s_nop 0
	global_load_lds_dwordx4 v[222:223], off
	s_mov_b32 m0, s45
	s_nop 0
	global_load_lds_dwordx4 v[224:225], off
	s_waitcnt vmcnt(8)
	s_waitcnt lgkmcnt(0)
	s_barrier
	s_setprio 1
	s_waitcnt lgkmcnt(0)
	v_mfma_f32_16x16x32_bf16 v[62:65], v[148:151], v[186:189], v[62:65]
	v_mfma_f32_16x16x32_bf16 v[62:65], v[152:155], v[190:193], v[62:65]
	v_mfma_f32_16x16x32_bf16 v[58:61], v[166:169], v[190:193], v[58:61]
	v_mfma_f32_16x16x32_bf16 v[58:61], v[156:159], v[186:189], v[58:61]
	v_mfma_f32_16x16x32_bf16 v[46:49], v[156:159], v[194:197], v[46:49]
	v_mfma_f32_16x16x32_bf16 v[46:49], v[166:169], v[202:205], v[46:49]
	v_mfma_f32_16x16x32_bf16 v[54:57], v[152:155], v[202:205], v[54:57]
	v_mfma_f32_16x16x32_bf16 v[54:57], v[148:151], v[194:197], v[54:57]
	v_mfma_f32_16x16x32_bf16 v[38:41], v[148:151], v[206:209], v[38:41]
	v_mfma_f32_16x16x32_bf16 v[38:41], v[152:155], v[210:213], v[38:41]
	v_mfma_f32_16x16x32_bf16 v[30:33], v[166:169], v[210:213], v[30:33]
	v_mfma_f32_16x16x32_bf16 v[30:33], v[156:159], v[206:209], v[30:33]
	v_mfma_f32_16x16x32_bf16 v[14:17], v[156:159], v[214:217], v[14:17]
	v_mfma_f32_16x16x32_bf16 v[14:17], v[166:169], v[218:221], v[14:17]
	v_mfma_f32_16x16x32_bf16 v[22:25], v[152:155], v[218:221], v[22:25]
	v_mfma_f32_16x16x32_bf16 v[22:25], v[148:151], v[214:217], v[22:25]
	s_setprio 0
	s_setprio 1
	v_mfma_f32_16x16x32_bf16 v[50:53], v[170:173], v[186:189], v[50:53]
	v_mfma_f32_16x16x32_bf16 v[50:53], v[174:177], v[190:193], v[50:53]
	v_mfma_f32_16x16x32_bf16 v[42:45], v[182:185], v[190:193], v[42:45]
	v_mfma_f32_16x16x32_bf16 v[42:45], v[178:181], v[186:189], v[42:45]
	v_mfma_f32_16x16x32_bf16 v[26:29], v[178:181], v[194:197], v[26:29]
	v_mfma_f32_16x16x32_bf16 v[26:29], v[182:185], v[202:205], v[26:29]
	v_mfma_f32_16x16x32_bf16 v[34:37], v[174:177], v[202:205], v[34:37]
	v_mfma_f32_16x16x32_bf16 v[34:37], v[170:173], v[194:197], v[34:37]
	v_mfma_f32_16x16x32_bf16 v[18:21], v[170:173], v[206:209], v[18:21]
	v_mfma_f32_16x16x32_bf16 v[18:21], v[174:177], v[210:213], v[18:21]
	v_mfma_f32_16x16x32_bf16 v[10:13], v[182:185], v[210:213], v[10:13]
	v_mfma_f32_16x16x32_bf16 v[10:13], v[178:181], v[206:209], v[10:13]
	v_mfma_f32_16x16x32_bf16 v[2:5], v[178:181], v[214:217], v[2:5]
	v_mfma_f32_16x16x32_bf16 v[2:5], v[182:185], v[218:221], v[2:5]
	v_mfma_f32_16x16x32_bf16 v[6:9], v[174:177], v[218:221], v[6:9]
	v_mfma_f32_16x16x32_bf16 v[6:9], v[170:173], v[214:217], v[6:9]
	s_setprio 0
	s_barrier
	v_add_u32_e32 v147, s92, v142
	ds_read_b128 v[148:151], v147
	ds_read_b128 v[152:155], v147 offset:1024
	ds_read_b128 v[156:159], v147 offset:2048
	ds_read_b128 v[166:169], v147 offset:3072
	v_add_u32_e32 v147, s89, v142
	ds_read_b128 v[170:173], v147
	ds_read_b128 v[174:177], v147 offset:1024
	ds_read_b128 v[178:181], v147 offset:2048
	ds_read_b128 v[182:185], v147 offset:3072
	s_mov_b32 m0, s49
	ds_read_b128 v[186:189], v146 offset:32768
	ds_read_b128 v[190:193], v146 offset:33792
	ds_read_b128 v[194:197], v146 offset:34816
	ds_read_b128 v[202:205], v146 offset:35840
	ds_read_b128 v[206:209], v146 offset:36864
	ds_read_b128 v[210:213], v146 offset:37888
	ds_read_b128 v[214:217], v146 offset:38912
	ds_read_b128 v[218:221], v146 offset:39936
	global_load_lds_dwordx4 v130, s[64:65]
	s_mov_b32 m0, s74
	s_nop 0
	global_load_lds_dwordx4 v134, s[64:65]
	s_waitcnt vmcnt(8)
	s_waitcnt lgkmcnt(0)
	s_barrier
	s_setprio 1
	s_waitcnt lgkmcnt(0)
	v_mfma_f32_16x16x32_bf16 v[126:129], v[148:151], v[186:189], v[126:129]
	v_mfma_f32_16x16x32_bf16 v[126:129], v[152:155], v[190:193], v[126:129]
	v_mfma_f32_16x16x32_bf16 v[122:125], v[166:169], v[190:193], v[122:125]
	v_mfma_f32_16x16x32_bf16 v[122:125], v[156:159], v[186:189], v[122:125]
	v_mfma_f32_16x16x32_bf16 v[110:113], v[156:159], v[194:197], v[110:113]
	v_mfma_f32_16x16x32_bf16 v[110:113], v[166:169], v[202:205], v[110:113]
	v_mfma_f32_16x16x32_bf16 v[118:121], v[152:155], v[202:205], v[118:121]
	v_mfma_f32_16x16x32_bf16 v[118:121], v[148:151], v[194:197], v[118:121]
	v_mfma_f32_16x16x32_bf16 v[102:105], v[148:151], v[206:209], v[102:105]
	v_mfma_f32_16x16x32_bf16 v[102:105], v[152:155], v[210:213], v[102:105]
	v_mfma_f32_16x16x32_bf16 v[94:97], v[166:169], v[210:213], v[94:97]
	v_mfma_f32_16x16x32_bf16 v[94:97], v[156:159], v[206:209], v[94:97]
	v_mfma_f32_16x16x32_bf16 v[78:81], v[156:159], v[214:217], v[78:81]
	v_mfma_f32_16x16x32_bf16 v[78:81], v[166:169], v[218:221], v[78:81]
	v_mfma_f32_16x16x32_bf16 v[86:89], v[152:155], v[218:221], v[86:89]
	v_mfma_f32_16x16x32_bf16 v[86:89], v[148:151], v[214:217], v[86:89]
	s_setprio 0
	s_setprio 1
	v_mfma_f32_16x16x32_bf16 v[114:117], v[170:173], v[186:189], v[114:117]
	v_mfma_f32_16x16x32_bf16 v[114:117], v[174:177], v[190:193], v[114:117]
	v_mfma_f32_16x16x32_bf16 v[106:109], v[182:185], v[190:193], v[106:109]
	v_mfma_f32_16x16x32_bf16 v[106:109], v[178:181], v[186:189], v[106:109]
	v_mfma_f32_16x16x32_bf16 v[90:93], v[178:181], v[194:197], v[90:93]
	v_mfma_f32_16x16x32_bf16 v[90:93], v[182:185], v[202:205], v[90:93]
	v_mfma_f32_16x16x32_bf16 v[98:101], v[174:177], v[202:205], v[98:101]
	v_mfma_f32_16x16x32_bf16 v[98:101], v[170:173], v[194:197], v[98:101]
	v_mfma_f32_16x16x32_bf16 v[82:85], v[170:173], v[206:209], v[82:85]
	v_mfma_f32_16x16x32_bf16 v[82:85], v[174:177], v[210:213], v[82:85]
	v_mfma_f32_16x16x32_bf16 v[74:77], v[182:185], v[210:213], v[74:77]
	v_mfma_f32_16x16x32_bf16 v[74:77], v[178:181], v[206:209], v[74:77]
	v_mfma_f32_16x16x32_bf16 v[66:69], v[178:181], v[214:217], v[66:69]
	v_mfma_f32_16x16x32_bf16 v[66:69], v[182:185], v[218:221], v[66:69]
	v_mfma_f32_16x16x32_bf16 v[70:73], v[174:177], v[218:221], v[70:73]
	v_mfma_f32_16x16x32_bf16 v[70:73], v[170:173], v[214:217], v[70:73]
	s_setprio 0
	s_barrier
	s_mov_b32 m0, s87
	v_lshl_add_u64 v[160:161], v[160:161], 0, s[10:11]
	ds_read_b128 v[186:189], v146 offset:49152
	ds_read_b128 v[190:193], v146 offset:50176
	ds_read_b128 v[194:197], v146 offset:51200
	ds_read_b128 v[202:205], v146 offset:52224
	ds_read_b128 v[206:209], v146 offset:53248
	ds_read_b128 v[210:213], v146 offset:54272
	ds_read_b128 v[214:217], v146 offset:55296
	ds_read_b128 v[218:221], v146 offset:56320
	global_load_lds_dwordx4 v[160:161], off
	v_lshl_add_u64 v[160:161], v[198:199], 0, s[10:11]
	s_mov_b32 m0, s85
	s_nop 0
	global_load_lds_dwordx4 v[160:161], off
	s_mov_b32 m0, s86
	s_nop 0
	global_load_lds_dwordx4 v132, s[62:63]
	s_mov_b32 m0, s44
	s_nop 0
	global_load_lds_dwordx4 v136, s[62:63]
	v_lshl_add_u64 v[160:161], v[222:223], 0, s[10:11]
	s_mov_b32 m0, s76
	s_nop 0
	global_load_lds_dwordx4 v[160:161], off
	v_lshl_add_u64 v[160:161], v[224:225], 0, s[10:11]
	s_mov_b32 m0, s77
	s_nop 0
	global_load_lds_dwordx4 v[160:161], off
	s_waitcnt vmcnt(8)
	s_waitcnt lgkmcnt(0)
	s_barrier
	s_setprio 1
	s_waitcnt lgkmcnt(0)
	v_mfma_f32_16x16x32_bf16 v[62:65], v[148:151], v[186:189], v[62:65]
	v_mfma_f32_16x16x32_bf16 v[62:65], v[152:155], v[190:193], v[62:65]
	v_mfma_f32_16x16x32_bf16 v[58:61], v[166:169], v[190:193], v[58:61]
	v_mfma_f32_16x16x32_bf16 v[58:61], v[156:159], v[186:189], v[58:61]
	v_mfma_f32_16x16x32_bf16 v[46:49], v[156:159], v[194:197], v[46:49]
	v_mfma_f32_16x16x32_bf16 v[46:49], v[166:169], v[202:205], v[46:49]
	v_mfma_f32_16x16x32_bf16 v[54:57], v[152:155], v[202:205], v[54:57]
	v_mfma_f32_16x16x32_bf16 v[54:57], v[148:151], v[194:197], v[54:57]
	v_mfma_f32_16x16x32_bf16 v[38:41], v[148:151], v[206:209], v[38:41]
	v_mfma_f32_16x16x32_bf16 v[38:41], v[152:155], v[210:213], v[38:41]
	v_mfma_f32_16x16x32_bf16 v[30:33], v[166:169], v[210:213], v[30:33]
	v_mfma_f32_16x16x32_bf16 v[30:33], v[156:159], v[206:209], v[30:33]
	v_mfma_f32_16x16x32_bf16 v[14:17], v[156:159], v[214:217], v[14:17]
	v_mfma_f32_16x16x32_bf16 v[14:17], v[166:169], v[218:221], v[14:17]
	v_mfma_f32_16x16x32_bf16 v[22:25], v[152:155], v[218:221], v[22:25]
	v_mfma_f32_16x16x32_bf16 v[22:25], v[148:151], v[214:217], v[22:25]
	s_setprio 0
	s_setprio 1
	v_mfma_f32_16x16x32_bf16 v[50:53], v[170:173], v[186:189], v[50:53]
	v_mfma_f32_16x16x32_bf16 v[50:53], v[174:177], v[190:193], v[50:53]
	v_mfma_f32_16x16x32_bf16 v[42:45], v[182:185], v[190:193], v[42:45]
	v_mfma_f32_16x16x32_bf16 v[42:45], v[178:181], v[186:189], v[42:45]
	v_mfma_f32_16x16x32_bf16 v[26:29], v[178:181], v[194:197], v[26:29]
	v_mfma_f32_16x16x32_bf16 v[26:29], v[182:185], v[202:205], v[26:29]
	v_mfma_f32_16x16x32_bf16 v[34:37], v[174:177], v[202:205], v[34:37]
	v_mfma_f32_16x16x32_bf16 v[34:37], v[170:173], v[194:197], v[34:37]
	v_mfma_f32_16x16x32_bf16 v[18:21], v[170:173], v[206:209], v[18:21]
	v_mfma_f32_16x16x32_bf16 v[18:21], v[174:177], v[210:213], v[18:21]
	v_mfma_f32_16x16x32_bf16 v[10:13], v[182:185], v[210:213], v[10:13]
	v_mfma_f32_16x16x32_bf16 v[10:13], v[178:181], v[206:209], v[10:13]
	v_mfma_f32_16x16x32_bf16 v[2:5], v[178:181], v[214:217], v[2:5]
	v_mfma_f32_16x16x32_bf16 v[2:5], v[182:185], v[218:221], v[2:5]
	v_mfma_f32_16x16x32_bf16 v[6:9], v[174:177], v[218:221], v[6:9]
	v_mfma_f32_16x16x32_bf16 v[6:9], v[170:173], v[214:217], v[6:9]
	s_setprio 0
	s_barrier
	s_movk_i32 s44, 0x100
	s_andn2_b64 vcc, exec, s[60:61]
	s_mov_b64 s[62:63], -1
	s_mov_b64 s[60:61], 0
	s_cbranch_vccz .LBB0_722
	s_and_b64 vcc, exec, s[12:13]
	s_cbranch_vccz .LBB0_725
	s_barrier

.LBB0_1226:
	v_add_u32_e32 v3, s71, v165
	ds_read_b128 v[150:153], v3
	ds_read_b128 v[154:157], v3 offset:1024
	ds_read_b128 v[158:161], v3 offset:2048
	ds_read_b128 v[170:173], v3 offset:3072
	v_add_u32_e32 v3, s72, v165
	ds_read_b128 v[174:177], v3
	ds_read_b128 v[178:181], v3 offset:1024
	ds_read_b128 v[182:185], v3 offset:2048
	ds_read_b128 v[186:189], v3 offset:3072
	s_add_u32 s36, s52, 0xfff80080
	s_addc_u32 s37, s53, -1
	s_cmp_eq_u32 s78, 28
	s_cselect_b32 s59, s21, s37
	s_cselect_b32 s58, s44, s36
	s_cselect_b32 s57, s19, s77
	s_cselect_b32 s56, s55, s76
	s_add_i32 m0, s63, 0xc000
	ds_read_b128 v[190:193], v169
	ds_read_b128 v[194:197], v169 offset:1024
	ds_read_b128 v[202:205], v169 offset:2048
	ds_read_b128 v[206:209], v169 offset:3072
	ds_read_b128 v[210:213], v169 offset:4096
	ds_read_b128 v[214:217], v169 offset:5120
	ds_read_b128 v[218:221], v169 offset:6144
	ds_read_b128 v[222:225], v169 offset:7168
	global_load_lds_dwordx4 v142, s[52:53]
	s_add_i32 m0, s63, 0xe000
	s_nop 0
	global_load_lds_dwordx4 v144, s[52:53]
	s_waitcnt vmcnt(8)
	s_waitcnt lgkmcnt(0)
	s_barrier
	s_setprio 1
	s_waitcnt lgkmcnt(0)
	v_mfma_f32_16x16x32_bf16 v[130:133], v[150:153], v[190:193], v[130:133]
	v_mfma_f32_16x16x32_bf16 v[130:133], v[154:157], v[194:197], v[130:133]
	v_mfma_f32_16x16x32_bf16 v[126:129], v[170:173], v[194:197], v[126:129]
	v_mfma_f32_16x16x32_bf16 v[126:129], v[158:161], v[190:193], v[126:129]
	v_mfma_f32_16x16x32_bf16 v[118:121], v[158:161], v[202:205], v[118:121]
	v_mfma_f32_16x16x32_bf16 v[118:121], v[170:173], v[206:209], v[118:121]
	v_mfma_f32_16x16x32_bf16 v[122:125], v[154:157], v[206:209], v[122:125]
	v_mfma_f32_16x16x32_bf16 v[122:125], v[150:153], v[202:205], v[122:125]
	v_mfma_f32_16x16x32_bf16 v[114:117], v[150:153], v[210:213], v[114:117]
	v_mfma_f32_16x16x32_bf16 v[114:117], v[154:157], v[214:217], v[114:117]
	v_mfma_f32_16x16x32_bf16 v[110:113], v[170:173], v[214:217], v[110:113]
	v_mfma_f32_16x16x32_bf16 v[110:113], v[158:161], v[210:213], v[110:113]
	v_mfma_f32_16x16x32_bf16 v[102:105], v[158:161], v[218:221], v[102:105]
	v_mfma_f32_16x16x32_bf16 v[102:105], v[170:173], v[222:225], v[102:105]
	v_mfma_f32_16x16x32_bf16 v[106:109], v[154:157], v[222:225], v[106:109]
	v_mfma_f32_16x16x32_bf16 v[106:109], v[150:153], v[218:221], v[106:109]
	s_setprio 0
	s_setprio 1
	v_mfma_f32_16x16x32_bf16 v[98:101], v[174:177], v[190:193], v[98:101]
	v_mfma_f32_16x16x32_bf16 v[98:101], v[178:181], v[194:197], v[98:101]
	v_mfma_f32_16x16x32_bf16 v[94:97], v[186:189], v[194:197], v[94:97]
	v_mfma_f32_16x16x32_bf16 v[94:97], v[182:185], v[190:193], v[94:97]
	v_mfma_f32_16x16x32_bf16 v[86:89], v[182:185], v[202:205], v[86:89]
	v_mfma_f32_16x16x32_bf16 v[86:89], v[186:189], v[206:209], v[86:89]
	v_mfma_f32_16x16x32_bf16 v[90:93], v[178:181], v[206:209], v[90:93]
	v_mfma_f32_16x16x32_bf16 v[90:93], v[174:177], v[202:205], v[90:93]
	v_mfma_f32_16x16x32_bf16 v[82:85], v[174:177], v[210:213], v[82:85]
	v_mfma_f32_16x16x32_bf16 v[82:85], v[178:181], v[214:217], v[82:85]
	v_mfma_f32_16x16x32_bf16 v[78:81], v[186:189], v[214:217], v[78:81]
	v_mfma_f32_16x16x32_bf16 v[78:81], v[182:185], v[210:213], v[78:81]
	v_mfma_f32_16x16x32_bf16 v[70:73], v[182:185], v[218:221], v[70:73]
	v_mfma_f32_16x16x32_bf16 v[70:73], v[186:189], v[222:225], v[70:73]
	v_mfma_f32_16x16x32_bf16 v[74:77], v[178:181], v[222:225], v[74:77]
	v_mfma_f32_16x16x32_bf16 v[74:77], v[174:177], v[218:221], v[74:77]
	s_setprio 0
	s_barrier
	s_add_i32 s36, s71, s43
	v_lshl_add_u64 v[166:167], s[56:57], 0, v[138:139]
	s_mov_b32 m0, s36
	ds_read_b128 v[190:193], v169 offset:16384
	ds_read_b128 v[194:197], v169 offset:17408
	ds_read_b128 v[202:205], v169 offset:18432
	ds_read_b128 v[206:209], v169 offset:19456
	ds_read_b128 v[210:213], v169 offset:20480
	ds_read_b128 v[214:217], v169 offset:21504
	ds_read_b128 v[218:221], v169 offset:22528
	ds_read_b128 v[222:225], v169 offset:23552
	global_load_lds_dwordx4 v[166:167], off
	s_add_i32 m0, s36, 0x2000
	s_add_u32 s80, s56, 0x80000
	v_lshl_add_u64 v[198:199], s[56:57], 0, v[134:135]
	s_addc_u32 s81, s57, 0
	s_add_i32 s36, s72, s43
	global_load_lds_dwordx4 v[198:199], off
	s_mov_b32 m0, s36
	v_lshl_add_u64 v[226:227], s[58:59], 0, v[140:141]
	global_load_lds_dwordx4 v138, s[80:81]
	v_lshl_add_u64 v[4:5], s[80:81], 0, v[134:135]
	s_add_i32 m0, s36, 0x2000
	v_lshl_add_u64 v[228:229], s[58:59], 0, v[136:137]
	global_load_lds_dwordx4 v[4:5], off
	s_mov_b32 m0, s63
	s_nop 0
	global_load_lds_dwordx4 v[226:227], off
	s_mov_b32 m0, s64
	s_nop 0
	global_load_lds_dwordx4 v[228:229], off
	s_waitcnt vmcnt(8)
	s_waitcnt lgkmcnt(0)
	s_barrier
	s_setprio 1
	s_waitcnt lgkmcnt(0)
	v_mfma_f32_16x16x32_bf16 v[66:69], v[150:153], v[190:193], v[66:69]
	v_mfma_f32_16x16x32_bf16 v[66:69], v[154:157], v[194:197], v[66:69]
	v_mfma_f32_16x16x32_bf16 v[62:65], v[170:173], v[194:197], v[62:65]
	v_mfma_f32_16x16x32_bf16 v[62:65], v[158:161], v[190:193], v[62:65]
	v_mfma_f32_16x16x32_bf16 v[54:57], v[158:161], v[202:205], v[54:57]
	v_mfma_f32_16x16x32_bf16 v[54:57], v[170:173], v[206:209], v[54:57]
	v_mfma_f32_16x16x32_bf16 v[58:61], v[154:157], v[206:209], v[58:61]
	v_mfma_f32_16x16x32_bf16 v[58:61], v[150:153], v[202:205], v[58:61]
	v_mfma_f32_16x16x32_bf16 v[50:53], v[150:153], v[210:213], v[50:53]
	v_mfma_f32_16x16x32_bf16 v[50:53], v[154:157], v[214:217], v[50:53]
	v_mfma_f32_16x16x32_bf16 v[46:49], v[170:173], v[214:217], v[46:49]
	v_mfma_f32_16x16x32_bf16 v[46:49], v[158:161], v[210:213], v[46:49]
	v_mfma_f32_16x16x32_bf16 v[38:41], v[158:161], v[218:221], v[38:41]
	v_mfma_f32_16x16x32_bf16 v[38:41], v[170:173], v[222:225], v[38:41]
	v_mfma_f32_16x16x32_bf16 v[42:45], v[154:157], v[222:225], v[42:45]
	v_mfma_f32_16x16x32_bf16 v[42:45], v[150:153], v[218:221], v[42:45]
	s_setprio 0
	s_setprio 1
	v_mfma_f32_16x16x32_bf16 v[34:37], v[174:177], v[190:193], v[34:37]
	v_mfma_f32_16x16x32_bf16 v[30:33], v[182:185], v[190:193], v[30:33]
	v_mfma_f32_16x16x32_bf16 v[26:29], v[174:177], v[202:205], v[26:29]
	v_mfma_f32_16x16x32_bf16 v[22:25], v[182:185], v[202:205], v[22:25]
	v_mfma_f32_16x16x32_bf16 v[18:21], v[174:177], v[210:213], v[18:21]
	v_mfma_f32_16x16x32_bf16 v[14:17], v[182:185], v[210:213], v[14:17]
	v_mfma_f32_16x16x32_bf16 v[10:13], v[174:177], v[218:221], v[10:13]
	v_mfma_f32_16x16x32_bf16 v[4:7], v[182:185], v[218:221], v[6:9]
	v_mfma_f32_16x16x32_bf16 v[34:37], v[178:181], v[194:197], v[34:37]
	v_mfma_f32_16x16x32_bf16 v[30:33], v[186:189], v[194:197], v[30:33]
	v_mfma_f32_16x16x32_bf16 v[26:29], v[178:181], v[206:209], v[26:29]
	v_mfma_f32_16x16x32_bf16 v[22:25], v[186:189], v[206:209], v[22:25]
	v_mfma_f32_16x16x32_bf16 v[18:21], v[178:181], v[214:217], v[18:21]
	v_mfma_f32_16x16x32_bf16 v[14:17], v[186:189], v[214:217], v[14:17]
	v_mfma_f32_16x16x32_bf16 v[10:13], v[178:181], v[222:225], v[10:13]
	v_mfma_f32_16x16x32_bf16 v[4:7], v[186:189], v[222:225], v[4:7]
	s_setprio 0
	s_barrier
	s_add_i32 s36, 0, 0x18000
	v_add_u32_e32 v3, s36, v165
	s_add_i32 s37, 0, 0x1c000
	ds_read_b128 v[150:153], v3
	ds_read_b128 v[154:157], v3 offset:1024
	ds_read_b128 v[158:161], v3 offset:2048
	ds_read_b128 v[170:173], v3 offset:3072
	v_add_u32_e32 v3, s37, v165
	ds_read_b128 v[174:177], v3
	ds_read_b128 v[178:181], v3 offset:1024
	ds_read_b128 v[182:185], v3 offset:2048
	ds_read_b128 v[186:189], v3 offset:3072
	s_add_u32 s58, s58, 0x80000
	s_addc_u32 s59, s59, 0
	s_mov_b32 m0, s65
	ds_read_b128 v[190:193], v169 offset:32768
	ds_read_b128 v[194:197], v169 offset:33792
	ds_read_b128 v[202:205], v169 offset:34816
	ds_read_b128 v[206:209], v169 offset:35840
	ds_read_b128 v[210:213], v169 offset:36864
	ds_read_b128 v[214:217], v169 offset:37888
	ds_read_b128 v[218:221], v169 offset:38912
	ds_read_b128 v[222:225], v169 offset:39936
	global_load_lds_dwordx4 v140, s[58:59]
	s_mov_b32 m0, s66
	s_nop 0
	global_load_lds_dwordx4 v136, s[58:59]
	s_waitcnt vmcnt(8)
	s_waitcnt lgkmcnt(0)
	s_barrier
	s_setprio 1
	s_waitcnt lgkmcnt(0)
	v_mfma_f32_16x16x32_bf16 v[130:133], v[150:153], v[190:193], v[130:133]
	v_mfma_f32_16x16x32_bf16 v[130:133], v[154:157], v[194:197], v[130:133]
	v_mfma_f32_16x16x32_bf16 v[126:129], v[170:173], v[194:197], v[126:129]
	v_mfma_f32_16x16x32_bf16 v[126:129], v[158:161], v[190:193], v[126:129]
	v_mfma_f32_16x16x32_bf16 v[118:121], v[158:161], v[202:205], v[118:121]
	v_mfma_f32_16x16x32_bf16 v[118:121], v[170:173], v[206:209], v[118:121]
	v_mfma_f32_16x16x32_bf16 v[122:125], v[154:157], v[206:209], v[122:125]
	v_mfma_f32_16x16x32_bf16 v[122:125], v[150:153], v[202:205], v[122:125]
	v_mfma_f32_16x16x32_bf16 v[114:117], v[150:153], v[210:213], v[114:117]
	v_mfma_f32_16x16x32_bf16 v[114:117], v[154:157], v[214:217], v[114:117]
	v_mfma_f32_16x16x32_bf16 v[110:113], v[170:173], v[214:217], v[110:113]
	v_mfma_f32_16x16x32_bf16 v[110:113], v[158:161], v[210:213], v[110:113]
	v_mfma_f32_16x16x32_bf16 v[102:105], v[158:161], v[218:221], v[102:105]
	v_mfma_f32_16x16x32_bf16 v[102:105], v[170:173], v[222:225], v[102:105]
	v_mfma_f32_16x16x32_bf16 v[106:109], v[154:157], v[222:225], v[106:109]
	v_mfma_f32_16x16x32_bf16 v[106:109], v[150:153], v[218:221], v[106:109]
	s_setprio 0
	s_setprio 1
	v_mfma_f32_16x16x32_bf16 v[98:101], v[174:177], v[190:193], v[98:101]
	v_mfma_f32_16x16x32_bf16 v[98:101], v[178:181], v[194:197], v[98:101]
	v_mfma_f32_16x16x32_bf16 v[94:97], v[186:189], v[194:197], v[94:97]
	v_mfma_f32_16x16x32_bf16 v[94:97], v[182:185], v[190:193], v[94:97]
	v_mfma_f32_16x16x32_bf16 v[86:89], v[182:185], v[202:205], v[86:89]
	v_mfma_f32_16x16x32_bf16 v[86:89], v[186:189], v[206:209], v[86:89]
	v_mfma_f32_16x16x32_bf16 v[90:93], v[178:181], v[206:209], v[90:93]
	v_mfma_f32_16x16x32_bf16 v[90:93], v[174:177], v[202:205], v[90:93]
	v_mfma_f32_16x16x32_bf16 v[82:85], v[174:177], v[210:213], v[82:85]
	v_mfma_f32_16x16x32_bf16 v[82:85], v[178:181], v[214:217], v[82:85]
	v_mfma_f32_16x16x32_bf16 v[78:81], v[186:189], v[214:217], v[78:81]
	v_mfma_f32_16x16x32_bf16 v[78:81], v[182:185], v[210:213], v[78:81]
	v_mfma_f32_16x16x32_bf16 v[70:73], v[182:185], v[218:221], v[70:73]
	v_mfma_f32_16x16x32_bf16 v[70:73], v[186:189], v[222:225], v[70:73]
	v_mfma_f32_16x16x32_bf16 v[74:77], v[178:181], v[222:225], v[74:77]
	v_mfma_f32_16x16x32_bf16 v[74:77], v[174:177], v[218:221], v[74:77]
	s_setprio 0
	s_barrier
	s_add_i32 s36, s36, s43
	v_lshl_add_u64 v[8:9], v[166:167], 0, s[10:11]
	s_mov_b32 m0, s36
	ds_read_b128 v[190:193], v169 offset:49152
	ds_read_b128 v[194:197], v169 offset:50176
	ds_read_b128 v[202:205], v169 offset:51200
	ds_read_b128 v[206:209], v169 offset:52224
	ds_read_b128 v[210:213], v169 offset:53248
	ds_read_b128 v[214:217], v169 offset:54272
	ds_read_b128 v[218:221], v169 offset:55296
	ds_read_b128 v[222:225], v169 offset:56320
	global_load_lds_dwordx4 v[8:9], off
	s_add_i32 m0, s36, 0x2000
	s_add_u32 s56, s56, 0x80080
	v_lshl_add_u64 v[8:9], v[198:199], 0, s[10:11]
	s_addc_u32 s57, s57, 0
	s_add_i32 s36, s37, s43
	global_load_lds_dwordx4 v[8:9], off
	s_mov_b32 m0, s36
	s_nop 0
	global_load_lds_dwordx4 v138, s[56:57]
	s_add_i32 m0, s36, 0x2000
	s_nop 0
	global_load_lds_dwordx4 v134, s[56:57]
	v_lshl_add_u64 v[8:9], v[226:227], 0, s[10:11]
	s_mov_b32 m0, s69
	s_nop 0
	global_load_lds_dwordx4 v[8:9], off
	v_lshl_add_u64 v[8:9], v[228:229], 0, s[10:11]
	s_mov_b32 m0, s70
	s_nop 0
	global_load_lds_dwordx4 v[8:9], off
	s_waitcnt vmcnt(8)
	s_waitcnt lgkmcnt(0)
	s_barrier
	s_setprio 1
	s_waitcnt lgkmcnt(0)
	v_mfma_f32_16x16x32_bf16 v[66:69], v[150:153], v[190:193], v[66:69]
	v_mfma_f32_16x16x32_bf16 v[66:69], v[154:157], v[194:197], v[66:69]
	v_mfma_f32_16x16x32_bf16 v[62:65], v[170:173], v[194:197], v[62:65]
	v_mfma_f32_16x16x32_bf16 v[62:65], v[158:161], v[190:193], v[62:65]
	v_mfma_f32_16x16x32_bf16 v[54:57], v[158:161], v[202:205], v[54:57]
	v_mfma_f32_16x16x32_bf16 v[54:57], v[170:173], v[206:209], v[54:57]
	v_mfma_f32_16x16x32_bf16 v[58:61], v[154:157], v[206:209], v[58:61]
	v_mfma_f32_16x16x32_bf16 v[58:61], v[150:153], v[202:205], v[58:61]
	v_mfma_f32_16x16x32_bf16 v[50:53], v[150:153], v[210:213], v[50:53]
	v_mfma_f32_16x16x32_bf16 v[50:53], v[154:157], v[214:217], v[50:53]
	v_mfma_f32_16x16x32_bf16 v[46:49], v[170:173], v[214:217], v[46:49]
	v_mfma_f32_16x16x32_bf16 v[46:49], v[158:161], v[210:213], v[46:49]
	v_mfma_f32_16x16x32_bf16 v[38:41], v[158:161], v[218:221], v[38:41]
	v_mfma_f32_16x16x32_bf16 v[38:41], v[170:173], v[222:225], v[38:41]
	v_mfma_f32_16x16x32_bf16 v[42:45], v[154:157], v[222:225], v[42:45]
	v_mfma_f32_16x16x32_bf16 v[42:45], v[150:153], v[218:221], v[42:45]
	s_setprio 0
	s_setprio 1
	v_mfma_f32_16x16x32_bf16 v[34:37], v[174:177], v[190:193], v[34:37]
	v_mfma_f32_16x16x32_bf16 v[30:33], v[182:185], v[190:193], v[30:33]
	v_mfma_f32_16x16x32_bf16 v[26:29], v[174:177], v[202:205], v[26:29]
	v_mfma_f32_16x16x32_bf16 v[22:25], v[182:185], v[202:205], v[22:25]
	v_mfma_f32_16x16x32_bf16 v[18:21], v[174:177], v[210:213], v[18:21]
	v_mfma_f32_16x16x32_bf16 v[14:17], v[182:185], v[210:213], v[14:17]
	v_mfma_f32_16x16x32_bf16 v[8:11], v[174:177], v[218:221], v[10:13]
	v_mfma_f32_16x16x32_bf16 v[4:7], v[182:185], v[218:221], v[4:7]
	v_mfma_f32_16x16x32_bf16 v[34:37], v[178:181], v[194:197], v[34:37]
	v_mfma_f32_16x16x32_bf16 v[30:33], v[186:189], v[194:197], v[30:33]
	v_mfma_f32_16x16x32_bf16 v[26:29], v[178:181], v[206:209], v[26:29]
	v_mfma_f32_16x16x32_bf16 v[22:25], v[186:189], v[206:209], v[22:25]
	v_mfma_f32_16x16x32_bf16 v[18:21], v[178:181], v[214:217], v[18:21]
	v_mfma_f32_16x16x32_bf16 v[14:17], v[186:189], v[214:217], v[14:17]
	v_mfma_f32_16x16x32_bf16 v[10:13], v[178:181], v[222:225], v[8:11]
	v_mfma_f32_16x16x32_bf16 v[6:9], v[186:189], v[222:225], v[4:7]
	s_setprio 0
	s_barrier
	s_add_i32 s78, s78, 2
	s_add_u32 s52, s52, 0x100
	s_addc_u32 s53, s53, 0
	s_add_u32 s76, s76, 0x100
	s_addc_u32 s77, s77, 0
	s_cmp_gt_u32 s78, 29
	s_cbranch_scc0 .LBB0_1226
	s_and_b64 vcc, exec, s[12:13]
	s_cbranch_vccz .LBB0_1229
	s_barrier

.LBB0_1397:
	ds_read_b128 v[146:149], v154
	ds_read_b128 v[158:161], v154 offset:1024
	ds_read_b128 v[166:169], v154 offset:2048
	ds_read_b128 v[170:173], v154 offset:3072
	ds_read_b128 v[174:177], v155
	ds_read_b128 v[178:181], v155 offset:1024
	ds_read_b128 v[182:185], v155 offset:2048
	ds_read_b128 v[186:189], v155 offset:3072
	s_add_i32 s93, s44, 2
	s_add_u32 s36, s62, 0xfff00080
	s_addc_u32 s37, s63, -1
	s_cmp_eq_u32 s59, s44
	s_cselect_b32 s67, s38, s37
	s_cselect_b32 s66, s39, s36
	s_cselect_b32 s65, s51, s92
	s_cselect_b32 s64, s53, s61
	s_add_i32 m0, s72, 0xc000
	ds_read_b128 v[190:193], v156
	ds_read_b128 v[194:197], v156 offset:1024
	ds_read_b128 v[202:205], v156 offset:2048
	ds_read_b128 v[206:209], v156 offset:3072
	ds_read_b128 v[210:213], v156 offset:4096
	ds_read_b128 v[214:217], v156 offset:5120
	ds_read_b128 v[218:221], v156 offset:6144
	ds_read_b128 v[222:225], v156 offset:7168
	global_load_lds_dwordx4 v140, s[62:63]
	s_add_i32 m0, s72, 0xe000
	s_nop 0
	global_load_lds_dwordx4 v142, s[62:63]
	s_waitcnt vmcnt(8)
	s_waitcnt lgkmcnt(0)
	s_barrier
	s_setprio 1
	s_waitcnt lgkmcnt(0)
	v_mfma_f32_16x16x32_bf16 v[126:129], v[146:149], v[190:193], v[126:129]
	v_mfma_f32_16x16x32_bf16 v[126:129], v[158:161], v[194:197], v[126:129]
	v_mfma_f32_16x16x32_bf16 v[122:125], v[170:173], v[194:197], v[122:125]
	v_mfma_f32_16x16x32_bf16 v[122:125], v[166:169], v[190:193], v[122:125]
	v_mfma_f32_16x16x32_bf16 v[106:109], v[166:169], v[202:205], v[106:109]
	v_mfma_f32_16x16x32_bf16 v[106:109], v[170:173], v[206:209], v[106:109]
	v_mfma_f32_16x16x32_bf16 v[110:113], v[158:161], v[206:209], v[110:113]
	v_mfma_f32_16x16x32_bf16 v[110:113], v[146:149], v[202:205], v[110:113]
	v_mfma_f32_16x16x32_bf16 v[94:97], v[146:149], v[210:213], v[94:97]
	v_mfma_f32_16x16x32_bf16 v[94:97], v[158:161], v[214:217], v[94:97]
	v_mfma_f32_16x16x32_bf16 v[90:93], v[170:173], v[214:217], v[90:93]
	v_mfma_f32_16x16x32_bf16 v[90:93], v[166:169], v[210:213], v[90:93]
	v_mfma_f32_16x16x32_bf16 v[74:77], v[166:169], v[218:221], v[74:77]
	v_mfma_f32_16x16x32_bf16 v[74:77], v[170:173], v[222:225], v[74:77]
	v_mfma_f32_16x16x32_bf16 v[78:81], v[158:161], v[222:225], v[78:81]
	v_mfma_f32_16x16x32_bf16 v[78:81], v[146:149], v[218:221], v[78:81]
	s_setprio 0
	s_setprio 1
	v_mfma_f32_16x16x32_bf16 v[118:121], v[174:177], v[190:193], v[118:121]
	v_mfma_f32_16x16x32_bf16 v[118:121], v[178:181], v[194:197], v[118:121]
	v_mfma_f32_16x16x32_bf16 v[114:117], v[186:189], v[194:197], v[114:117]
	v_mfma_f32_16x16x32_bf16 v[114:117], v[182:185], v[190:193], v[114:117]
	v_mfma_f32_16x16x32_bf16 v[98:101], v[182:185], v[202:205], v[98:101]
	v_mfma_f32_16x16x32_bf16 v[98:101], v[186:189], v[206:209], v[98:101]
	v_mfma_f32_16x16x32_bf16 v[102:105], v[178:181], v[206:209], v[102:105]
	v_mfma_f32_16x16x32_bf16 v[102:105], v[174:177], v[202:205], v[102:105]
	v_mfma_f32_16x16x32_bf16 v[86:89], v[174:177], v[210:213], v[86:89]
	v_mfma_f32_16x16x32_bf16 v[86:89], v[178:181], v[214:217], v[86:89]
	v_mfma_f32_16x16x32_bf16 v[82:85], v[186:189], v[214:217], v[82:85]
	v_mfma_f32_16x16x32_bf16 v[82:85], v[182:185], v[210:213], v[82:85]
	v_mfma_f32_16x16x32_bf16 v[66:69], v[182:185], v[218:221], v[66:69]
	v_mfma_f32_16x16x32_bf16 v[66:69], v[186:189], v[222:225], v[66:69]
	v_mfma_f32_16x16x32_bf16 v[70:73], v[178:181], v[222:225], v[70:73]
	v_mfma_f32_16x16x32_bf16 v[70:73], v[174:177], v[218:221], v[70:73]
	s_setprio 0
	s_barrier
	s_add_i32 s36, s82, s69
	v_lshl_add_u64 v[150:151], s[64:65], 0, v[132:133]
	s_mov_b32 m0, s36
	ds_read_b128 v[190:193], v156 offset:16384
	ds_read_b128 v[194:197], v156 offset:17408
	ds_read_b128 v[202:205], v156 offset:18432
	ds_read_b128 v[206:209], v156 offset:19456
	ds_read_b128 v[210:213], v156 offset:20480
	ds_read_b128 v[214:217], v156 offset:21504
	ds_read_b128 v[218:221], v156 offset:22528
	ds_read_b128 v[222:225], v156 offset:23552
	global_load_lds_dwordx4 v[150:151], off
	s_add_i32 m0, s36, 0x2000
	s_add_u32 s94, s64, 0x100000
	v_lshl_add_u64 v[198:199], s[64:65], 0, v[136:137]
	s_addc_u32 s95, s65, 0
	s_add_i32 s36, s83, s69
	global_load_lds_dwordx4 v[198:199], off
	s_mov_b32 m0, s36
	v_lshl_add_u64 v[228:229], s[66:67], 0, v[134:135]
	global_load_lds_dwordx4 v132, s[94:95]
	s_add_i32 m0, s36, 0x2000
	s_nop 0
	global_load_lds_dwordx4 v136, s[94:95]
	v_lshl_add_u64 v[226:227], s[66:67], 0, v[130:131]
	s_mov_b32 m0, s72
	s_nop 0
	global_load_lds_dwordx4 v[226:227], off
	s_mov_b32 m0, s73
	s_nop 0
	global_load_lds_dwordx4 v[228:229], off
	s_waitcnt vmcnt(8)
	s_waitcnt lgkmcnt(0)
	s_barrier
	s_setprio 1
	s_waitcnt lgkmcnt(0)
	v_mfma_f32_16x16x32_bf16 v[62:65], v[146:149], v[190:193], v[62:65]
	v_mfma_f32_16x16x32_bf16 v[62:65], v[158:161], v[194:197], v[62:65]
	v_mfma_f32_16x16x32_bf16 v[58:61], v[170:173], v[194:197], v[58:61]
	v_mfma_f32_16x16x32_bf16 v[58:61], v[166:169], v[190:193], v[58:61]
	v_mfma_f32_16x16x32_bf16 v[42:45], v[166:169], v[202:205], v[42:45]
	v_mfma_f32_16x16x32_bf16 v[42:45], v[170:173], v[206:209], v[42:45]
	v_mfma_f32_16x16x32_bf16 v[46:49], v[158:161], v[206:209], v[46:49]
	v_mfma_f32_16x16x32_bf16 v[46:49], v[146:149], v[202:205], v[46:49]
	v_mfma_f32_16x16x32_bf16 v[30:33], v[146:149], v[210:213], v[30:33]
	v_mfma_f32_16x16x32_bf16 v[30:33], v[158:161], v[214:217], v[30:33]
	v_mfma_f32_16x16x32_bf16 v[26:29], v[170:173], v[214:217], v[26:29]
	v_mfma_f32_16x16x32_bf16 v[26:29], v[166:169], v[210:213], v[26:29]
	v_mfma_f32_16x16x32_bf16 v[10:13], v[166:169], v[218:221], v[10:13]
	v_mfma_f32_16x16x32_bf16 v[10:13], v[170:173], v[222:225], v[10:13]
	v_mfma_f32_16x16x32_bf16 v[14:17], v[158:161], v[222:225], v[14:17]
	v_mfma_f32_16x16x32_bf16 v[14:17], v[146:149], v[218:221], v[14:17]
	s_setprio 0
	s_setprio 1
	v_mfma_f32_16x16x32_bf16 v[54:57], v[174:177], v[190:193], v[54:57]
	v_mfma_f32_16x16x32_bf16 v[54:57], v[178:181], v[194:197], v[54:57]
	v_mfma_f32_16x16x32_bf16 v[50:53], v[186:189], v[194:197], v[50:53]
	v_mfma_f32_16x16x32_bf16 v[50:53], v[182:185], v[190:193], v[50:53]
	v_mfma_f32_16x16x32_bf16 v[34:37], v[182:185], v[202:205], v[34:37]
	v_mfma_f32_16x16x32_bf16 v[34:37], v[186:189], v[206:209], v[34:37]
	v_mfma_f32_16x16x32_bf16 v[38:41], v[178:181], v[206:209], v[38:41]
	v_mfma_f32_16x16x32_bf16 v[38:41], v[174:177], v[202:205], v[38:41]
	v_mfma_f32_16x16x32_bf16 v[22:25], v[174:177], v[210:213], v[22:25]
	v_mfma_f32_16x16x32_bf16 v[22:25], v[178:181], v[214:217], v[22:25]
	v_mfma_f32_16x16x32_bf16 v[18:21], v[186:189], v[214:217], v[18:21]
	v_mfma_f32_16x16x32_bf16 v[18:21], v[182:185], v[210:213], v[18:21]
	v_mfma_f32_16x16x32_bf16 v[2:5], v[182:185], v[218:221], v[2:5]
	v_mfma_f32_16x16x32_bf16 v[2:5], v[186:189], v[222:225], v[2:5]
	v_mfma_f32_16x16x32_bf16 v[6:9], v[178:181], v[222:225], v[6:9]
	v_mfma_f32_16x16x32_bf16 v[6:9], v[174:177], v[218:221], v[6:9]
	s_setprio 0
	s_barrier
	s_add_i32 s36, 0, 0x18000
	v_add_u32_e32 v138, s36, v152
	s_add_i32 s37, 0, 0x1c000
	ds_read_b128 v[146:149], v138
	ds_read_b128 v[158:161], v138 offset:1024
	ds_read_b128 v[166:169], v138 offset:2048
	ds_read_b128 v[170:173], v138 offset:3072
	v_add_u32_e32 v138, s37, v152
	ds_read_b128 v[174:177], v138
	ds_read_b128 v[178:181], v138 offset:1024
	ds_read_b128 v[182:185], v138 offset:2048
	ds_read_b128 v[186:189], v138 offset:3072
	s_add_u32 s66, s66, 0x100000
	s_addc_u32 s67, s67, 0
	s_mov_b32 m0, s74
	ds_read_b128 v[190:193], v156 offset:32768
	ds_read_b128 v[194:197], v156 offset:33792
	ds_read_b128 v[202:205], v156 offset:34816
	ds_read_b128 v[206:209], v156 offset:35840
	ds_read_b128 v[210:213], v156 offset:36864
	ds_read_b128 v[214:217], v156 offset:37888
	ds_read_b128 v[218:221], v156 offset:38912
	ds_read_b128 v[222:225], v156 offset:39936
	global_load_lds_dwordx4 v130, s[66:67]
	s_mov_b32 m0, s75
	s_nop 0
	global_load_lds_dwordx4 v134, s[66:67]
	s_waitcnt vmcnt(8)
	s_waitcnt lgkmcnt(0)
	s_barrier
	s_setprio 1
	s_waitcnt lgkmcnt(0)
	v_mfma_f32_16x16x32_bf16 v[126:129], v[146:149], v[190:193], v[126:129]
	v_mfma_f32_16x16x32_bf16 v[126:129], v[158:161], v[194:197], v[126:129]
	v_mfma_f32_16x16x32_bf16 v[122:125], v[170:173], v[194:197], v[122:125]
	v_mfma_f32_16x16x32_bf16 v[122:125], v[166:169], v[190:193], v[122:125]
	v_mfma_f32_16x16x32_bf16 v[106:109], v[166:169], v[202:205], v[106:109]
	v_mfma_f32_16x16x32_bf16 v[106:109], v[170:173], v[206:209], v[106:109]
	v_mfma_f32_16x16x32_bf16 v[110:113], v[158:161], v[206:209], v[110:113]
	v_mfma_f32_16x16x32_bf16 v[110:113], v[146:149], v[202:205], v[110:113]
	v_mfma_f32_16x16x32_bf16 v[94:97], v[146:149], v[210:213], v[94:97]
	v_mfma_f32_16x16x32_bf16 v[94:97], v[158:161], v[214:217], v[94:97]
	v_mfma_f32_16x16x32_bf16 v[90:93], v[170:173], v[214:217], v[90:93]
	v_mfma_f32_16x16x32_bf16 v[90:93], v[166:169], v[210:213], v[90:93]
	v_mfma_f32_16x16x32_bf16 v[74:77], v[166:169], v[218:221], v[74:77]
	v_mfma_f32_16x16x32_bf16 v[74:77], v[170:173], v[222:225], v[74:77]
	v_mfma_f32_16x16x32_bf16 v[78:81], v[158:161], v[222:225], v[78:81]
	v_mfma_f32_16x16x32_bf16 v[78:81], v[146:149], v[218:221], v[78:81]
	s_setprio 0
	s_setprio 1
	v_mfma_f32_16x16x32_bf16 v[118:121], v[174:177], v[190:193], v[118:121]
	v_mfma_f32_16x16x32_bf16 v[118:121], v[178:181], v[194:197], v[118:121]
	v_mfma_f32_16x16x32_bf16 v[114:117], v[186:189], v[194:197], v[114:117]
	v_mfma_f32_16x16x32_bf16 v[114:117], v[182:185], v[190:193], v[114:117]
	v_mfma_f32_16x16x32_bf16 v[98:101], v[182:185], v[202:205], v[98:101]
	v_mfma_f32_16x16x32_bf16 v[98:101], v[186:189], v[206:209], v[98:101]
	v_mfma_f32_16x16x32_bf16 v[102:105], v[178:181], v[206:209], v[102:105]
	v_mfma_f32_16x16x32_bf16 v[102:105], v[174:177], v[202:205], v[102:105]
	v_mfma_f32_16x16x32_bf16 v[86:89], v[174:177], v[210:213], v[86:89]
	v_mfma_f32_16x16x32_bf16 v[86:89], v[178:181], v[214:217], v[86:89]
	v_mfma_f32_16x16x32_bf16 v[82:85], v[186:189], v[214:217], v[82:85]
	v_mfma_f32_16x16x32_bf16 v[82:85], v[182:185], v[210:213], v[82:85]
	v_mfma_f32_16x16x32_bf16 v[66:69], v[182:185], v[218:221], v[66:69]
	v_mfma_f32_16x16x32_bf16 v[66:69], v[186:189], v[222:225], v[66:69]
	v_mfma_f32_16x16x32_bf16 v[70:73], v[178:181], v[222:225], v[70:73]
	v_mfma_f32_16x16x32_bf16 v[70:73], v[174:177], v[218:221], v[70:73]
	s_setprio 0
	s_barrier
	s_add_i32 s36, s36, s69
	v_lshl_add_u64 v[150:151], v[150:151], 0, s[16:17]
	s_mov_b32 m0, s36
	ds_read_b128 v[190:193], v156 offset:49152
	ds_read_b128 v[194:197], v156 offset:50176
	ds_read_b128 v[202:205], v156 offset:51200
	ds_read_b128 v[206:209], v156 offset:52224
	ds_read_b128 v[210:213], v156 offset:53248
	ds_read_b128 v[214:217], v156 offset:54272
	ds_read_b128 v[218:221], v156 offset:55296
	ds_read_b128 v[222:225], v156 offset:56320
	global_load_lds_dwordx4 v[150:151], off
	s_add_i32 m0, s36, 0x2000
	s_add_u32 s64, s64, 0x100080
	v_lshl_add_u64 v[150:151], v[198:199], 0, s[16:17]
	s_addc_u32 s65, s65, 0
	s_add_i32 s36, s37, s69
	global_load_lds_dwordx4 v[150:151], off
	s_mov_b32 m0, s36
	s_nop 0
	global_load_lds_dwordx4 v132, s[64:65]
	s_add_i32 m0, s36, 0x2000
	s_nop 0
	global_load_lds_dwordx4 v136, s[64:65]
	v_lshl_add_u64 v[150:151], v[226:227], 0, s[16:17]
	s_mov_b32 m0, s78
	s_nop 0
	global_load_lds_dwordx4 v[150:151], off
	v_lshl_add_u64 v[150:151], v[228:229], 0, s[16:17]
	s_mov_b32 m0, s79
	s_nop 0
	global_load_lds_dwordx4 v[150:151], off
	s_waitcnt vmcnt(8)
	s_waitcnt lgkmcnt(0)
	s_barrier
	s_setprio 1
	s_waitcnt lgkmcnt(0)
	v_mfma_f32_16x16x32_bf16 v[62:65], v[146:149], v[190:193], v[62:65]
	v_mfma_f32_16x16x32_bf16 v[62:65], v[158:161], v[194:197], v[62:65]
	v_mfma_f32_16x16x32_bf16 v[58:61], v[170:173], v[194:197], v[58:61]
	v_mfma_f32_16x16x32_bf16 v[58:61], v[166:169], v[190:193], v[58:61]
	v_mfma_f32_16x16x32_bf16 v[42:45], v[166:169], v[202:205], v[42:45]
	v_mfma_f32_16x16x32_bf16 v[42:45], v[170:173], v[206:209], v[42:45]
	v_mfma_f32_16x16x32_bf16 v[46:49], v[158:161], v[206:209], v[46:49]
	v_mfma_f32_16x16x32_bf16 v[46:49], v[146:149], v[202:205], v[46:49]
	v_mfma_f32_16x16x32_bf16 v[30:33], v[146:149], v[210:213], v[30:33]
	v_mfma_f32_16x16x32_bf16 v[30:33], v[158:161], v[214:217], v[30:33]
	v_mfma_f32_16x16x32_bf16 v[26:29], v[170:173], v[214:217], v[26:29]
	v_mfma_f32_16x16x32_bf16 v[26:29], v[166:169], v[210:213], v[26:29]
	v_mfma_f32_16x16x32_bf16 v[10:13], v[166:169], v[218:221], v[10:13]
	v_mfma_f32_16x16x32_bf16 v[10:13], v[170:173], v[222:225], v[10:13]
	v_mfma_f32_16x16x32_bf16 v[14:17], v[158:161], v[222:225], v[14:17]
	v_mfma_f32_16x16x32_bf16 v[14:17], v[146:149], v[218:221], v[14:17]
	s_setprio 0
	s_setprio 1
	v_mfma_f32_16x16x32_bf16 v[54:57], v[174:177], v[190:193], v[54:57]
	v_mfma_f32_16x16x32_bf16 v[54:57], v[178:181], v[194:197], v[54:57]
	v_mfma_f32_16x16x32_bf16 v[50:53], v[186:189], v[194:197], v[50:53]
	v_mfma_f32_16x16x32_bf16 v[50:53], v[182:185], v[190:193], v[50:53]
	v_mfma_f32_16x16x32_bf16 v[34:37], v[182:185], v[202:205], v[34:37]
	v_mfma_f32_16x16x32_bf16 v[34:37], v[186:189], v[206:209], v[34:37]
	v_mfma_f32_16x16x32_bf16 v[38:41], v[178:181], v[206:209], v[38:41]
	v_mfma_f32_16x16x32_bf16 v[38:41], v[174:177], v[202:205], v[38:41]
	v_mfma_f32_16x16x32_bf16 v[22:25], v[174:177], v[210:213], v[22:25]
	v_mfma_f32_16x16x32_bf16 v[22:25], v[178:181], v[214:217], v[22:25]
	v_mfma_f32_16x16x32_bf16 v[18:21], v[186:189], v[214:217], v[18:21]
	v_mfma_f32_16x16x32_bf16 v[18:21], v[182:185], v[210:213], v[18:21]
	v_mfma_f32_16x16x32_bf16 v[2:5], v[182:185], v[218:221], v[2:5]
	v_mfma_f32_16x16x32_bf16 v[2:5], v[186:189], v[222:225], v[2:5]
	v_mfma_f32_16x16x32_bf16 v[6:9], v[178:181], v[222:225], v[6:9]
	v_mfma_f32_16x16x32_bf16 v[6:9], v[174:177], v[218:221], v[6:9]
	s_setprio 0
	s_barrier
	s_add_u32 s62, s62, 0x100
	s_addc_u32 s63, s63, 0
	s_add_u32 s61, s61, 0x100
	s_addc_u32 s92, s92, 0
	s_cmp_ge_i32 s93, s11
	s_mov_b32 s44, s93
	s_cbranch_scc0 .LBB0_1397
	s_and_b64 vcc, exec, s[18:19]
	s_cbranch_vccz .LBB0_1400

.LBB0_1631:
	ds_read_b128 v[166:169], v158
	ds_read_b128 v[170:173], v158 offset:1024
	ds_read_b128 v[174:177], v158 offset:2048
	ds_read_b128 v[178:181], v158 offset:3072
	ds_read_b128 v[182:185], v159
	ds_read_b128 v[186:189], v159 offset:1024
	ds_read_b128 v[190:193], v159 offset:2048
	ds_read_b128 v[194:197], v159 offset:3072
	s_add_u32 s36, s54, 0xfff00080
	s_addc_u32 s37, s55, -1
	s_cmp_eq_u32 s78, 60
	s_cselect_b32 s59, s21, s37
	s_cselect_b32 s58, s74, s36
	s_cselect_b32 s57, s19, s77
	s_cselect_b32 s56, s75, s76
	s_add_i32 m0, s53, 0xc000
	ds_read_b128 v[202:205], v160
	ds_read_b128 v[206:209], v160 offset:1024
	ds_read_b128 v[210:213], v160 offset:2048
	ds_read_b128 v[214:217], v160 offset:3072
	ds_read_b128 v[218:221], v160 offset:4096
	ds_read_b128 v[222:225], v160 offset:5120
	ds_read_b128 v[226:229], v160 offset:6144
	ds_read_b128 v[230:233], v160 offset:7168
	global_load_lds_dwordx4 v140, s[54:55]
	s_add_i32 m0, s53, 0xe000
	s_nop 0
	global_load_lds_dwordx4 v142, s[54:55]
	s_waitcnt vmcnt(8)
	s_waitcnt lgkmcnt(0)
	s_barrier
	s_setprio 1
	s_waitcnt lgkmcnt(0)
	v_mfma_f32_16x16x32_bf16 v[126:129], v[166:169], v[202:205], v[126:129]
	v_mfma_f32_16x16x32_bf16 v[126:129], v[170:173], v[206:209], v[126:129]
	v_mfma_f32_16x16x32_bf16 v[122:125], v[178:181], v[206:209], v[122:125]
	v_mfma_f32_16x16x32_bf16 v[122:125], v[174:177], v[202:205], v[122:125]
	v_mfma_f32_16x16x32_bf16 v[110:113], v[174:177], v[210:213], v[110:113]
	v_mfma_f32_16x16x32_bf16 v[110:113], v[178:181], v[214:217], v[110:113]
	v_mfma_f32_16x16x32_bf16 v[118:121], v[170:173], v[214:217], v[118:121]
	v_mfma_f32_16x16x32_bf16 v[118:121], v[166:169], v[210:213], v[118:121]
	v_mfma_f32_16x16x32_bf16 v[102:105], v[166:169], v[218:221], v[102:105]
	v_mfma_f32_16x16x32_bf16 v[102:105], v[170:173], v[222:225], v[102:105]
	v_mfma_f32_16x16x32_bf16 v[94:97], v[178:181], v[222:225], v[94:97]
	v_mfma_f32_16x16x32_bf16 v[94:97], v[174:177], v[218:221], v[94:97]
	v_mfma_f32_16x16x32_bf16 v[78:81], v[174:177], v[226:229], v[78:81]
	v_mfma_f32_16x16x32_bf16 v[78:81], v[178:181], v[230:233], v[78:81]
	v_mfma_f32_16x16x32_bf16 v[86:89], v[170:173], v[230:233], v[86:89]
	v_mfma_f32_16x16x32_bf16 v[86:89], v[166:169], v[226:229], v[86:89]
	s_setprio 0
	s_setprio 1
	v_mfma_f32_16x16x32_bf16 v[114:117], v[182:185], v[202:205], v[114:117]
	v_mfma_f32_16x16x32_bf16 v[114:117], v[186:189], v[206:209], v[114:117]
	v_mfma_f32_16x16x32_bf16 v[106:109], v[194:197], v[206:209], v[106:109]
	v_mfma_f32_16x16x32_bf16 v[106:109], v[190:193], v[202:205], v[106:109]
	v_mfma_f32_16x16x32_bf16 v[90:93], v[190:193], v[210:213], v[90:93]
	v_mfma_f32_16x16x32_bf16 v[90:93], v[194:197], v[214:217], v[90:93]
	v_mfma_f32_16x16x32_bf16 v[98:101], v[186:189], v[214:217], v[98:101]
	v_mfma_f32_16x16x32_bf16 v[98:101], v[182:185], v[210:213], v[98:101]
	v_mfma_f32_16x16x32_bf16 v[82:85], v[182:185], v[218:221], v[82:85]
	v_mfma_f32_16x16x32_bf16 v[82:85], v[186:189], v[222:225], v[82:85]
	v_mfma_f32_16x16x32_bf16 v[74:77], v[194:197], v[222:225], v[74:77]
	v_mfma_f32_16x16x32_bf16 v[74:77], v[190:193], v[218:221], v[74:77]
	v_mfma_f32_16x16x32_bf16 v[66:69], v[190:193], v[226:229], v[66:69]
	v_mfma_f32_16x16x32_bf16 v[66:69], v[194:197], v[230:233], v[66:69]
	v_mfma_f32_16x16x32_bf16 v[70:73], v[186:189], v[230:233], v[70:73]
	v_mfma_f32_16x16x32_bf16 v[70:73], v[182:185], v[226:229], v[70:73]
	s_setprio 0
	s_barrier
	s_add_i32 s36, s68, s38
	v_lshl_add_u64 v[198:199], s[56:57], 0, v[136:137]
	s_mov_b32 m0, s36
	ds_read_b128 v[202:205], v160 offset:16384
	ds_read_b128 v[206:209], v160 offset:17408
	ds_read_b128 v[210:213], v160 offset:18432
	ds_read_b128 v[214:217], v160 offset:19456
	ds_read_b128 v[218:221], v160 offset:20480
	ds_read_b128 v[222:225], v160 offset:21504
	ds_read_b128 v[226:229], v160 offset:22528
	ds_read_b128 v[230:233], v160 offset:23552
	global_load_lds_dwordx4 v[198:199], off
	s_add_i32 m0, s36, 0x2000
	s_add_u32 s80, s56, 0x100000
	v_lshl_add_u64 v[234:235], s[56:57], 0, v[132:133]
	s_addc_u32 s81, s57, 0
	s_add_i32 s36, s69, s38
	global_load_lds_dwordx4 v[234:235], off
	s_mov_b32 m0, s36
	v_lshl_add_u64 v[238:239], s[58:59], 0, v[134:135]
	global_load_lds_dwordx4 v136, s[80:81]
	s_add_i32 m0, s36, 0x2000
	s_nop 0
	global_load_lds_dwordx4 v132, s[80:81]
	v_lshl_add_u64 v[236:237], s[58:59], 0, v[138:139]
	s_mov_b32 m0, s53
	s_nop 0
	global_load_lds_dwordx4 v[236:237], off
	s_mov_b32 m0, s61
	s_nop 0
	global_load_lds_dwordx4 v[238:239], off
	s_waitcnt vmcnt(8)
	s_waitcnt lgkmcnt(0)
	s_barrier
	s_setprio 1
	s_waitcnt lgkmcnt(0)
	v_mfma_f32_16x16x32_bf16 v[62:65], v[166:169], v[202:205], v[62:65]
	v_mfma_f32_16x16x32_bf16 v[62:65], v[170:173], v[206:209], v[62:65]
	v_mfma_f32_16x16x32_bf16 v[58:61], v[178:181], v[206:209], v[58:61]
	v_mfma_f32_16x16x32_bf16 v[58:61], v[174:177], v[202:205], v[58:61]
	v_mfma_f32_16x16x32_bf16 v[46:49], v[174:177], v[210:213], v[46:49]
	v_mfma_f32_16x16x32_bf16 v[46:49], v[178:181], v[214:217], v[46:49]
	v_mfma_f32_16x16x32_bf16 v[54:57], v[170:173], v[214:217], v[54:57]
	v_mfma_f32_16x16x32_bf16 v[54:57], v[166:169], v[210:213], v[54:57]
	v_mfma_f32_16x16x32_bf16 v[38:41], v[166:169], v[218:221], v[38:41]
	v_mfma_f32_16x16x32_bf16 v[38:41], v[170:173], v[222:225], v[38:41]
	v_mfma_f32_16x16x32_bf16 v[30:33], v[178:181], v[222:225], v[30:33]
	v_mfma_f32_16x16x32_bf16 v[30:33], v[174:177], v[218:221], v[30:33]
	v_mfma_f32_16x16x32_bf16 v[14:17], v[174:177], v[226:229], v[14:17]
	v_mfma_f32_16x16x32_bf16 v[14:17], v[178:181], v[230:233], v[14:17]
	v_mfma_f32_16x16x32_bf16 v[22:25], v[170:173], v[230:233], v[22:25]
	v_mfma_f32_16x16x32_bf16 v[22:25], v[166:169], v[226:229], v[22:25]
	s_setprio 0
	s_setprio 1
	v_mfma_f32_16x16x32_bf16 v[50:53], v[182:185], v[202:205], v[50:53]
	v_mfma_f32_16x16x32_bf16 v[50:53], v[186:189], v[206:209], v[50:53]
	v_mfma_f32_16x16x32_bf16 v[42:45], v[194:197], v[206:209], v[42:45]
	v_mfma_f32_16x16x32_bf16 v[42:45], v[190:193], v[202:205], v[42:45]
	v_mfma_f32_16x16x32_bf16 v[26:29], v[190:193], v[210:213], v[26:29]
	v_mfma_f32_16x16x32_bf16 v[26:29], v[194:197], v[214:217], v[26:29]
	v_mfma_f32_16x16x32_bf16 v[34:37], v[186:189], v[214:217], v[34:37]
	v_mfma_f32_16x16x32_bf16 v[34:37], v[182:185], v[210:213], v[34:37]
	v_mfma_f32_16x16x32_bf16 v[18:21], v[182:185], v[218:221], v[18:21]
	v_mfma_f32_16x16x32_bf16 v[18:21], v[186:189], v[222:225], v[18:21]
	v_mfma_f32_16x16x32_bf16 v[10:13], v[194:197], v[222:225], v[10:13]
	v_mfma_f32_16x16x32_bf16 v[10:13], v[190:193], v[218:221], v[10:13]
	v_mfma_f32_16x16x32_bf16 v[2:5], v[190:193], v[226:229], v[2:5]
	v_mfma_f32_16x16x32_bf16 v[2:5], v[194:197], v[230:233], v[2:5]
	v_mfma_f32_16x16x32_bf16 v[6:9], v[186:189], v[230:233], v[6:9]
	v_mfma_f32_16x16x32_bf16 v[6:9], v[182:185], v[226:229], v[6:9]
	s_setprio 0
	s_barrier
	s_add_i32 s36, 0, 0x18000
	v_add_u32_e32 v161, s36, v156
	s_add_i32 s37, 0, 0x1c000
	ds_read_b128 v[166:169], v161
	ds_read_b128 v[170:173], v161 offset:1024
	ds_read_b128 v[174:177], v161 offset:2048
	ds_read_b128 v[178:181], v161 offset:3072
	v_add_u32_e32 v161, s37, v156
	ds_read_b128 v[182:185], v161
	ds_read_b128 v[186:189], v161 offset:1024
	ds_read_b128 v[190:193], v161 offset:2048
	ds_read_b128 v[194:197], v161 offset:3072
	s_add_u32 s58, s58, 0x100000
	s_addc_u32 s59, s59, 0
	s_mov_b32 m0, s62
	ds_read_b128 v[202:205], v160 offset:32768
	ds_read_b128 v[206:209], v160 offset:33792
	ds_read_b128 v[210:213], v160 offset:34816
	ds_read_b128 v[214:217], v160 offset:35840
	ds_read_b128 v[218:221], v160 offset:36864
	ds_read_b128 v[222:225], v160 offset:37888
	ds_read_b128 v[226:229], v160 offset:38912
	ds_read_b128 v[230:233], v160 offset:39936
	global_load_lds_dwordx4 v138, s[58:59]
	s_mov_b32 m0, s63
	s_nop 0
	global_load_lds_dwordx4 v134, s[58:59]
	s_waitcnt vmcnt(8)
	s_waitcnt lgkmcnt(0)
	s_barrier
	s_setprio 1
	s_waitcnt lgkmcnt(0)
	v_mfma_f32_16x16x32_bf16 v[126:129], v[166:169], v[202:205], v[126:129]
	v_mfma_f32_16x16x32_bf16 v[126:129], v[170:173], v[206:209], v[126:129]
	v_mfma_f32_16x16x32_bf16 v[122:125], v[178:181], v[206:209], v[122:125]
	v_mfma_f32_16x16x32_bf16 v[122:125], v[174:177], v[202:205], v[122:125]
	v_mfma_f32_16x16x32_bf16 v[110:113], v[174:177], v[210:213], v[110:113]
	v_mfma_f32_16x16x32_bf16 v[110:113], v[178:181], v[214:217], v[110:113]
	v_mfma_f32_16x16x32_bf16 v[118:121], v[170:173], v[214:217], v[118:121]
	v_mfma_f32_16x16x32_bf16 v[118:121], v[166:169], v[210:213], v[118:121]
	v_mfma_f32_16x16x32_bf16 v[102:105], v[166:169], v[218:221], v[102:105]
	v_mfma_f32_16x16x32_bf16 v[102:105], v[170:173], v[222:225], v[102:105]
	v_mfma_f32_16x16x32_bf16 v[94:97], v[178:181], v[222:225], v[94:97]
	v_mfma_f32_16x16x32_bf16 v[94:97], v[174:177], v[218:221], v[94:97]
	v_mfma_f32_16x16x32_bf16 v[78:81], v[174:177], v[226:229], v[78:81]
	v_mfma_f32_16x16x32_bf16 v[78:81], v[178:181], v[230:233], v[78:81]
	v_mfma_f32_16x16x32_bf16 v[86:89], v[170:173], v[230:233], v[86:89]
	v_mfma_f32_16x16x32_bf16 v[86:89], v[166:169], v[226:229], v[86:89]
	s_setprio 0
	s_setprio 1
	v_mfma_f32_16x16x32_bf16 v[114:117], v[182:185], v[202:205], v[114:117]
	v_mfma_f32_16x16x32_bf16 v[114:117], v[186:189], v[206:209], v[114:117]
	v_mfma_f32_16x16x32_bf16 v[106:109], v[194:197], v[206:209], v[106:109]
	v_mfma_f32_16x16x32_bf16 v[106:109], v[190:193], v[202:205], v[106:109]
	v_mfma_f32_16x16x32_bf16 v[90:93], v[190:193], v[210:213], v[90:93]
	v_mfma_f32_16x16x32_bf16 v[90:93], v[194:197], v[214:217], v[90:93]
	v_mfma_f32_16x16x32_bf16 v[98:101], v[186:189], v[214:217], v[98:101]
	v_mfma_f32_16x16x32_bf16 v[98:101], v[182:185], v[210:213], v[98:101]
	v_mfma_f32_16x16x32_bf16 v[82:85], v[182:185], v[218:221], v[82:85]
	v_mfma_f32_16x16x32_bf16 v[82:85], v[186:189], v[222:225], v[82:85]
	v_mfma_f32_16x16x32_bf16 v[74:77], v[194:197], v[222:225], v[74:77]
	v_mfma_f32_16x16x32_bf16 v[74:77], v[190:193], v[218:221], v[74:77]
	v_mfma_f32_16x16x32_bf16 v[66:69], v[190:193], v[226:229], v[66:69]
	v_mfma_f32_16x16x32_bf16 v[66:69], v[194:197], v[230:233], v[66:69]
	v_mfma_f32_16x16x32_bf16 v[70:73], v[186:189], v[230:233], v[70:73]
	v_mfma_f32_16x16x32_bf16 v[70:73], v[182:185], v[226:229], v[70:73]
	s_setprio 0
	s_barrier
	s_add_i32 s36, s36, s38
	v_lshl_add_u64 v[198:199], v[198:199], 0, s[14:15]
	s_mov_b32 m0, s36
	ds_read_b128 v[202:205], v160 offset:49152
	ds_read_b128 v[206:209], v160 offset:50176
	ds_read_b128 v[210:213], v160 offset:51200
	ds_read_b128 v[214:217], v160 offset:52224
	ds_read_b128 v[218:221], v160 offset:53248
	ds_read_b128 v[222:225], v160 offset:54272
	ds_read_b128 v[226:229], v160 offset:55296
	ds_read_b128 v[230:233], v160 offset:56320
	global_load_lds_dwordx4 v[198:199], off
	s_add_i32 m0, s36, 0x2000
	s_add_u32 s56, s56, 0x100080
	v_lshl_add_u64 v[198:199], v[234:235], 0, s[14:15]
	s_addc_u32 s57, s57, 0
	s_add_i32 s36, s37, s38
	global_load_lds_dwordx4 v[198:199], off
	s_mov_b32 m0, s36
	s_nop 0
	global_load_lds_dwordx4 v136, s[56:57]
	s_add_i32 m0, s36, 0x2000
	s_nop 0
	global_load_lds_dwordx4 v132, s[56:57]
	v_lshl_add_u64 v[198:199], v[236:237], 0, s[14:15]
	s_mov_b32 m0, s65
	s_nop 0
	global_load_lds_dwordx4 v[198:199], off
	v_lshl_add_u64 v[198:199], v[238:239], 0, s[14:15]
	s_mov_b32 m0, s66
	s_nop 0
	global_load_lds_dwordx4 v[198:199], off
	s_waitcnt vmcnt(8)
	s_waitcnt lgkmcnt(0)
	s_barrier
	s_setprio 1
	s_waitcnt lgkmcnt(0)
	v_mfma_f32_16x16x32_bf16 v[62:65], v[166:169], v[202:205], v[62:65]
	v_mfma_f32_16x16x32_bf16 v[62:65], v[170:173], v[206:209], v[62:65]
	v_mfma_f32_16x16x32_bf16 v[58:61], v[178:181], v[206:209], v[58:61]
	v_mfma_f32_16x16x32_bf16 v[58:61], v[174:177], v[202:205], v[58:61]
	v_mfma_f32_16x16x32_bf16 v[46:49], v[174:177], v[210:213], v[46:49]
	v_mfma_f32_16x16x32_bf16 v[46:49], v[178:181], v[214:217], v[46:49]
	v_mfma_f32_16x16x32_bf16 v[54:57], v[170:173], v[214:217], v[54:57]
	v_mfma_f32_16x16x32_bf16 v[54:57], v[166:169], v[210:213], v[54:57]
	v_mfma_f32_16x16x32_bf16 v[38:41], v[166:169], v[218:221], v[38:41]
	v_mfma_f32_16x16x32_bf16 v[38:41], v[170:173], v[222:225], v[38:41]
	v_mfma_f32_16x16x32_bf16 v[30:33], v[178:181], v[222:225], v[30:33]
	v_mfma_f32_16x16x32_bf16 v[30:33], v[174:177], v[218:221], v[30:33]
	v_mfma_f32_16x16x32_bf16 v[14:17], v[174:177], v[226:229], v[14:17]
	v_mfma_f32_16x16x32_bf16 v[14:17], v[178:181], v[230:233], v[14:17]
	v_mfma_f32_16x16x32_bf16 v[22:25], v[170:173], v[230:233], v[22:25]
	v_mfma_f32_16x16x32_bf16 v[22:25], v[166:169], v[226:229], v[22:25]
	s_setprio 0
	s_setprio 1
	v_mfma_f32_16x16x32_bf16 v[50:53], v[182:185], v[202:205], v[50:53]
	v_mfma_f32_16x16x32_bf16 v[50:53], v[186:189], v[206:209], v[50:53]
	v_mfma_f32_16x16x32_bf16 v[42:45], v[194:197], v[206:209], v[42:45]
	v_mfma_f32_16x16x32_bf16 v[42:45], v[190:193], v[202:205], v[42:45]
	v_mfma_f32_16x16x32_bf16 v[26:29], v[190:193], v[210:213], v[26:29]
	v_mfma_f32_16x16x32_bf16 v[26:29], v[194:197], v[214:217], v[26:29]
	v_mfma_f32_16x16x32_bf16 v[34:37], v[186:189], v[214:217], v[34:37]
	v_mfma_f32_16x16x32_bf16 v[34:37], v[182:185], v[210:213], v[34:37]
	v_mfma_f32_16x16x32_bf16 v[18:21], v[182:185], v[218:221], v[18:21]
	v_mfma_f32_16x16x32_bf16 v[18:21], v[186:189], v[222:225], v[18:21]
	v_mfma_f32_16x16x32_bf16 v[10:13], v[194:197], v[222:225], v[10:13]
	v_mfma_f32_16x16x32_bf16 v[10:13], v[190:193], v[218:221], v[10:13]
	v_mfma_f32_16x16x32_bf16 v[2:5], v[190:193], v[226:229], v[2:5]
	v_mfma_f32_16x16x32_bf16 v[2:5], v[194:197], v[230:233], v[2:5]
	v_mfma_f32_16x16x32_bf16 v[6:9], v[186:189], v[230:233], v[6:9]
	v_mfma_f32_16x16x32_bf16 v[6:9], v[182:185], v[226:229], v[6:9]
	s_setprio 0
	s_barrier
	s_add_i32 s78, s78, 2
	s_add_u32 s54, s54, 0x100
	s_addc_u32 s55, s55, 0
	s_add_u32 s76, s76, 0x100
	s_addc_u32 s77, s77, 0
	s_cmp_gt_u32 s78, 61
	s_cbranch_scc0 .LBB0_1631
	s_and_b64 vcc, exec, s[16:17]
	s_cbranch_vccz .LBB0_1634
	s_barrier

.LBB0_1649:
	s_add_u32 s36, s56, s44
	s_addc_u32 s37, s57, 0
	s_add_u32 s64, s36, 0x100
	s_addc_u32 s65, s37, 0
	s_and_b64 s[62:63], s[60:61], exec
	s_cselect_b32 s65, s21, s65
	s_cselect_b32 s64, s87, s64
	s_add_u32 s44, s54, s44
	s_addc_u32 s62, s55, 0
	s_add_u32 s44, s44, 0x100
	s_addc_u32 s62, s62, 0
	s_and_b64 s[60:61], s[60:61], exec
	s_cselect_b32 s67, s19, s62
	s_cselect_b32 s66, s89, s44
	s_add_u32 s70, s36, 0x10080
	s_addc_u32 s71, s37, 0
	s_add_i32 vcc_lo, s84, s39
	ds_read_b128 v[158:161], v147
	ds_read_b128 v[166:169], v147 offset:1024
	ds_read_b128 v[170:173], v147 offset:2048
	ds_read_b128 v[174:177], v147 offset:3072
	ds_read_b128 v[178:181], v155
	ds_read_b128 v[182:185], v155 offset:1024
	ds_read_b128 v[186:189], v155 offset:2048
	ds_read_b128 v[190:193], v155 offset:3072
	s_add_i32 m0, s53, 0xc000
	s_add_i32 vcc_hi, s53, 0xe000
	s_add_i32 s95, vcc_lo, 0x2000
	s_add_u32 s68, s66, 0x10000
	s_addc_u32 s69, s67, 0
	s_add_i32 s97, s85, s39
	s_add_i32 s96, s97, 0x2000
	s_add_i32 s94, 0, 0x18000
	s_add_i32 s93, 0, 0x1c000
	s_add_u32 s62, s64, 0x10000
	s_addc_u32 s63, s65, 0
	s_add_i32 s92, s94, s39
	s_add_i32 s90, s92, 0x2000
	s_add_u32 s60, s66, 0x10080
	s_addc_u32 s61, s67, 0
	s_add_i32 s91, s93, s39
	s_add_i32 s44, s91, 0x2000
	ds_read_b128 v[194:197], v156
	ds_read_b128 v[202:205], v156 offset:1024
	ds_read_b128 v[206:209], v156 offset:2048
	ds_read_b128 v[210:213], v156 offset:3072
	ds_read_b128 v[214:217], v156 offset:4096
	ds_read_b128 v[218:221], v156 offset:5120
	ds_read_b128 v[222:225], v156 offset:6144
	ds_read_b128 v[226:229], v156 offset:7168
	global_load_lds_dwordx4 v138, s[70:71]
	s_mov_b32 m0, vcc_hi
	s_nop 0
	global_load_lds_dwordx4 v134, s[70:71]
	s_waitcnt vmcnt(8)
	s_waitcnt lgkmcnt(0)
	s_barrier
	s_setprio 1
	s_waitcnt lgkmcnt(0)
	v_mfma_f32_16x16x32_bf16 v[126:129], v[158:161], v[194:197], v[126:129]
	v_mfma_f32_16x16x32_bf16 v[126:129], v[166:169], v[202:205], v[126:129]
	v_mfma_f32_16x16x32_bf16 v[122:125], v[174:177], v[202:205], v[122:125]
	v_mfma_f32_16x16x32_bf16 v[122:125], v[170:173], v[194:197], v[122:125]
	v_mfma_f32_16x16x32_bf16 v[110:113], v[170:173], v[206:209], v[110:113]
	v_mfma_f32_16x16x32_bf16 v[110:113], v[174:177], v[210:213], v[110:113]
	v_mfma_f32_16x16x32_bf16 v[118:121], v[166:169], v[210:213], v[118:121]
	v_mfma_f32_16x16x32_bf16 v[118:121], v[158:161], v[206:209], v[118:121]
	v_mfma_f32_16x16x32_bf16 v[102:105], v[158:161], v[214:217], v[102:105]
	v_mfma_f32_16x16x32_bf16 v[102:105], v[166:169], v[218:221], v[102:105]
	v_mfma_f32_16x16x32_bf16 v[94:97], v[174:177], v[218:221], v[94:97]
	v_mfma_f32_16x16x32_bf16 v[94:97], v[170:173], v[214:217], v[94:97]
	v_mfma_f32_16x16x32_bf16 v[78:81], v[170:173], v[222:225], v[78:81]
	v_mfma_f32_16x16x32_bf16 v[78:81], v[174:177], v[226:229], v[78:81]
	v_mfma_f32_16x16x32_bf16 v[86:89], v[166:169], v[226:229], v[86:89]
	v_mfma_f32_16x16x32_bf16 v[86:89], v[158:161], v[222:225], v[86:89]
	s_setprio 0
	s_setprio 1
	v_mfma_f32_16x16x32_bf16 v[114:117], v[178:181], v[194:197], v[114:117]
	v_mfma_f32_16x16x32_bf16 v[114:117], v[182:185], v[202:205], v[114:117]
	v_mfma_f32_16x16x32_bf16 v[106:109], v[190:193], v[202:205], v[106:109]
	v_mfma_f32_16x16x32_bf16 v[106:109], v[186:189], v[194:197], v[106:109]
	v_mfma_f32_16x16x32_bf16 v[90:93], v[186:189], v[206:209], v[90:93]
	v_mfma_f32_16x16x32_bf16 v[90:93], v[190:193], v[210:213], v[90:93]
	v_mfma_f32_16x16x32_bf16 v[98:101], v[182:185], v[210:213], v[98:101]
	v_mfma_f32_16x16x32_bf16 v[98:101], v[178:181], v[206:209], v[98:101]
	v_mfma_f32_16x16x32_bf16 v[82:85], v[178:181], v[214:217], v[82:85]
	v_mfma_f32_16x16x32_bf16 v[82:85], v[182:185], v[218:221], v[82:85]
	v_mfma_f32_16x16x32_bf16 v[74:77], v[190:193], v[218:221], v[74:77]
	v_mfma_f32_16x16x32_bf16 v[74:77], v[186:189], v[214:217], v[74:77]
	v_mfma_f32_16x16x32_bf16 v[66:69], v[186:189], v[222:225], v[66:69]
	v_mfma_f32_16x16x32_bf16 v[66:69], v[190:193], v[226:229], v[66:69]
	v_mfma_f32_16x16x32_bf16 v[70:73], v[182:185], v[226:229], v[70:73]
	v_mfma_f32_16x16x32_bf16 v[70:73], v[178:181], v[222:225], v[70:73]
	s_setprio 0
	s_barrier
	s_mov_b32 m0, vcc_lo
	v_lshl_add_u64 v[198:199], s[66:67], 0, v[136:137]
	ds_read_b128 v[194:197], v156 offset:16384
	ds_read_b128 v[202:205], v156 offset:17408
	ds_read_b128 v[206:209], v156 offset:18432
	ds_read_b128 v[210:213], v156 offset:19456
	ds_read_b128 v[214:217], v156 offset:20480
	ds_read_b128 v[218:221], v156 offset:21504
	ds_read_b128 v[222:225], v156 offset:22528
	ds_read_b128 v[226:229], v156 offset:23552
	global_load_lds_dwordx4 v[198:199], off
	v_lshl_add_u64 v[230:231], s[66:67], 0, v[132:133]
	s_mov_b32 m0, s95
	s_nop 0
	global_load_lds_dwordx4 v[230:231], off
	s_mov_b32 m0, s97
	v_lshl_add_u64 v[234:235], s[64:65], 0, v[134:135]
	global_load_lds_dwordx4 v136, s[68:69]
	s_mov_b32 m0, s96
	s_nop 0
	global_load_lds_dwordx4 v132, s[68:69]
	v_lshl_add_u64 v[232:233], s[64:65], 0, v[138:139]
	s_mov_b32 m0, s53
	s_nop 0
	global_load_lds_dwordx4 v[232:233], off
	s_mov_b32 m0, s75
	s_nop 0
	global_load_lds_dwordx4 v[234:235], off
	s_waitcnt vmcnt(8)
	s_waitcnt lgkmcnt(0)
	s_barrier
	s_setprio 1
	s_waitcnt lgkmcnt(0)
	v_mfma_f32_16x16x32_bf16 v[62:65], v[158:161], v[194:197], v[62:65]
	v_mfma_f32_16x16x32_bf16 v[62:65], v[166:169], v[202:205], v[62:65]
	v_mfma_f32_16x16x32_bf16 v[58:61], v[174:177], v[202:205], v[58:61]
	v_mfma_f32_16x16x32_bf16 v[58:61], v[170:173], v[194:197], v[58:61]
	v_mfma_f32_16x16x32_bf16 v[46:49], v[170:173], v[206:209], v[46:49]
	v_mfma_f32_16x16x32_bf16 v[46:49], v[174:177], v[210:213], v[46:49]
	v_mfma_f32_16x16x32_bf16 v[54:57], v[166:169], v[210:213], v[54:57]
	v_mfma_f32_16x16x32_bf16 v[54:57], v[158:161], v[206:209], v[54:57]
	v_mfma_f32_16x16x32_bf16 v[38:41], v[158:161], v[214:217], v[38:41]
	v_mfma_f32_16x16x32_bf16 v[38:41], v[166:169], v[218:221], v[38:41]
	v_mfma_f32_16x16x32_bf16 v[30:33], v[174:177], v[218:221], v[30:33]
	v_mfma_f32_16x16x32_bf16 v[30:33], v[170:173], v[214:217], v[30:33]
	v_mfma_f32_16x16x32_bf16 v[14:17], v[170:173], v[222:225], v[14:17]
	v_mfma_f32_16x16x32_bf16 v[14:17], v[174:177], v[226:229], v[14:17]
	v_mfma_f32_16x16x32_bf16 v[22:25], v[166:169], v[226:229], v[22:25]
	v_mfma_f32_16x16x32_bf16 v[22:25], v[158:161], v[222:225], v[22:25]
	s_setprio 0
	s_setprio 1
	v_mfma_f32_16x16x32_bf16 v[50:53], v[178:181], v[194:197], v[50:53]
	v_mfma_f32_16x16x32_bf16 v[50:53], v[182:185], v[202:205], v[50:53]
	v_mfma_f32_16x16x32_bf16 v[42:45], v[190:193], v[202:205], v[42:45]
	v_mfma_f32_16x16x32_bf16 v[42:45], v[186:189], v[194:197], v[42:45]
	v_mfma_f32_16x16x32_bf16 v[26:29], v[186:189], v[206:209], v[26:29]
	v_mfma_f32_16x16x32_bf16 v[26:29], v[190:193], v[210:213], v[26:29]
	v_mfma_f32_16x16x32_bf16 v[34:37], v[182:185], v[210:213], v[34:37]
	v_mfma_f32_16x16x32_bf16 v[34:37], v[178:181], v[206:209], v[34:37]
	v_mfma_f32_16x16x32_bf16 v[18:21], v[178:181], v[214:217], v[18:21]
	v_mfma_f32_16x16x32_bf16 v[18:21], v[182:185], v[218:221], v[18:21]
	v_mfma_f32_16x16x32_bf16 v[10:13], v[190:193], v[218:221], v[10:13]
	v_mfma_f32_16x16x32_bf16 v[10:13], v[186:189], v[214:217], v[10:13]
	v_mfma_f32_16x16x32_bf16 v[2:5], v[186:189], v[222:225], v[2:5]
	v_mfma_f32_16x16x32_bf16 v[2:5], v[190:193], v[226:229], v[2:5]
	v_mfma_f32_16x16x32_bf16 v[6:9], v[182:185], v[226:229], v[6:9]
	v_mfma_f32_16x16x32_bf16 v[6:9], v[178:181], v[222:225], v[6:9]
	s_setprio 0
	s_barrier
	v_add_u32_e32 v157, s94, v145
	ds_read_b128 v[158:161], v157
	ds_read_b128 v[166:169], v157 offset:1024
	ds_read_b128 v[170:173], v157 offset:2048
	ds_read_b128 v[174:177], v157 offset:3072
	v_add_u32_e32 v157, s93, v145
	ds_read_b128 v[178:181], v157
	ds_read_b128 v[182:185], v157 offset:1024
	ds_read_b128 v[186:189], v157 offset:2048
	ds_read_b128 v[190:193], v157 offset:3072
	s_mov_b32 m0, s76
	ds_read_b128 v[194:197], v156 offset:32768
	ds_read_b128 v[202:205], v156 offset:33792
	ds_read_b128 v[206:209], v156 offset:34816
	ds_read_b128 v[210:213], v156 offset:35840
	ds_read_b128 v[214:217], v156 offset:36864
	ds_read_b128 v[218:221], v156 offset:37888
	ds_read_b128 v[222:225], v156 offset:38912
	ds_read_b128 v[226:229], v156 offset:39936
	global_load_lds_dwordx4 v138, s[62:63]
	s_mov_b32 m0, s77
	s_nop 0
	global_load_lds_dwordx4 v134, s[62:63]
	s_waitcnt vmcnt(8)
	s_waitcnt lgkmcnt(0)
	s_barrier
	s_setprio 1
	s_waitcnt lgkmcnt(0)
	v_mfma_f32_16x16x32_bf16 v[126:129], v[158:161], v[194:197], v[126:129]
	v_mfma_f32_16x16x32_bf16 v[126:129], v[166:169], v[202:205], v[126:129]
	v_mfma_f32_16x16x32_bf16 v[122:125], v[174:177], v[202:205], v[122:125]
	v_mfma_f32_16x16x32_bf16 v[122:125], v[170:173], v[194:197], v[122:125]
	v_mfma_f32_16x16x32_bf16 v[110:113], v[170:173], v[206:209], v[110:113]
	v_mfma_f32_16x16x32_bf16 v[110:113], v[174:177], v[210:213], v[110:113]
	v_mfma_f32_16x16x32_bf16 v[118:121], v[166:169], v[210:213], v[118:121]
	v_mfma_f32_16x16x32_bf16 v[118:121], v[158:161], v[206:209], v[118:121]
	v_mfma_f32_16x16x32_bf16 v[102:105], v[158:161], v[214:217], v[102:105]
	v_mfma_f32_16x16x32_bf16 v[102:105], v[166:169], v[218:221], v[102:105]
	v_mfma_f32_16x16x32_bf16 v[94:97], v[174:177], v[218:221], v[94:97]
	v_mfma_f32_16x16x32_bf16 v[94:97], v[170:173], v[214:217], v[94:97]
	v_mfma_f32_16x16x32_bf16 v[78:81], v[170:173], v[222:225], v[78:81]
	v_mfma_f32_16x16x32_bf16 v[78:81], v[174:177], v[226:229], v[78:81]
	v_mfma_f32_16x16x32_bf16 v[86:89], v[166:169], v[226:229], v[86:89]
	v_mfma_f32_16x16x32_bf16 v[86:89], v[158:161], v[222:225], v[86:89]
	s_setprio 0
	s_setprio 1
	v_mfma_f32_16x16x32_bf16 v[114:117], v[178:181], v[194:197], v[114:117]
	v_mfma_f32_16x16x32_bf16 v[114:117], v[182:185], v[202:205], v[114:117]
	v_mfma_f32_16x16x32_bf16 v[106:109], v[190:193], v[202:205], v[106:109]
	v_mfma_f32_16x16x32_bf16 v[106:109], v[186:189], v[194:197], v[106:109]
	v_mfma_f32_16x16x32_bf16 v[90:93], v[186:189], v[206:209], v[90:93]
	v_mfma_f32_16x16x32_bf16 v[90:93], v[190:193], v[210:213], v[90:93]
	v_mfma_f32_16x16x32_bf16 v[98:101], v[182:185], v[210:213], v[98:101]
	v_mfma_f32_16x16x32_bf16 v[98:101], v[178:181], v[206:209], v[98:101]
	v_mfma_f32_16x16x32_bf16 v[82:85], v[178:181], v[214:217], v[82:85]
	v_mfma_f32_16x16x32_bf16 v[82:85], v[182:185], v[218:221], v[82:85]
	v_mfma_f32_16x16x32_bf16 v[74:77], v[190:193], v[218:221], v[74:77]
	v_mfma_f32_16x16x32_bf16 v[74:77], v[186:189], v[214:217], v[74:77]
	v_mfma_f32_16x16x32_bf16 v[66:69], v[186:189], v[222:225], v[66:69]
	v_mfma_f32_16x16x32_bf16 v[66:69], v[190:193], v[226:229], v[66:69]
	v_mfma_f32_16x16x32_bf16 v[70:73], v[182:185], v[226:229], v[70:73]
	v_mfma_f32_16x16x32_bf16 v[70:73], v[178:181], v[222:225], v[70:73]
	s_setprio 0
	s_barrier
	s_mov_b32 m0, s92
	v_lshl_add_u64 v[198:199], v[198:199], 0, s[14:15]
	ds_read_b128 v[194:197], v156 offset:49152
	ds_read_b128 v[202:205], v156 offset:50176
	ds_read_b128 v[206:209], v156 offset:51200
	ds_read_b128 v[210:213], v156 offset:52224
	ds_read_b128 v[214:217], v156 offset:53248
	ds_read_b128 v[218:221], v156 offset:54272
	ds_read_b128 v[222:225], v156 offset:55296
	ds_read_b128 v[226:229], v156 offset:56320
	global_load_lds_dwordx4 v[198:199], off
	v_lshl_add_u64 v[198:199], v[230:231], 0, s[14:15]
	s_mov_b32 m0, s90
	s_nop 0
	global_load_lds_dwordx4 v[198:199], off
	s_mov_b32 m0, s91
	s_nop 0
	global_load_lds_dwordx4 v136, s[60:61]
	s_mov_b32 m0, s44
	s_nop 0
	global_load_lds_dwordx4 v132, s[60:61]
	v_lshl_add_u64 v[198:199], v[232:233], 0, s[14:15]
	s_mov_b32 m0, s80
	s_nop 0
	global_load_lds_dwordx4 v[198:199], off
	v_lshl_add_u64 v[198:199], v[234:235], 0, s[14:15]
	s_mov_b32 m0, s81
	s_nop 0
	global_load_lds_dwordx4 v[198:199], off
	s_waitcnt vmcnt(8)
	s_waitcnt lgkmcnt(0)
	s_barrier
	s_setprio 1
	s_waitcnt lgkmcnt(0)
	v_mfma_f32_16x16x32_bf16 v[62:65], v[158:161], v[194:197], v[62:65]
	v_mfma_f32_16x16x32_bf16 v[62:65], v[166:169], v[202:205], v[62:65]
	v_mfma_f32_16x16x32_bf16 v[58:61], v[174:177], v[202:205], v[58:61]
	v_mfma_f32_16x16x32_bf16 v[58:61], v[170:173], v[194:197], v[58:61]
	v_mfma_f32_16x16x32_bf16 v[46:49], v[170:173], v[206:209], v[46:49]
	v_mfma_f32_16x16x32_bf16 v[46:49], v[174:177], v[210:213], v[46:49]
	v_mfma_f32_16x16x32_bf16 v[54:57], v[166:169], v[210:213], v[54:57]
	v_mfma_f32_16x16x32_bf16 v[54:57], v[158:161], v[206:209], v[54:57]
	v_mfma_f32_16x16x32_bf16 v[38:41], v[158:161], v[214:217], v[38:41]
	v_mfma_f32_16x16x32_bf16 v[38:41], v[166:169], v[218:221], v[38:41]
	v_mfma_f32_16x16x32_bf16 v[30:33], v[174:177], v[218:221], v[30:33]
	v_mfma_f32_16x16x32_bf16 v[30:33], v[170:173], v[214:217], v[30:33]
	v_mfma_f32_16x16x32_bf16 v[14:17], v[170:173], v[222:225], v[14:17]
	v_mfma_f32_16x16x32_bf16 v[14:17], v[174:177], v[226:229], v[14:17]
	v_mfma_f32_16x16x32_bf16 v[22:25], v[166:169], v[226:229], v[22:25]
	v_mfma_f32_16x16x32_bf16 v[22:25], v[158:161], v[222:225], v[22:25]
	s_setprio 0
	s_setprio 1
	v_mfma_f32_16x16x32_bf16 v[50:53], v[178:181], v[194:197], v[50:53]
	v_mfma_f32_16x16x32_bf16 v[50:53], v[182:185], v[202:205], v[50:53]
	v_mfma_f32_16x16x32_bf16 v[42:45], v[190:193], v[202:205], v[42:45]
	v_mfma_f32_16x16x32_bf16 v[42:45], v[186:189], v[194:197], v[42:45]
	v_mfma_f32_16x16x32_bf16 v[26:29], v[186:189], v[206:209], v[26:29]
	v_mfma_f32_16x16x32_bf16 v[26:29], v[190:193], v[210:213], v[26:29]
	v_mfma_f32_16x16x32_bf16 v[34:37], v[182:185], v[210:213], v[34:37]
	v_mfma_f32_16x16x32_bf16 v[34:37], v[178:181], v[206:209], v[34:37]
	v_mfma_f32_16x16x32_bf16 v[18:21], v[178:181], v[214:217], v[18:21]
	v_mfma_f32_16x16x32_bf16 v[18:21], v[182:185], v[218:221], v[18:21]
	v_mfma_f32_16x16x32_bf16 v[10:13], v[190:193], v[218:221], v[10:13]
	v_mfma_f32_16x16x32_bf16 v[10:13], v[186:189], v[214:217], v[10:13]
	v_mfma_f32_16x16x32_bf16 v[2:5], v[186:189], v[222:225], v[2:5]
	v_mfma_f32_16x16x32_bf16 v[2:5], v[190:193], v[226:229], v[2:5]
	v_mfma_f32_16x16x32_bf16 v[6:9], v[182:185], v[226:229], v[6:9]
	v_mfma_f32_16x16x32_bf16 v[6:9], v[178:181], v[222:225], v[6:9]
	s_setprio 0
	s_barrier
	s_movk_i32 s44, 0x100
	s_andn2_b64 vcc, exec, s[58:59]
	s_mov_b64 s[60:61], -1
	s_mov_b64 s[58:59], 0
	s_cbranch_vccz .LBB0_1649
	s_and_b64 vcc, exec, s[16:17]
	s_cbranch_vccz .LBB0_1652
	s_barrier

.LBB0_1667:
	s_add_u32 s36, s56, s44
	s_addc_u32 s37, s57, 0
	s_add_u32 s64, s36, 0x100
	s_addc_u32 s65, s37, 0
	s_and_b64 s[62:63], s[60:61], exec
	s_cselect_b32 s65, s21, s65
	s_cselect_b32 s64, s86, s64
	s_add_u32 s44, s54, s44
	s_addc_u32 s62, s55, 0
	s_add_u32 s44, s44, 0x100
	s_addc_u32 s62, s62, 0
	s_and_b64 s[60:61], s[60:61], exec
	s_cselect_b32 s67, s19, s62
	s_cselect_b32 s66, s87, s44
	s_add_u32 s70, s36, 0x10080
	s_addc_u32 s71, s37, 0
	s_add_i32 s97, s82, s38
	ds_read_b128 v[150:153], v146
	ds_read_b128 v[154:157], v146 offset:1024
	ds_read_b128 v[158:161], v146 offset:2048
	ds_read_b128 v[166:169], v146 offset:3072
	ds_read_b128 v[170:173], v147
	ds_read_b128 v[174:177], v147 offset:1024
	ds_read_b128 v[178:181], v147 offset:2048
	ds_read_b128 v[182:185], v147 offset:3072
	s_add_i32 m0, s53, 0xc000
	s_add_i32 vcc_lo, s53, 0xe000
	s_add_i32 s94, s97, 0x2000
	s_add_u32 s68, s66, 0x10000
	s_addc_u32 s69, s67, 0
	s_add_i32 s96, s83, s38
	s_add_i32 s95, s96, 0x2000
	s_add_i32 s93, 0, 0x18000
	s_add_i32 s92, 0, 0x1c000
	s_add_u32 s62, s64, 0x10000
	s_addc_u32 s63, s65, 0
	s_add_i32 s91, s93, s38
	s_add_i32 s89, s91, 0x2000
	s_add_u32 s60, s66, 0x10080
	s_addc_u32 s61, s67, 0
	s_add_i32 s90, s92, s38
	s_add_i32 s44, s90, 0x2000
	ds_read_b128 v[186:189], v148
	ds_read_b128 v[190:193], v148 offset:1024
	ds_read_b128 v[194:197], v148 offset:2048
	ds_read_b128 v[202:205], v148 offset:3072
	ds_read_b128 v[206:209], v148 offset:4096
	ds_read_b128 v[210:213], v148 offset:5120
	ds_read_b128 v[214:217], v148 offset:6144
	ds_read_b128 v[218:221], v148 offset:7168
	global_load_lds_dwordx4 v138, s[70:71]
	s_mov_b32 m0, vcc_lo
	s_nop 0
	global_load_lds_dwordx4 v134, s[70:71]
	s_waitcnt vmcnt(8)
	s_waitcnt lgkmcnt(0)
	s_barrier
	s_setprio 1
	s_waitcnt lgkmcnt(0)
	v_mfma_f32_16x16x32_bf16 v[126:129], v[150:153], v[186:189], v[126:129]
	v_mfma_f32_16x16x32_bf16 v[126:129], v[154:157], v[190:193], v[126:129]
	v_mfma_f32_16x16x32_bf16 v[122:125], v[166:169], v[190:193], v[122:125]
	v_mfma_f32_16x16x32_bf16 v[122:125], v[158:161], v[186:189], v[122:125]
	v_mfma_f32_16x16x32_bf16 v[110:113], v[158:161], v[194:197], v[110:113]
	v_mfma_f32_16x16x32_bf16 v[110:113], v[166:169], v[202:205], v[110:113]
	v_mfma_f32_16x16x32_bf16 v[118:121], v[154:157], v[202:205], v[118:121]
	v_mfma_f32_16x16x32_bf16 v[118:121], v[150:153], v[194:197], v[118:121]
	v_mfma_f32_16x16x32_bf16 v[102:105], v[150:153], v[206:209], v[102:105]
	v_mfma_f32_16x16x32_bf16 v[102:105], v[154:157], v[210:213], v[102:105]
	v_mfma_f32_16x16x32_bf16 v[94:97], v[166:169], v[210:213], v[94:97]
	v_mfma_f32_16x16x32_bf16 v[94:97], v[158:161], v[206:209], v[94:97]
	v_mfma_f32_16x16x32_bf16 v[78:81], v[158:161], v[214:217], v[78:81]
	v_mfma_f32_16x16x32_bf16 v[78:81], v[166:169], v[218:221], v[78:81]
	v_mfma_f32_16x16x32_bf16 v[86:89], v[154:157], v[218:221], v[86:89]
	v_mfma_f32_16x16x32_bf16 v[86:89], v[150:153], v[214:217], v[86:89]
	s_setprio 0
	s_setprio 1
	v_mfma_f32_16x16x32_bf16 v[114:117], v[170:173], v[186:189], v[114:117]
	v_mfma_f32_16x16x32_bf16 v[114:117], v[174:177], v[190:193], v[114:117]
	v_mfma_f32_16x16x32_bf16 v[106:109], v[182:185], v[190:193], v[106:109]
	v_mfma_f32_16x16x32_bf16 v[106:109], v[178:181], v[186:189], v[106:109]
	v_mfma_f32_16x16x32_bf16 v[90:93], v[178:181], v[194:197], v[90:93]
	v_mfma_f32_16x16x32_bf16 v[90:93], v[182:185], v[202:205], v[90:93]
	v_mfma_f32_16x16x32_bf16 v[98:101], v[174:177], v[202:205], v[98:101]
	v_mfma_f32_16x16x32_bf16 v[98:101], v[170:173], v[194:197], v[98:101]
	v_mfma_f32_16x16x32_bf16 v[82:85], v[170:173], v[206:209], v[82:85]
	v_mfma_f32_16x16x32_bf16 v[82:85], v[174:177], v[210:213], v[82:85]
	v_mfma_f32_16x16x32_bf16 v[74:77], v[182:185], v[210:213], v[74:77]
	v_mfma_f32_16x16x32_bf16 v[74:77], v[178:181], v[206:209], v[74:77]
	v_mfma_f32_16x16x32_bf16 v[66:69], v[178:181], v[214:217], v[66:69]
	v_mfma_f32_16x16x32_bf16 v[66:69], v[182:185], v[218:221], v[66:69]
	v_mfma_f32_16x16x32_bf16 v[70:73], v[174:177], v[218:221], v[70:73]
	v_mfma_f32_16x16x32_bf16 v[70:73], v[170:173], v[214:217], v[70:73]
	s_setprio 0
	s_barrier
	s_mov_b32 m0, s97
	v_lshl_add_u64 v[198:199], s[66:67], 0, v[136:137]
	ds_read_b128 v[186:189], v148 offset:16384
	ds_read_b128 v[190:193], v148 offset:17408
	ds_read_b128 v[194:197], v148 offset:18432
	ds_read_b128 v[202:205], v148 offset:19456
	ds_read_b128 v[206:209], v148 offset:20480
	ds_read_b128 v[210:213], v148 offset:21504
	ds_read_b128 v[214:217], v148 offset:22528
	ds_read_b128 v[218:221], v148 offset:23552
	global_load_lds_dwordx4 v[198:199], off
	v_lshl_add_u64 v[222:223], s[66:67], 0, v[132:133]
	s_mov_b32 m0, s94
	s_nop 0
	global_load_lds_dwordx4 v[222:223], off
	s_mov_b32 m0, s96
	v_lshl_add_u64 v[226:227], s[64:65], 0, v[134:135]
	global_load_lds_dwordx4 v136, s[68:69]
	s_mov_b32 m0, s95
	s_nop 0
	global_load_lds_dwordx4 v132, s[68:69]
	v_lshl_add_u64 v[224:225], s[64:65], 0, v[138:139]
	s_mov_b32 m0, s53
	s_nop 0
	global_load_lds_dwordx4 v[224:225], off
	s_mov_b32 m0, s75
	s_nop 0
	global_load_lds_dwordx4 v[226:227], off
	s_waitcnt vmcnt(8)
	s_waitcnt lgkmcnt(0)
	s_barrier
	s_setprio 1
	s_waitcnt lgkmcnt(0)
	v_mfma_f32_16x16x32_bf16 v[62:65], v[150:153], v[186:189], v[62:65]
	v_mfma_f32_16x16x32_bf16 v[62:65], v[154:157], v[190:193], v[62:65]
	v_mfma_f32_16x16x32_bf16 v[58:61], v[166:169], v[190:193], v[58:61]
	v_mfma_f32_16x16x32_bf16 v[58:61], v[158:161], v[186:189], v[58:61]
	v_mfma_f32_16x16x32_bf16 v[46:49], v[158:161], v[194:197], v[46:49]
	v_mfma_f32_16x16x32_bf16 v[46:49], v[166:169], v[202:205], v[46:49]
	v_mfma_f32_16x16x32_bf16 v[54:57], v[154:157], v[202:205], v[54:57]
	v_mfma_f32_16x16x32_bf16 v[54:57], v[150:153], v[194:197], v[54:57]
	v_mfma_f32_16x16x32_bf16 v[38:41], v[150:153], v[206:209], v[38:41]
	v_mfma_f32_16x16x32_bf16 v[38:41], v[154:157], v[210:213], v[38:41]
	v_mfma_f32_16x16x32_bf16 v[30:33], v[166:169], v[210:213], v[30:33]
	v_mfma_f32_16x16x32_bf16 v[30:33], v[158:161], v[206:209], v[30:33]
	v_mfma_f32_16x16x32_bf16 v[14:17], v[158:161], v[214:217], v[14:17]
	v_mfma_f32_16x16x32_bf16 v[14:17], v[166:169], v[218:221], v[14:17]
	v_mfma_f32_16x16x32_bf16 v[22:25], v[154:157], v[218:221], v[22:25]
	v_mfma_f32_16x16x32_bf16 v[22:25], v[150:153], v[214:217], v[22:25]
	s_setprio 0
	s_setprio 1
	v_mfma_f32_16x16x32_bf16 v[50:53], v[170:173], v[186:189], v[50:53]
	v_mfma_f32_16x16x32_bf16 v[50:53], v[174:177], v[190:193], v[50:53]
	v_mfma_f32_16x16x32_bf16 v[42:45], v[182:185], v[190:193], v[42:45]
	v_mfma_f32_16x16x32_bf16 v[42:45], v[178:181], v[186:189], v[42:45]
	v_mfma_f32_16x16x32_bf16 v[26:29], v[178:181], v[194:197], v[26:29]
	v_mfma_f32_16x16x32_bf16 v[26:29], v[182:185], v[202:205], v[26:29]
	v_mfma_f32_16x16x32_bf16 v[34:37], v[174:177], v[202:205], v[34:37]
	v_mfma_f32_16x16x32_bf16 v[34:37], v[170:173], v[194:197], v[34:37]
	v_mfma_f32_16x16x32_bf16 v[18:21], v[170:173], v[206:209], v[18:21]
	v_mfma_f32_16x16x32_bf16 v[18:21], v[174:177], v[210:213], v[18:21]
	v_mfma_f32_16x16x32_bf16 v[10:13], v[182:185], v[210:213], v[10:13]
	v_mfma_f32_16x16x32_bf16 v[10:13], v[178:181], v[206:209], v[10:13]
	v_mfma_f32_16x16x32_bf16 v[2:5], v[178:181], v[214:217], v[2:5]
	v_mfma_f32_16x16x32_bf16 v[2:5], v[182:185], v[218:221], v[2:5]
	v_mfma_f32_16x16x32_bf16 v[6:9], v[174:177], v[218:221], v[6:9]
	v_mfma_f32_16x16x32_bf16 v[6:9], v[170:173], v[214:217], v[6:9]
	s_setprio 0
	s_barrier
	v_add_u32_e32 v149, s93, v145
	ds_read_b128 v[150:153], v149
	ds_read_b128 v[154:157], v149 offset:1024
	ds_read_b128 v[158:161], v149 offset:2048
	ds_read_b128 v[166:169], v149 offset:3072
	v_add_u32_e32 v149, s92, v145
	ds_read_b128 v[170:173], v149
	ds_read_b128 v[174:177], v149 offset:1024
	ds_read_b128 v[178:181], v149 offset:2048
	ds_read_b128 v[182:185], v149 offset:3072
	s_mov_b32 m0, s76
	ds_read_b128 v[186:189], v148 offset:32768
	ds_read_b128 v[190:193], v148 offset:33792
	ds_read_b128 v[194:197], v148 offset:34816
	ds_read_b128 v[202:205], v148 offset:35840
	ds_read_b128 v[206:209], v148 offset:36864
	ds_read_b128 v[210:213], v148 offset:37888
	ds_read_b128 v[214:217], v148 offset:38912
	ds_read_b128 v[218:221], v148 offset:39936
	global_load_lds_dwordx4 v138, s[62:63]
	s_mov_b32 m0, s77
	s_nop 0
	global_load_lds_dwordx4 v134, s[62:63]
	s_waitcnt vmcnt(8)
	s_waitcnt lgkmcnt(0)
	s_barrier
	s_setprio 1
	s_waitcnt lgkmcnt(0)
	v_mfma_f32_16x16x32_bf16 v[126:129], v[150:153], v[186:189], v[126:129]
	v_mfma_f32_16x16x32_bf16 v[126:129], v[154:157], v[190:193], v[126:129]
	v_mfma_f32_16x16x32_bf16 v[122:125], v[166:169], v[190:193], v[122:125]
	v_mfma_f32_16x16x32_bf16 v[122:125], v[158:161], v[186:189], v[122:125]
	v_mfma_f32_16x16x32_bf16 v[110:113], v[158:161], v[194:197], v[110:113]
	v_mfma_f32_16x16x32_bf16 v[110:113], v[166:169], v[202:205], v[110:113]
	v_mfma_f32_16x16x32_bf16 v[118:121], v[154:157], v[202:205], v[118:121]
	v_mfma_f32_16x16x32_bf16 v[118:121], v[150:153], v[194:197], v[118:121]
	v_mfma_f32_16x16x32_bf16 v[102:105], v[150:153], v[206:209], v[102:105]
	v_mfma_f32_16x16x32_bf16 v[102:105], v[154:157], v[210:213], v[102:105]
	v_mfma_f32_16x16x32_bf16 v[94:97], v[166:169], v[210:213], v[94:97]
	v_mfma_f32_16x16x32_bf16 v[94:97], v[158:161], v[206:209], v[94:97]
	v_mfma_f32_16x16x32_bf16 v[78:81], v[158:161], v[214:217], v[78:81]
	v_mfma_f32_16x16x32_bf16 v[78:81], v[166:169], v[218:221], v[78:81]
	v_mfma_f32_16x16x32_bf16 v[86:89], v[154:157], v[218:221], v[86:89]
	v_mfma_f32_16x16x32_bf16 v[86:89], v[150:153], v[214:217], v[86:89]
	s_setprio 0
	s_setprio 1
	v_mfma_f32_16x16x32_bf16 v[114:117], v[170:173], v[186:189], v[114:117]
	v_mfma_f32_16x16x32_bf16 v[114:117], v[174:177], v[190:193], v[114:117]
	v_mfma_f32_16x16x32_bf16 v[106:109], v[182:185], v[190:193], v[106:109]
	v_mfma_f32_16x16x32_bf16 v[106:109], v[178:181], v[186:189], v[106:109]
	v_mfma_f32_16x16x32_bf16 v[90:93], v[178:181], v[194:197], v[90:93]
	v_mfma_f32_16x16x32_bf16 v[90:93], v[182:185], v[202:205], v[90:93]
	v_mfma_f32_16x16x32_bf16 v[98:101], v[174:177], v[202:205], v[98:101]
	v_mfma_f32_16x16x32_bf16 v[98:101], v[170:173], v[194:197], v[98:101]
	v_mfma_f32_16x16x32_bf16 v[82:85], v[170:173], v[206:209], v[82:85]
	v_mfma_f32_16x16x32_bf16 v[82:85], v[174:177], v[210:213], v[82:85]
	v_mfma_f32_16x16x32_bf16 v[74:77], v[182:185], v[210:213], v[74:77]
	v_mfma_f32_16x16x32_bf16 v[74:77], v[178:181], v[206:209], v[74:77]
	v_mfma_f32_16x16x32_bf16 v[66:69], v[178:181], v[214:217], v[66:69]
	v_mfma_f32_16x16x32_bf16 v[66:69], v[182:185], v[218:221], v[66:69]
	v_mfma_f32_16x16x32_bf16 v[70:73], v[174:177], v[218:221], v[70:73]
	v_mfma_f32_16x16x32_bf16 v[70:73], v[170:173], v[214:217], v[70:73]
	s_setprio 0
	s_barrier
	s_mov_b32 m0, s91
	v_lshl_add_u64 v[198:199], v[198:199], 0, s[14:15]
	ds_read_b128 v[186:189], v148 offset:49152
	ds_read_b128 v[190:193], v148 offset:50176
	ds_read_b128 v[194:197], v148 offset:51200
	ds_read_b128 v[202:205], v148 offset:52224
	ds_read_b128 v[206:209], v148 offset:53248
	ds_read_b128 v[210:213], v148 offset:54272
	ds_read_b128 v[214:217], v148 offset:55296
	ds_read_b128 v[218:221], v148 offset:56320
	global_load_lds_dwordx4 v[198:199], off
	v_lshl_add_u64 v[198:199], v[222:223], 0, s[14:15]
	s_mov_b32 m0, s89
	s_nop 0
	global_load_lds_dwordx4 v[198:199], off
	s_mov_b32 m0, s90
	s_nop 0
	global_load_lds_dwordx4 v136, s[60:61]
	s_mov_b32 m0, s44
	s_nop 0
	global_load_lds_dwordx4 v132, s[60:61]
	v_lshl_add_u64 v[198:199], v[224:225], 0, s[14:15]
	s_mov_b32 m0, s79
	s_nop 0
	global_load_lds_dwordx4 v[198:199], off
	v_lshl_add_u64 v[198:199], v[226:227], 0, s[14:15]
	s_mov_b32 m0, s80
	s_nop 0
	global_load_lds_dwordx4 v[198:199], off
	s_waitcnt vmcnt(8)
	s_waitcnt lgkmcnt(0)
	s_barrier
	s_setprio 1
	s_waitcnt lgkmcnt(0)
	v_mfma_f32_16x16x32_bf16 v[62:65], v[150:153], v[186:189], v[62:65]
	v_mfma_f32_16x16x32_bf16 v[62:65], v[154:157], v[190:193], v[62:65]
	v_mfma_f32_16x16x32_bf16 v[58:61], v[166:169], v[190:193], v[58:61]
	v_mfma_f32_16x16x32_bf16 v[58:61], v[158:161], v[186:189], v[58:61]
	v_mfma_f32_16x16x32_bf16 v[46:49], v[158:161], v[194:197], v[46:49]
	v_mfma_f32_16x16x32_bf16 v[46:49], v[166:169], v[202:205], v[46:49]
	v_mfma_f32_16x16x32_bf16 v[54:57], v[154:157], v[202:205], v[54:57]
	v_mfma_f32_16x16x32_bf16 v[54:57], v[150:153], v[194:197], v[54:57]
	v_mfma_f32_16x16x32_bf16 v[38:41], v[150:153], v[206:209], v[38:41]
	v_mfma_f32_16x16x32_bf16 v[38:41], v[154:157], v[210:213], v[38:41]
	v_mfma_f32_16x16x32_bf16 v[30:33], v[166:169], v[210:213], v[30:33]
	v_mfma_f32_16x16x32_bf16 v[30:33], v[158:161], v[206:209], v[30:33]
	v_mfma_f32_16x16x32_bf16 v[14:17], v[158:161], v[214:217], v[14:17]
	v_mfma_f32_16x16x32_bf16 v[14:17], v[166:169], v[218:221], v[14:17]
	v_mfma_f32_16x16x32_bf16 v[22:25], v[154:157], v[218:221], v[22:25]
	v_mfma_f32_16x16x32_bf16 v[22:25], v[150:153], v[214:217], v[22:25]
	s_setprio 0
	s_setprio 1
	v_mfma_f32_16x16x32_bf16 v[50:53], v[170:173], v[186:189], v[50:53]
	v_mfma_f32_16x16x32_bf16 v[50:53], v[174:177], v[190:193], v[50:53]
	v_mfma_f32_16x16x32_bf16 v[42:45], v[182:185], v[190:193], v[42:45]
	v_mfma_f32_16x16x32_bf16 v[42:45], v[178:181], v[186:189], v[42:45]
	v_mfma_f32_16x16x32_bf16 v[26:29], v[178:181], v[194:197], v[26:29]
	v_mfma_f32_16x16x32_bf16 v[26:29], v[182:185], v[202:205], v[26:29]
	v_mfma_f32_16x16x32_bf16 v[34:37], v[174:177], v[202:205], v[34:37]
	v_mfma_f32_16x16x32_bf16 v[34:37], v[170:173], v[194:197], v[34:37]
	v_mfma_f32_16x16x32_bf16 v[18:21], v[170:173], v[206:209], v[18:21]
	v_mfma_f32_16x16x32_bf16 v[18:21], v[174:177], v[210:213], v[18:21]
	v_mfma_f32_16x16x32_bf16 v[10:13], v[182:185], v[210:213], v[10:13]
	v_mfma_f32_16x16x32_bf16 v[10:13], v[178:181], v[206:209], v[10:13]
	v_mfma_f32_16x16x32_bf16 v[2:5], v[178:181], v[214:217], v[2:5]
	v_mfma_f32_16x16x32_bf16 v[2:5], v[182:185], v[218:221], v[2:5]
	v_mfma_f32_16x16x32_bf16 v[6:9], v[174:177], v[218:221], v[6:9]
	v_mfma_f32_16x16x32_bf16 v[6:9], v[170:173], v[214:217], v[6:9]
	s_setprio 0
	s_barrier
	s_movk_i32 s44, 0x100
	s_andn2_b64 vcc, exec, s[58:59]
	s_mov_b64 s[60:61], -1
	s_mov_b64 s[58:59], 0
	s_cbranch_vccz .LBB0_1667
	s_and_b64 vcc, exec, s[16:17]
	s_cbranch_vccz .LBB0_1670
	s_barrier

.LBB0_1685:
	ds_read_b128 v[156:159], v153
	ds_read_b128 v[166:169], v153 offset:1024
	ds_read_b128 v[170:173], v153 offset:2048
	ds_read_b128 v[174:177], v153 offset:3072
	ds_read_b128 v[178:181], v154
	ds_read_b128 v[182:185], v154 offset:1024
	ds_read_b128 v[186:189], v154 offset:2048
	ds_read_b128 v[190:193], v154 offset:3072
	s_add_u32 s36, s56, 0xfff00080
	s_addc_u32 s37, s57, -1
	s_cmp_eq_u32 s78, 60
	s_cselect_b32 s61, s25, s37
	s_cselect_b32 s60, s74, s36
	s_cselect_b32 s59, s21, s77
	s_cselect_b32 s58, s75, s76
	s_add_i32 m0, s55, 0xc000
	ds_read_b128 v[194:197], v155
	ds_read_b128 v[202:205], v155 offset:1024
	ds_read_b128 v[206:209], v155 offset:2048
	ds_read_b128 v[210:213], v155 offset:3072
	ds_read_b128 v[214:217], v155 offset:4096
	ds_read_b128 v[218:221], v155 offset:5120
	ds_read_b128 v[222:225], v155 offset:6144
	ds_read_b128 v[226:229], v155 offset:7168
	global_load_lds_dwordx4 v140, s[56:57]
	s_add_i32 m0, s55, 0xe000
	s_nop 0
	global_load_lds_dwordx4 v142, s[56:57]
	s_waitcnt vmcnt(8)
	s_waitcnt lgkmcnt(0)
	s_barrier
	s_setprio 1
	s_waitcnt lgkmcnt(0)
	v_mfma_f32_16x16x32_bf16 v[126:129], v[156:159], v[194:197], v[126:129]
	v_mfma_f32_16x16x32_bf16 v[126:129], v[166:169], v[202:205], v[126:129]
	v_mfma_f32_16x16x32_bf16 v[122:125], v[174:177], v[202:205], v[122:125]
	v_mfma_f32_16x16x32_bf16 v[122:125], v[170:173], v[194:197], v[122:125]
	v_mfma_f32_16x16x32_bf16 v[110:113], v[170:173], v[206:209], v[110:113]
	v_mfma_f32_16x16x32_bf16 v[110:113], v[174:177], v[210:213], v[110:113]
	v_mfma_f32_16x16x32_bf16 v[118:121], v[166:169], v[210:213], v[118:121]
	v_mfma_f32_16x16x32_bf16 v[118:121], v[156:159], v[206:209], v[118:121]
	v_mfma_f32_16x16x32_bf16 v[102:105], v[156:159], v[214:217], v[102:105]
	v_mfma_f32_16x16x32_bf16 v[102:105], v[166:169], v[218:221], v[102:105]
	v_mfma_f32_16x16x32_bf16 v[94:97], v[174:177], v[218:221], v[94:97]
	v_mfma_f32_16x16x32_bf16 v[94:97], v[170:173], v[214:217], v[94:97]
	v_mfma_f32_16x16x32_bf16 v[78:81], v[170:173], v[222:225], v[78:81]
	v_mfma_f32_16x16x32_bf16 v[78:81], v[174:177], v[226:229], v[78:81]
	v_mfma_f32_16x16x32_bf16 v[86:89], v[166:169], v[226:229], v[86:89]
	v_mfma_f32_16x16x32_bf16 v[86:89], v[156:159], v[222:225], v[86:89]
	s_setprio 0
	s_setprio 1
	v_mfma_f32_16x16x32_bf16 v[114:117], v[178:181], v[194:197], v[114:117]
	v_mfma_f32_16x16x32_bf16 v[114:117], v[182:185], v[202:205], v[114:117]
	v_mfma_f32_16x16x32_bf16 v[106:109], v[190:193], v[202:205], v[106:109]
	v_mfma_f32_16x16x32_bf16 v[106:109], v[186:189], v[194:197], v[106:109]
	v_mfma_f32_16x16x32_bf16 v[90:93], v[186:189], v[206:209], v[90:93]
	v_mfma_f32_16x16x32_bf16 v[90:93], v[190:193], v[210:213], v[90:93]
	v_mfma_f32_16x16x32_bf16 v[98:101], v[182:185], v[210:213], v[98:101]
	v_mfma_f32_16x16x32_bf16 v[98:101], v[178:181], v[206:209], v[98:101]
	v_mfma_f32_16x16x32_bf16 v[82:85], v[178:181], v[214:217], v[82:85]
	v_mfma_f32_16x16x32_bf16 v[82:85], v[182:185], v[218:221], v[82:85]
	v_mfma_f32_16x16x32_bf16 v[74:77], v[190:193], v[218:221], v[74:77]
	v_mfma_f32_16x16x32_bf16 v[74:77], v[186:189], v[214:217], v[74:77]
	v_mfma_f32_16x16x32_bf16 v[66:69], v[186:189], v[222:225], v[66:69]
	v_mfma_f32_16x16x32_bf16 v[66:69], v[190:193], v[226:229], v[66:69]
	v_mfma_f32_16x16x32_bf16 v[70:73], v[182:185], v[226:229], v[70:73]
	v_mfma_f32_16x16x32_bf16 v[70:73], v[178:181], v[222:225], v[70:73]
	s_setprio 0
	s_barrier
	s_add_i32 s36, s68, s38
	v_lshl_add_u64 v[160:161], s[58:59], 0, v[136:137]
	s_mov_b32 m0, s36
	ds_read_b128 v[194:197], v155 offset:16384
	ds_read_b128 v[202:205], v155 offset:17408
	ds_read_b128 v[206:209], v155 offset:18432
	ds_read_b128 v[210:213], v155 offset:19456
	ds_read_b128 v[214:217], v155 offset:20480
	ds_read_b128 v[218:221], v155 offset:21504
	ds_read_b128 v[222:225], v155 offset:22528
	ds_read_b128 v[226:229], v155 offset:23552
	global_load_lds_dwordx4 v[160:161], off
	s_add_i32 m0, s36, 0x2000
	s_add_u32 s80, s58, 0x100000
	v_lshl_add_u64 v[198:199], s[58:59], 0, v[132:133]
	s_addc_u32 s81, s59, 0
	s_add_i32 s36, s69, s38
	global_load_lds_dwordx4 v[198:199], off
	s_mov_b32 m0, s36
	v_lshl_add_u64 v[232:233], s[60:61], 0, v[134:135]
	global_load_lds_dwordx4 v136, s[80:81]
	s_add_i32 m0, s36, 0x2000
	s_nop 0
	global_load_lds_dwordx4 v132, s[80:81]
	v_lshl_add_u64 v[230:231], s[60:61], 0, v[138:139]
	s_mov_b32 m0, s55
	s_nop 0
	global_load_lds_dwordx4 v[230:231], off
	s_mov_b32 m0, s63
	s_nop 0
	global_load_lds_dwordx4 v[232:233], off
	s_waitcnt vmcnt(8)
	s_waitcnt lgkmcnt(0)
	s_barrier
	s_setprio 1
	s_waitcnt lgkmcnt(0)
	v_mfma_f32_16x16x32_bf16 v[62:65], v[156:159], v[194:197], v[62:65]
	v_mfma_f32_16x16x32_bf16 v[62:65], v[166:169], v[202:205], v[62:65]
	v_mfma_f32_16x16x32_bf16 v[58:61], v[174:177], v[202:205], v[58:61]
	v_mfma_f32_16x16x32_bf16 v[58:61], v[170:173], v[194:197], v[58:61]
	v_mfma_f32_16x16x32_bf16 v[46:49], v[170:173], v[206:209], v[46:49]
	v_mfma_f32_16x16x32_bf16 v[46:49], v[174:177], v[210:213], v[46:49]
	v_mfma_f32_16x16x32_bf16 v[54:57], v[166:169], v[210:213], v[54:57]
	v_mfma_f32_16x16x32_bf16 v[54:57], v[156:159], v[206:209], v[54:57]
	v_mfma_f32_16x16x32_bf16 v[38:41], v[156:159], v[214:217], v[38:41]
	v_mfma_f32_16x16x32_bf16 v[38:41], v[166:169], v[218:221], v[38:41]
	v_mfma_f32_16x16x32_bf16 v[30:33], v[174:177], v[218:221], v[30:33]
	v_mfma_f32_16x16x32_bf16 v[30:33], v[170:173], v[214:217], v[30:33]
	v_mfma_f32_16x16x32_bf16 v[14:17], v[170:173], v[222:225], v[14:17]
	v_mfma_f32_16x16x32_bf16 v[14:17], v[174:177], v[226:229], v[14:17]
	v_mfma_f32_16x16x32_bf16 v[22:25], v[166:169], v[226:229], v[22:25]
	v_mfma_f32_16x16x32_bf16 v[22:25], v[156:159], v[222:225], v[22:25]
	s_setprio 0
	s_setprio 1
	v_mfma_f32_16x16x32_bf16 v[50:53], v[178:181], v[194:197], v[50:53]
	v_mfma_f32_16x16x32_bf16 v[50:53], v[182:185], v[202:205], v[50:53]
	v_mfma_f32_16x16x32_bf16 v[42:45], v[190:193], v[202:205], v[42:45]
	v_mfma_f32_16x16x32_bf16 v[42:45], v[186:189], v[194:197], v[42:45]
	v_mfma_f32_16x16x32_bf16 v[26:29], v[186:189], v[206:209], v[26:29]
	v_mfma_f32_16x16x32_bf16 v[26:29], v[190:193], v[210:213], v[26:29]
	v_mfma_f32_16x16x32_bf16 v[34:37], v[182:185], v[210:213], v[34:37]
	v_mfma_f32_16x16x32_bf16 v[34:37], v[178:181], v[206:209], v[34:37]
	v_mfma_f32_16x16x32_bf16 v[18:21], v[178:181], v[214:217], v[18:21]
	v_mfma_f32_16x16x32_bf16 v[18:21], v[182:185], v[218:221], v[18:21]
	v_mfma_f32_16x16x32_bf16 v[10:13], v[190:193], v[218:221], v[10:13]
	v_mfma_f32_16x16x32_bf16 v[10:13], v[186:189], v[214:217], v[10:13]
	v_mfma_f32_16x16x32_bf16 v[2:5], v[186:189], v[222:225], v[2:5]
	v_mfma_f32_16x16x32_bf16 v[2:5], v[190:193], v[226:229], v[2:5]
	v_mfma_f32_16x16x32_bf16 v[6:9], v[182:185], v[226:229], v[6:9]
	v_mfma_f32_16x16x32_bf16 v[6:9], v[178:181], v[222:225], v[6:9]
	s_setprio 0
	s_barrier
	s_add_i32 s36, 0, 0x18000
	v_add_u32_e32 v165, s36, v151
	s_add_i32 s37, 0, 0x1c000
	ds_read_b128 v[156:159], v165
	ds_read_b128 v[166:169], v165 offset:1024
	ds_read_b128 v[170:173], v165 offset:2048
	ds_read_b128 v[174:177], v165 offset:3072
	v_add_u32_e32 v165, s37, v151
	ds_read_b128 v[178:181], v165
	ds_read_b128 v[182:185], v165 offset:1024
	ds_read_b128 v[186:189], v165 offset:2048
	ds_read_b128 v[190:193], v165 offset:3072
	s_add_u32 s60, s60, 0x100000
	s_addc_u32 s61, s61, 0
	s_mov_b32 m0, s64
	ds_read_b128 v[194:197], v155 offset:32768
	ds_read_b128 v[202:205], v155 offset:33792
	ds_read_b128 v[206:209], v155 offset:34816
	ds_read_b128 v[210:213], v155 offset:35840
	ds_read_b128 v[214:217], v155 offset:36864
	ds_read_b128 v[218:221], v155 offset:37888
	ds_read_b128 v[222:225], v155 offset:38912
	ds_read_b128 v[226:229], v155 offset:39936
	global_load_lds_dwordx4 v138, s[60:61]
	s_mov_b32 m0, s65
	s_nop 0
	global_load_lds_dwordx4 v134, s[60:61]
	s_waitcnt vmcnt(8)
	s_waitcnt lgkmcnt(0)
	s_barrier
	s_setprio 1
	s_waitcnt lgkmcnt(0)
	v_mfma_f32_16x16x32_bf16 v[126:129], v[156:159], v[194:197], v[126:129]
	v_mfma_f32_16x16x32_bf16 v[126:129], v[166:169], v[202:205], v[126:129]
	v_mfma_f32_16x16x32_bf16 v[122:125], v[174:177], v[202:205], v[122:125]
	v_mfma_f32_16x16x32_bf16 v[122:125], v[170:173], v[194:197], v[122:125]
	v_mfma_f32_16x16x32_bf16 v[110:113], v[170:173], v[206:209], v[110:113]
	v_mfma_f32_16x16x32_bf16 v[110:113], v[174:177], v[210:213], v[110:113]
	v_mfma_f32_16x16x32_bf16 v[118:121], v[166:169], v[210:213], v[118:121]
	v_mfma_f32_16x16x32_bf16 v[118:121], v[156:159], v[206:209], v[118:121]
	v_mfma_f32_16x16x32_bf16 v[102:105], v[156:159], v[214:217], v[102:105]
	v_mfma_f32_16x16x32_bf16 v[102:105], v[166:169], v[218:221], v[102:105]
	v_mfma_f32_16x16x32_bf16 v[94:97], v[174:177], v[218:221], v[94:97]
	v_mfma_f32_16x16x32_bf16 v[94:97], v[170:173], v[214:217], v[94:97]
	v_mfma_f32_16x16x32_bf16 v[78:81], v[170:173], v[222:225], v[78:81]
	v_mfma_f32_16x16x32_bf16 v[78:81], v[174:177], v[226:229], v[78:81]
	v_mfma_f32_16x16x32_bf16 v[86:89], v[166:169], v[226:229], v[86:89]
	v_mfma_f32_16x16x32_bf16 v[86:89], v[156:159], v[222:225], v[86:89]
	s_setprio 0
	s_setprio 1
	v_mfma_f32_16x16x32_bf16 v[114:117], v[178:181], v[194:197], v[114:117]
	v_mfma_f32_16x16x32_bf16 v[114:117], v[182:185], v[202:205], v[114:117]
	v_mfma_f32_16x16x32_bf16 v[106:109], v[190:193], v[202:205], v[106:109]
	v_mfma_f32_16x16x32_bf16 v[106:109], v[186:189], v[194:197], v[106:109]
	v_mfma_f32_16x16x32_bf16 v[90:93], v[186:189], v[206:209], v[90:93]
	v_mfma_f32_16x16x32_bf16 v[90:93], v[190:193], v[210:213], v[90:93]
	v_mfma_f32_16x16x32_bf16 v[98:101], v[182:185], v[210:213], v[98:101]
	v_mfma_f32_16x16x32_bf16 v[98:101], v[178:181], v[206:209], v[98:101]
	v_mfma_f32_16x16x32_bf16 v[82:85], v[178:181], v[214:217], v[82:85]
	v_mfma_f32_16x16x32_bf16 v[82:85], v[182:185], v[218:221], v[82:85]
	v_mfma_f32_16x16x32_bf16 v[74:77], v[190:193], v[218:221], v[74:77]
	v_mfma_f32_16x16x32_bf16 v[74:77], v[186:189], v[214:217], v[74:77]
	v_mfma_f32_16x16x32_bf16 v[66:69], v[186:189], v[222:225], v[66:69]
	v_mfma_f32_16x16x32_bf16 v[66:69], v[190:193], v[226:229], v[66:69]
	v_mfma_f32_16x16x32_bf16 v[70:73], v[182:185], v[226:229], v[70:73]
	v_mfma_f32_16x16x32_bf16 v[70:73], v[178:181], v[222:225], v[70:73]
	s_setprio 0
	s_barrier
	s_add_i32 s36, s36, s38
	v_lshl_add_u64 v[160:161], v[160:161], 0, s[16:17]
	s_mov_b32 m0, s36
	ds_read_b128 v[194:197], v155 offset:49152
	ds_read_b128 v[202:205], v155 offset:50176
	ds_read_b128 v[206:209], v155 offset:51200
	ds_read_b128 v[210:213], v155 offset:52224
	ds_read_b128 v[214:217], v155 offset:53248
	ds_read_b128 v[218:221], v155 offset:54272
	ds_read_b128 v[222:225], v155 offset:55296
	ds_read_b128 v[226:229], v155 offset:56320
	global_load_lds_dwordx4 v[160:161], off
	s_add_i32 m0, s36, 0x2000
	s_add_u32 s58, s58, 0x100080
	v_lshl_add_u64 v[160:161], v[198:199], 0, s[16:17]
	s_addc_u32 s59, s59, 0
	s_add_i32 s36, s37, s38
	global_load_lds_dwordx4 v[160:161], off
	s_mov_b32 m0, s36
	s_nop 0
	global_load_lds_dwordx4 v136, s[58:59]
	s_add_i32 m0, s36, 0x2000
	s_nop 0
	global_load_lds_dwordx4 v132, s[58:59]
	v_lshl_add_u64 v[160:161], v[230:231], 0, s[16:17]
	s_mov_b32 m0, s66
	s_nop 0
	global_load_lds_dwordx4 v[160:161], off
	v_lshl_add_u64 v[160:161], v[232:233], 0, s[16:17]
	s_mov_b32 m0, s67
	s_nop 0
	global_load_lds_dwordx4 v[160:161], off
	s_waitcnt vmcnt(8)
	s_waitcnt lgkmcnt(0)
	s_barrier
	s_setprio 1
	s_waitcnt lgkmcnt(0)
	v_mfma_f32_16x16x32_bf16 v[62:65], v[156:159], v[194:197], v[62:65]
	v_mfma_f32_16x16x32_bf16 v[62:65], v[166:169], v[202:205], v[62:65]
	v_mfma_f32_16x16x32_bf16 v[58:61], v[174:177], v[202:205], v[58:61]
	v_mfma_f32_16x16x32_bf16 v[58:61], v[170:173], v[194:197], v[58:61]
	v_mfma_f32_16x16x32_bf16 v[46:49], v[170:173], v[206:209], v[46:49]
	v_mfma_f32_16x16x32_bf16 v[46:49], v[174:177], v[210:213], v[46:49]
	v_mfma_f32_16x16x32_bf16 v[54:57], v[166:169], v[210:213], v[54:57]
	v_mfma_f32_16x16x32_bf16 v[54:57], v[156:159], v[206:209], v[54:57]
	v_mfma_f32_16x16x32_bf16 v[38:41], v[156:159], v[214:217], v[38:41]
	v_mfma_f32_16x16x32_bf16 v[38:41], v[166:169], v[218:221], v[38:41]
	v_mfma_f32_16x16x32_bf16 v[30:33], v[174:177], v[218:221], v[30:33]
	v_mfma_f32_16x16x32_bf16 v[30:33], v[170:173], v[214:217], v[30:33]
	v_mfma_f32_16x16x32_bf16 v[14:17], v[170:173], v[222:225], v[14:17]
	v_mfma_f32_16x16x32_bf16 v[14:17], v[174:177], v[226:229], v[14:17]
	v_mfma_f32_16x16x32_bf16 v[22:25], v[166:169], v[226:229], v[22:25]
	v_mfma_f32_16x16x32_bf16 v[22:25], v[156:159], v[222:225], v[22:25]
	s_setprio 0
	s_setprio 1
	v_mfma_f32_16x16x32_bf16 v[50:53], v[178:181], v[194:197], v[50:53]
	v_mfma_f32_16x16x32_bf16 v[50:53], v[182:185], v[202:205], v[50:53]
	v_mfma_f32_16x16x32_bf16 v[42:45], v[190:193], v[202:205], v[42:45]
	v_mfma_f32_16x16x32_bf16 v[42:45], v[186:189], v[194:197], v[42:45]
	v_mfma_f32_16x16x32_bf16 v[26:29], v[186:189], v[206:209], v[26:29]
	v_mfma_f32_16x16x32_bf16 v[26:29], v[190:193], v[210:213], v[26:29]
	v_mfma_f32_16x16x32_bf16 v[34:37], v[182:185], v[210:213], v[34:37]
	v_mfma_f32_16x16x32_bf16 v[34:37], v[178:181], v[206:209], v[34:37]
	v_mfma_f32_16x16x32_bf16 v[18:21], v[178:181], v[214:217], v[18:21]
	v_mfma_f32_16x16x32_bf16 v[18:21], v[182:185], v[218:221], v[18:21]
	v_mfma_f32_16x16x32_bf16 v[10:13], v[190:193], v[218:221], v[10:13]
	v_mfma_f32_16x16x32_bf16 v[10:13], v[186:189], v[214:217], v[10:13]
	v_mfma_f32_16x16x32_bf16 v[2:5], v[186:189], v[222:225], v[2:5]
	v_mfma_f32_16x16x32_bf16 v[2:5], v[190:193], v[226:229], v[2:5]
	v_mfma_f32_16x16x32_bf16 v[6:9], v[182:185], v[226:229], v[6:9]
	v_mfma_f32_16x16x32_bf16 v[6:9], v[178:181], v[222:225], v[6:9]
	s_setprio 0
	s_barrier
	s_add_i32 s78, s78, 2
	s_add_u32 s56, s56, 0x100
	s_addc_u32 s57, s57, 0
	s_add_u32 s76, s76, 0x100
	s_addc_u32 s77, s77, 0
	s_cmp_gt_u32 s78, 61
	s_cbranch_scc0 .LBB0_1685
	s_and_b64 vcc, exec, s[18:19]
	s_cbranch_vccz .LBB0_1688
	s_barrier

.LBB0_1701:
	s_add_u32 s36, s56, s44
	s_addc_u32 s37, s57, 0
	s_add_u32 s64, s36, 0x100
	s_addc_u32 s65, s37, 0
	s_and_b64 s[62:63], s[60:61], exec
	s_cselect_b32 s65, s21, s65
	s_cselect_b32 s64, s86, s64
	s_add_u32 s44, s54, s44
	s_addc_u32 s62, s55, 0
	s_add_u32 s44, s44, 0x100
	s_addc_u32 s62, s62, 0
	s_and_b64 s[60:61], s[60:61], exec
	s_cselect_b32 s67, s25, s62
	s_cselect_b32 s66, s87, s44
	s_add_u32 s70, s36, 0x10080
	s_addc_u32 s71, s37, 0
	s_add_i32 s97, s81, s39
	ds_read_b128 v[152:155], v147
	ds_read_b128 v[156:159], v147 offset:1024
	ds_read_b128 v[166:169], v147 offset:2048
	ds_read_b128 v[170:173], v147 offset:3072
	ds_read_b128 v[174:177], v150
	ds_read_b128 v[178:181], v150 offset:1024
	ds_read_b128 v[182:185], v150 offset:2048
	ds_read_b128 v[186:189], v150 offset:3072
	s_add_i32 m0, s74, 0xc000
	s_add_i32 vcc_lo, s74, 0xe000
	s_add_i32 s94, s97, 0x2000
	s_add_u32 s68, s66, 0x10000
	s_addc_u32 s69, s67, 0
	s_add_i32 s96, s82, s39
	s_add_i32 s95, s96, 0x2000
	s_add_i32 s93, 0, 0x18000
	s_add_i32 s92, 0, 0x1c000
	s_add_u32 s62, s64, 0x10000
	s_addc_u32 s63, s65, 0
	s_add_i32 s91, s93, s39
	s_add_i32 s89, s91, 0x2000
	s_add_u32 s60, s66, 0x10080
	s_addc_u32 s61, s67, 0
	s_add_i32 s90, s92, s39
	s_add_i32 s44, s90, 0x2000
	ds_read_b128 v[190:193], v151
	ds_read_b128 v[194:197], v151 offset:1024
	ds_read_b128 v[202:205], v151 offset:2048
	ds_read_b128 v[206:209], v151 offset:3072
	ds_read_b128 v[210:213], v151 offset:4096
	ds_read_b128 v[214:217], v151 offset:5120
	ds_read_b128 v[218:221], v151 offset:6144
	ds_read_b128 v[222:225], v151 offset:7168
	global_load_lds_dwordx4 v138, s[70:71]
	s_mov_b32 m0, vcc_lo
	s_nop 0
	global_load_lds_dwordx4 v134, s[70:71]
	s_waitcnt vmcnt(8)
	s_waitcnt lgkmcnt(0)
	s_barrier
	s_setprio 1
	s_waitcnt lgkmcnt(0)
	v_mfma_f32_16x16x32_bf16 v[126:129], v[152:155], v[190:193], v[126:129]
	v_mfma_f32_16x16x32_bf16 v[126:129], v[156:159], v[194:197], v[126:129]
	v_mfma_f32_16x16x32_bf16 v[122:125], v[170:173], v[194:197], v[122:125]
	v_mfma_f32_16x16x32_bf16 v[122:125], v[166:169], v[190:193], v[122:125]
	v_mfma_f32_16x16x32_bf16 v[110:113], v[166:169], v[202:205], v[110:113]
	v_mfma_f32_16x16x32_bf16 v[110:113], v[170:173], v[206:209], v[110:113]
	v_mfma_f32_16x16x32_bf16 v[118:121], v[156:159], v[206:209], v[118:121]
	v_mfma_f32_16x16x32_bf16 v[118:121], v[152:155], v[202:205], v[118:121]
	v_mfma_f32_16x16x32_bf16 v[102:105], v[152:155], v[210:213], v[102:105]
	v_mfma_f32_16x16x32_bf16 v[102:105], v[156:159], v[214:217], v[102:105]
	v_mfma_f32_16x16x32_bf16 v[94:97], v[170:173], v[214:217], v[94:97]
	v_mfma_f32_16x16x32_bf16 v[94:97], v[166:169], v[210:213], v[94:97]
	v_mfma_f32_16x16x32_bf16 v[78:81], v[166:169], v[218:221], v[78:81]
	v_mfma_f32_16x16x32_bf16 v[78:81], v[170:173], v[222:225], v[78:81]
	v_mfma_f32_16x16x32_bf16 v[86:89], v[156:159], v[222:225], v[86:89]
	v_mfma_f32_16x16x32_bf16 v[86:89], v[152:155], v[218:221], v[86:89]
	s_setprio 0
	s_setprio 1
	v_mfma_f32_16x16x32_bf16 v[114:117], v[174:177], v[190:193], v[114:117]
	v_mfma_f32_16x16x32_bf16 v[114:117], v[178:181], v[194:197], v[114:117]
	v_mfma_f32_16x16x32_bf16 v[106:109], v[186:189], v[194:197], v[106:109]
	v_mfma_f32_16x16x32_bf16 v[106:109], v[182:185], v[190:193], v[106:109]
	v_mfma_f32_16x16x32_bf16 v[90:93], v[182:185], v[202:205], v[90:93]
	v_mfma_f32_16x16x32_bf16 v[90:93], v[186:189], v[206:209], v[90:93]
	v_mfma_f32_16x16x32_bf16 v[98:101], v[178:181], v[206:209], v[98:101]
	v_mfma_f32_16x16x32_bf16 v[98:101], v[174:177], v[202:205], v[98:101]
	v_mfma_f32_16x16x32_bf16 v[82:85], v[174:177], v[210:213], v[82:85]
	v_mfma_f32_16x16x32_bf16 v[82:85], v[178:181], v[214:217], v[82:85]
	v_mfma_f32_16x16x32_bf16 v[74:77], v[186:189], v[214:217], v[74:77]
	v_mfma_f32_16x16x32_bf16 v[74:77], v[182:185], v[210:213], v[74:77]
	v_mfma_f32_16x16x32_bf16 v[66:69], v[182:185], v[218:221], v[66:69]
	v_mfma_f32_16x16x32_bf16 v[66:69], v[186:189], v[222:225], v[66:69]
	v_mfma_f32_16x16x32_bf16 v[70:73], v[178:181], v[222:225], v[70:73]
	v_mfma_f32_16x16x32_bf16 v[70:73], v[174:177], v[218:221], v[70:73]
	s_setprio 0
	s_barrier
	s_mov_b32 m0, s97
	v_lshl_add_u64 v[160:161], s[66:67], 0, v[136:137]
	ds_read_b128 v[190:193], v151 offset:16384
	ds_read_b128 v[194:197], v151 offset:17408
	ds_read_b128 v[202:205], v151 offset:18432
	ds_read_b128 v[206:209], v151 offset:19456
	ds_read_b128 v[210:213], v151 offset:20480
	ds_read_b128 v[214:217], v151 offset:21504
	ds_read_b128 v[218:221], v151 offset:22528
	ds_read_b128 v[222:225], v151 offset:23552
	global_load_lds_dwordx4 v[160:161], off
	v_lshl_add_u64 v[198:199], s[66:67], 0, v[132:133]
	s_mov_b32 m0, s94
	s_nop 0
	global_load_lds_dwordx4 v[198:199], off
	s_mov_b32 m0, s96
	v_lshl_add_u64 v[228:229], s[64:65], 0, v[134:135]
	global_load_lds_dwordx4 v136, s[68:69]
	s_mov_b32 m0, s95
	s_nop 0
	global_load_lds_dwordx4 v132, s[68:69]
	v_lshl_add_u64 v[226:227], s[64:65], 0, v[138:139]
	s_mov_b32 m0, s74
	s_nop 0
	global_load_lds_dwordx4 v[226:227], off
	s_mov_b32 m0, s75
	s_nop 0
	global_load_lds_dwordx4 v[228:229], off
	s_waitcnt vmcnt(8)
	s_waitcnt lgkmcnt(0)
	s_barrier
	s_setprio 1
	s_waitcnt lgkmcnt(0)
	v_mfma_f32_16x16x32_bf16 v[62:65], v[152:155], v[190:193], v[62:65]
	v_mfma_f32_16x16x32_bf16 v[62:65], v[156:159], v[194:197], v[62:65]
	v_mfma_f32_16x16x32_bf16 v[58:61], v[170:173], v[194:197], v[58:61]
	v_mfma_f32_16x16x32_bf16 v[58:61], v[166:169], v[190:193], v[58:61]
	v_mfma_f32_16x16x32_bf16 v[46:49], v[166:169], v[202:205], v[46:49]
	v_mfma_f32_16x16x32_bf16 v[46:49], v[170:173], v[206:209], v[46:49]
	v_mfma_f32_16x16x32_bf16 v[54:57], v[156:159], v[206:209], v[54:57]
	v_mfma_f32_16x16x32_bf16 v[54:57], v[152:155], v[202:205], v[54:57]
	v_mfma_f32_16x16x32_bf16 v[38:41], v[152:155], v[210:213], v[38:41]
	v_mfma_f32_16x16x32_bf16 v[38:41], v[156:159], v[214:217], v[38:41]
	v_mfma_f32_16x16x32_bf16 v[30:33], v[170:173], v[214:217], v[30:33]
	v_mfma_f32_16x16x32_bf16 v[30:33], v[166:169], v[210:213], v[30:33]
	v_mfma_f32_16x16x32_bf16 v[14:17], v[166:169], v[218:221], v[14:17]
	v_mfma_f32_16x16x32_bf16 v[14:17], v[170:173], v[222:225], v[14:17]
	v_mfma_f32_16x16x32_bf16 v[22:25], v[156:159], v[222:225], v[22:25]
	v_mfma_f32_16x16x32_bf16 v[22:25], v[152:155], v[218:221], v[22:25]
	s_setprio 0
	s_setprio 1
	v_mfma_f32_16x16x32_bf16 v[50:53], v[174:177], v[190:193], v[50:53]
	v_mfma_f32_16x16x32_bf16 v[50:53], v[178:181], v[194:197], v[50:53]
	v_mfma_f32_16x16x32_bf16 v[42:45], v[186:189], v[194:197], v[42:45]
	v_mfma_f32_16x16x32_bf16 v[42:45], v[182:185], v[190:193], v[42:45]
	v_mfma_f32_16x16x32_bf16 v[26:29], v[182:185], v[202:205], v[26:29]
	v_mfma_f32_16x16x32_bf16 v[26:29], v[186:189], v[206:209], v[26:29]
	v_mfma_f32_16x16x32_bf16 v[34:37], v[178:181], v[206:209], v[34:37]
	v_mfma_f32_16x16x32_bf16 v[34:37], v[174:177], v[202:205], v[34:37]
	v_mfma_f32_16x16x32_bf16 v[18:21], v[174:177], v[210:213], v[18:21]
	v_mfma_f32_16x16x32_bf16 v[18:21], v[178:181], v[214:217], v[18:21]
	v_mfma_f32_16x16x32_bf16 v[10:13], v[186:189], v[214:217], v[10:13]
	v_mfma_f32_16x16x32_bf16 v[10:13], v[182:185], v[210:213], v[10:13]
	v_mfma_f32_16x16x32_bf16 v[2:5], v[182:185], v[218:221], v[2:5]
	v_mfma_f32_16x16x32_bf16 v[2:5], v[186:189], v[222:225], v[2:5]
	v_mfma_f32_16x16x32_bf16 v[6:9], v[178:181], v[222:225], v[6:9]
	v_mfma_f32_16x16x32_bf16 v[6:9], v[174:177], v[218:221], v[6:9]
	s_setprio 0
	s_barrier
	v_add_u32_e32 v165, s93, v145
	ds_read_b128 v[152:155], v165
	ds_read_b128 v[156:159], v165 offset:1024
	ds_read_b128 v[166:169], v165 offset:2048
	ds_read_b128 v[170:173], v165 offset:3072
	v_add_u32_e32 v165, s92, v145
	ds_read_b128 v[174:177], v165
	ds_read_b128 v[178:181], v165 offset:1024
	ds_read_b128 v[182:185], v165 offset:2048
	ds_read_b128 v[186:189], v165 offset:3072
	s_mov_b32 m0, s76
	ds_read_b128 v[190:193], v151 offset:32768
	ds_read_b128 v[194:197], v151 offset:33792
	ds_read_b128 v[202:205], v151 offset:34816
	ds_read_b128 v[206:209], v151 offset:35840
	ds_read_b128 v[210:213], v151 offset:36864
	ds_read_b128 v[214:217], v151 offset:37888
	ds_read_b128 v[218:221], v151 offset:38912
	ds_read_b128 v[222:225], v151 offset:39936
	global_load_lds_dwordx4 v138, s[62:63]
	s_mov_b32 m0, s77
	s_nop 0
	global_load_lds_dwordx4 v134, s[62:63]
	s_waitcnt vmcnt(8)
	s_waitcnt lgkmcnt(0)
	s_barrier
	s_setprio 1
	s_waitcnt lgkmcnt(0)
	v_mfma_f32_16x16x32_bf16 v[126:129], v[152:155], v[190:193], v[126:129]
	v_mfma_f32_16x16x32_bf16 v[126:129], v[156:159], v[194:197], v[126:129]
	v_mfma_f32_16x16x32_bf16 v[122:125], v[170:173], v[194:197], v[122:125]
	v_mfma_f32_16x16x32_bf16 v[122:125], v[166:169], v[190:193], v[122:125]
	v_mfma_f32_16x16x32_bf16 v[110:113], v[166:169], v[202:205], v[110:113]
	v_mfma_f32_16x16x32_bf16 v[110:113], v[170:173], v[206:209], v[110:113]
	v_mfma_f32_16x16x32_bf16 v[118:121], v[156:159], v[206:209], v[118:121]
	v_mfma_f32_16x16x32_bf16 v[118:121], v[152:155], v[202:205], v[118:121]
	v_mfma_f32_16x16x32_bf16 v[102:105], v[152:155], v[210:213], v[102:105]
	v_mfma_f32_16x16x32_bf16 v[102:105], v[156:159], v[214:217], v[102:105]
	v_mfma_f32_16x16x32_bf16 v[94:97], v[170:173], v[214:217], v[94:97]
	v_mfma_f32_16x16x32_bf16 v[94:97], v[166:169], v[210:213], v[94:97]
	v_mfma_f32_16x16x32_bf16 v[78:81], v[166:169], v[218:221], v[78:81]
	v_mfma_f32_16x16x32_bf16 v[78:81], v[170:173], v[222:225], v[78:81]
	v_mfma_f32_16x16x32_bf16 v[86:89], v[156:159], v[222:225], v[86:89]
	v_mfma_f32_16x16x32_bf16 v[86:89], v[152:155], v[218:221], v[86:89]
	s_setprio 0
	s_setprio 1
	v_mfma_f32_16x16x32_bf16 v[114:117], v[174:177], v[190:193], v[114:117]
	v_mfma_f32_16x16x32_bf16 v[114:117], v[178:181], v[194:197], v[114:117]
	v_mfma_f32_16x16x32_bf16 v[106:109], v[186:189], v[194:197], v[106:109]
	v_mfma_f32_16x16x32_bf16 v[106:109], v[182:185], v[190:193], v[106:109]
	v_mfma_f32_16x16x32_bf16 v[90:93], v[182:185], v[202:205], v[90:93]
	v_mfma_f32_16x16x32_bf16 v[90:93], v[186:189], v[206:209], v[90:93]
	v_mfma_f32_16x16x32_bf16 v[98:101], v[178:181], v[206:209], v[98:101]
	v_mfma_f32_16x16x32_bf16 v[98:101], v[174:177], v[202:205], v[98:101]
	v_mfma_f32_16x16x32_bf16 v[82:85], v[174:177], v[210:213], v[82:85]
	v_mfma_f32_16x16x32_bf16 v[82:85], v[178:181], v[214:217], v[82:85]
	v_mfma_f32_16x16x32_bf16 v[74:77], v[186:189], v[214:217], v[74:77]
	v_mfma_f32_16x16x32_bf16 v[74:77], v[182:185], v[210:213], v[74:77]
	v_mfma_f32_16x16x32_bf16 v[66:69], v[182:185], v[218:221], v[66:69]
	v_mfma_f32_16x16x32_bf16 v[66:69], v[186:189], v[222:225], v[66:69]
	v_mfma_f32_16x16x32_bf16 v[70:73], v[178:181], v[222:225], v[70:73]
	v_mfma_f32_16x16x32_bf16 v[70:73], v[174:177], v[218:221], v[70:73]
	s_setprio 0
	s_barrier
	s_mov_b32 m0, s91
	v_lshl_add_u64 v[160:161], v[160:161], 0, s[14:15]
	ds_read_b128 v[190:193], v151 offset:49152
	ds_read_b128 v[194:197], v151 offset:50176
	ds_read_b128 v[202:205], v151 offset:51200
	ds_read_b128 v[206:209], v151 offset:52224
	ds_read_b128 v[210:213], v151 offset:53248
	ds_read_b128 v[214:217], v151 offset:54272
	ds_read_b128 v[218:221], v151 offset:55296
	ds_read_b128 v[222:225], v151 offset:56320
	global_load_lds_dwordx4 v[160:161], off
	v_lshl_add_u64 v[160:161], v[198:199], 0, s[14:15]
	s_mov_b32 m0, s89
	s_nop 0
	global_load_lds_dwordx4 v[160:161], off
	s_mov_b32 m0, s90
	s_nop 0
	global_load_lds_dwordx4 v136, s[60:61]
	s_mov_b32 m0, s44
	s_nop 0
	global_load_lds_dwordx4 v132, s[60:61]
	v_lshl_add_u64 v[160:161], v[226:227], 0, s[14:15]
	s_mov_b32 m0, s79
	s_nop 0
	global_load_lds_dwordx4 v[160:161], off
	v_lshl_add_u64 v[160:161], v[228:229], 0, s[14:15]
	s_mov_b32 m0, s80
	s_nop 0
	global_load_lds_dwordx4 v[160:161], off
	s_waitcnt vmcnt(8)
	s_waitcnt lgkmcnt(0)
	s_barrier
	s_setprio 1
	s_waitcnt lgkmcnt(0)
	v_mfma_f32_16x16x32_bf16 v[62:65], v[152:155], v[190:193], v[62:65]
	v_mfma_f32_16x16x32_bf16 v[62:65], v[156:159], v[194:197], v[62:65]
	v_mfma_f32_16x16x32_bf16 v[58:61], v[170:173], v[194:197], v[58:61]
	v_mfma_f32_16x16x32_bf16 v[58:61], v[166:169], v[190:193], v[58:61]
	v_mfma_f32_16x16x32_bf16 v[46:49], v[166:169], v[202:205], v[46:49]
	v_mfma_f32_16x16x32_bf16 v[46:49], v[170:173], v[206:209], v[46:49]
	v_mfma_f32_16x16x32_bf16 v[54:57], v[156:159], v[206:209], v[54:57]
	v_mfma_f32_16x16x32_bf16 v[54:57], v[152:155], v[202:205], v[54:57]
	v_mfma_f32_16x16x32_bf16 v[38:41], v[152:155], v[210:213], v[38:41]
	v_mfma_f32_16x16x32_bf16 v[38:41], v[156:159], v[214:217], v[38:41]
	v_mfma_f32_16x16x32_bf16 v[30:33], v[170:173], v[214:217], v[30:33]
	v_mfma_f32_16x16x32_bf16 v[30:33], v[166:169], v[210:213], v[30:33]
	v_mfma_f32_16x16x32_bf16 v[14:17], v[166:169], v[218:221], v[14:17]
	v_mfma_f32_16x16x32_bf16 v[14:17], v[170:173], v[222:225], v[14:17]
	v_mfma_f32_16x16x32_bf16 v[22:25], v[156:159], v[222:225], v[22:25]
	v_mfma_f32_16x16x32_bf16 v[22:25], v[152:155], v[218:221], v[22:25]
	s_setprio 0
	s_setprio 1
	v_mfma_f32_16x16x32_bf16 v[50:53], v[174:177], v[190:193], v[50:53]
	v_mfma_f32_16x16x32_bf16 v[50:53], v[178:181], v[194:197], v[50:53]
	v_mfma_f32_16x16x32_bf16 v[42:45], v[186:189], v[194:197], v[42:45]
	v_mfma_f32_16x16x32_bf16 v[42:45], v[182:185], v[190:193], v[42:45]
	v_mfma_f32_16x16x32_bf16 v[26:29], v[182:185], v[202:205], v[26:29]
	v_mfma_f32_16x16x32_bf16 v[26:29], v[186:189], v[206:209], v[26:29]
	v_mfma_f32_16x16x32_bf16 v[34:37], v[178:181], v[206:209], v[34:37]
	v_mfma_f32_16x16x32_bf16 v[34:37], v[174:177], v[202:205], v[34:37]
	v_mfma_f32_16x16x32_bf16 v[18:21], v[174:177], v[210:213], v[18:21]
	v_mfma_f32_16x16x32_bf16 v[18:21], v[178:181], v[214:217], v[18:21]
	v_mfma_f32_16x16x32_bf16 v[10:13], v[186:189], v[214:217], v[10:13]
	v_mfma_f32_16x16x32_bf16 v[10:13], v[182:185], v[210:213], v[10:13]
	v_mfma_f32_16x16x32_bf16 v[2:5], v[182:185], v[218:221], v[2:5]
	v_mfma_f32_16x16x32_bf16 v[2:5], v[186:189], v[222:225], v[2:5]
	v_mfma_f32_16x16x32_bf16 v[6:9], v[178:181], v[222:225], v[6:9]
	v_mfma_f32_16x16x32_bf16 v[6:9], v[174:177], v[218:221], v[6:9]
	s_setprio 0
	s_barrier
	s_movk_i32 s44, 0x100
	s_andn2_b64 vcc, exec, s[58:59]
	s_mov_b64 s[60:61], -1
	s_mov_b64 s[58:59], 0
	s_cbranch_vccz .LBB0_1701
	s_and_b64 vcc, exec, s[16:17]
	s_cbranch_vccz .LBB0_1704
	s_barrier

.LBB0_1902:
	ds_read_b128 v[148:151], v156
	ds_read_b128 v[166:169], v156 offset:1024
	ds_read_b128 v[170:173], v156 offset:2048
	ds_read_b128 v[174:177], v156 offset:3072
	ds_read_b128 v[178:181], v157
	ds_read_b128 v[182:185], v157 offset:1024
	ds_read_b128 v[186:189], v157 offset:2048
	ds_read_b128 v[190:193], v157 offset:3072
	s_add_i32 s92, s58, 2
	s_add_u32 s36, s56, 0xffd50080
	s_addc_u32 s37, s57, -1
	s_cmp_eq_u32 s89, s58
	s_cselect_b32 s58, s54, s90
	s_cselect_b32 s61, s53, s37
	s_cselect_b32 s60, s52, s36
	s_cselect_b32 s59, s55, s91
	s_add_i32 m0, s67, 0xc000
	ds_read_b128 v[194:197], v158
	ds_read_b128 v[202:205], v158 offset:1024
	ds_read_b128 v[206:209], v158 offset:2048
	ds_read_b128 v[210:213], v158 offset:3072
	ds_read_b128 v[214:217], v158 offset:4096
	ds_read_b128 v[218:221], v158 offset:5120
	ds_read_b128 v[222:225], v158 offset:6144
	ds_read_b128 v[226:229], v158 offset:7168
	global_load_lds_dwordx4 v142, s[56:57]
	s_add_i32 m0, s67, 0xe000
	s_nop 0
	global_load_lds_dwordx4 v144, s[56:57]
	s_waitcnt vmcnt(8)
	s_waitcnt lgkmcnt(0)
	s_barrier
	s_setprio 1
	s_waitcnt lgkmcnt(0)
	v_mfma_f32_16x16x32_bf16 v[126:129], v[148:151], v[194:197], v[126:129]
	v_mfma_f32_16x16x32_bf16 v[126:129], v[166:169], v[202:205], v[126:129]
	v_mfma_f32_16x16x32_bf16 v[122:125], v[174:177], v[202:205], v[122:125]
	v_mfma_f32_16x16x32_bf16 v[122:125], v[170:173], v[194:197], v[122:125]
	v_mfma_f32_16x16x32_bf16 v[106:109], v[170:173], v[206:209], v[106:109]
	v_mfma_f32_16x16x32_bf16 v[106:109], v[174:177], v[210:213], v[106:109]
	v_mfma_f32_16x16x32_bf16 v[110:113], v[166:169], v[210:213], v[110:113]
	v_mfma_f32_16x16x32_bf16 v[110:113], v[148:151], v[206:209], v[110:113]
	v_mfma_f32_16x16x32_bf16 v[94:97], v[148:151], v[214:217], v[94:97]
	v_mfma_f32_16x16x32_bf16 v[94:97], v[166:169], v[218:221], v[94:97]
	v_mfma_f32_16x16x32_bf16 v[90:93], v[174:177], v[218:221], v[90:93]
	v_mfma_f32_16x16x32_bf16 v[90:93], v[170:173], v[214:217], v[90:93]
	v_mfma_f32_16x16x32_bf16 v[74:77], v[170:173], v[222:225], v[74:77]
	v_mfma_f32_16x16x32_bf16 v[74:77], v[174:177], v[226:229], v[74:77]
	v_mfma_f32_16x16x32_bf16 v[78:81], v[166:169], v[226:229], v[78:81]
	v_mfma_f32_16x16x32_bf16 v[78:81], v[148:151], v[222:225], v[78:81]
	s_setprio 0
	s_setprio 1
	v_mfma_f32_16x16x32_bf16 v[118:121], v[178:181], v[194:197], v[118:121]
	v_mfma_f32_16x16x32_bf16 v[118:121], v[182:185], v[202:205], v[118:121]
	v_mfma_f32_16x16x32_bf16 v[114:117], v[190:193], v[202:205], v[114:117]
	v_mfma_f32_16x16x32_bf16 v[114:117], v[186:189], v[194:197], v[114:117]
	v_mfma_f32_16x16x32_bf16 v[98:101], v[186:189], v[206:209], v[98:101]
	v_mfma_f32_16x16x32_bf16 v[98:101], v[190:193], v[210:213], v[98:101]
	v_mfma_f32_16x16x32_bf16 v[102:105], v[182:185], v[210:213], v[102:105]
	v_mfma_f32_16x16x32_bf16 v[102:105], v[178:181], v[206:209], v[102:105]
	v_mfma_f32_16x16x32_bf16 v[86:89], v[178:181], v[214:217], v[86:89]
	v_mfma_f32_16x16x32_bf16 v[86:89], v[182:185], v[218:221], v[86:89]
	v_mfma_f32_16x16x32_bf16 v[82:85], v[190:193], v[218:221], v[82:85]
	v_mfma_f32_16x16x32_bf16 v[82:85], v[186:189], v[214:217], v[82:85]
	v_mfma_f32_16x16x32_bf16 v[66:69], v[186:189], v[222:225], v[66:69]
	v_mfma_f32_16x16x32_bf16 v[66:69], v[190:193], v[226:229], v[66:69]
	v_mfma_f32_16x16x32_bf16 v[70:73], v[182:185], v[226:229], v[70:73]
	v_mfma_f32_16x16x32_bf16 v[70:73], v[178:181], v[222:225], v[70:73]
	s_setprio 0
	s_barrier
	s_add_i32 s36, s77, s64
	v_lshl_add_u64 v[152:153], s[58:59], 0, v[134:135]
	s_mov_b32 m0, s36
	ds_read_b128 v[194:197], v158 offset:16384
	ds_read_b128 v[202:205], v158 offset:17408
	ds_read_b128 v[206:209], v158 offset:18432
	ds_read_b128 v[210:213], v158 offset:19456
	ds_read_b128 v[214:217], v158 offset:20480
	ds_read_b128 v[218:221], v158 offset:21504
	ds_read_b128 v[222:225], v158 offset:22528
	ds_read_b128 v[226:229], v158 offset:23552
	global_load_lds_dwordx4 v[152:153], off
	s_add_i32 m0, s36, 0x2000
	s_add_u32 s94, s58, 0x2b0000
	v_lshl_add_u64 v[160:161], s[58:59], 0, v[138:139]
	s_addc_u32 s95, s59, 0
	s_add_i32 s36, s78, s64
	global_load_lds_dwordx4 v[160:161], off
	s_mov_b32 m0, s36
	v_lshl_add_u64 v[230:231], s[60:61], 0, v[136:137]
	global_load_lds_dwordx4 v134, s[94:95]
	s_add_i32 m0, s36, 0x2000
	s_nop 0
	global_load_lds_dwordx4 v138, s[94:95]
	v_lshl_add_u64 v[198:199], s[60:61], 0, v[132:133]
	s_mov_b32 m0, s67
	s_nop 0
	global_load_lds_dwordx4 v[198:199], off
	s_mov_b32 m0, s68
	s_nop 0
	global_load_lds_dwordx4 v[230:231], off
	s_waitcnt vmcnt(8)
	s_waitcnt lgkmcnt(0)
	s_barrier
	s_setprio 1
	s_waitcnt lgkmcnt(0)
	v_mfma_f32_16x16x32_bf16 v[62:65], v[148:151], v[194:197], v[62:65]
	v_mfma_f32_16x16x32_bf16 v[62:65], v[166:169], v[202:205], v[62:65]
	v_mfma_f32_16x16x32_bf16 v[58:61], v[174:177], v[202:205], v[58:61]
	v_mfma_f32_16x16x32_bf16 v[58:61], v[170:173], v[194:197], v[58:61]
	v_mfma_f32_16x16x32_bf16 v[42:45], v[170:173], v[206:209], v[42:45]
	v_mfma_f32_16x16x32_bf16 v[42:45], v[174:177], v[210:213], v[42:45]
	v_mfma_f32_16x16x32_bf16 v[46:49], v[166:169], v[210:213], v[46:49]
	v_mfma_f32_16x16x32_bf16 v[46:49], v[148:151], v[206:209], v[46:49]
	v_mfma_f32_16x16x32_bf16 v[30:33], v[148:151], v[214:217], v[30:33]
	v_mfma_f32_16x16x32_bf16 v[30:33], v[166:169], v[218:221], v[30:33]
	v_mfma_f32_16x16x32_bf16 v[26:29], v[174:177], v[218:221], v[26:29]
	v_mfma_f32_16x16x32_bf16 v[26:29], v[170:173], v[214:217], v[26:29]
	v_mfma_f32_16x16x32_bf16 v[10:13], v[170:173], v[222:225], v[10:13]
	v_mfma_f32_16x16x32_bf16 v[10:13], v[174:177], v[226:229], v[10:13]
	v_mfma_f32_16x16x32_bf16 v[14:17], v[166:169], v[226:229], v[14:17]
	v_mfma_f32_16x16x32_bf16 v[14:17], v[148:151], v[222:225], v[14:17]
	s_setprio 0
	s_setprio 1
	v_mfma_f32_16x16x32_bf16 v[54:57], v[178:181], v[194:197], v[54:57]
	v_mfma_f32_16x16x32_bf16 v[54:57], v[182:185], v[202:205], v[54:57]
	v_mfma_f32_16x16x32_bf16 v[50:53], v[190:193], v[202:205], v[50:53]
	v_mfma_f32_16x16x32_bf16 v[50:53], v[186:189], v[194:197], v[50:53]
	v_mfma_f32_16x16x32_bf16 v[34:37], v[186:189], v[206:209], v[34:37]
	v_mfma_f32_16x16x32_bf16 v[34:37], v[190:193], v[210:213], v[34:37]
	v_mfma_f32_16x16x32_bf16 v[38:41], v[182:185], v[210:213], v[38:41]
	v_mfma_f32_16x16x32_bf16 v[38:41], v[178:181], v[206:209], v[38:41]
	v_mfma_f32_16x16x32_bf16 v[22:25], v[178:181], v[214:217], v[22:25]
	v_mfma_f32_16x16x32_bf16 v[22:25], v[182:185], v[218:221], v[22:25]
	v_mfma_f32_16x16x32_bf16 v[18:21], v[190:193], v[218:221], v[18:21]
	v_mfma_f32_16x16x32_bf16 v[18:21], v[186:189], v[214:217], v[18:21]
	v_mfma_f32_16x16x32_bf16 v[2:5], v[186:189], v[222:225], v[2:5]
	v_mfma_f32_16x16x32_bf16 v[2:5], v[190:193], v[226:229], v[2:5]
	v_mfma_f32_16x16x32_bf16 v[6:9], v[182:185], v[226:229], v[6:9]
	v_mfma_f32_16x16x32_bf16 v[6:9], v[178:181], v[222:225], v[6:9]
	s_setprio 0
	s_barrier
	s_add_i32 s36, 0, 0x18000
	v_add_u32_e32 v140, s36, v154
	s_add_i32 s37, 0, 0x1c000
	ds_read_b128 v[148:151], v140
	ds_read_b128 v[166:169], v140 offset:1024
	ds_read_b128 v[170:173], v140 offset:2048
	ds_read_b128 v[174:177], v140 offset:3072
	v_add_u32_e32 v140, s37, v154
	ds_read_b128 v[178:181], v140
	ds_read_b128 v[182:185], v140 offset:1024
	ds_read_b128 v[186:189], v140 offset:2048
	ds_read_b128 v[190:193], v140 offset:3072
	s_add_u32 s60, s60, 0x2b0000
	s_addc_u32 s61, s61, 0
	s_mov_b32 m0, s69
	ds_read_b128 v[194:197], v158 offset:32768
	ds_read_b128 v[202:205], v158 offset:33792
	ds_read_b128 v[206:209], v158 offset:34816
	ds_read_b128 v[210:213], v158 offset:35840
	ds_read_b128 v[214:217], v158 offset:36864
	ds_read_b128 v[218:221], v158 offset:37888
	ds_read_b128 v[222:225], v158 offset:38912
	ds_read_b128 v[226:229], v158 offset:39936
	global_load_lds_dwordx4 v132, s[60:61]
	s_mov_b32 m0, s70
	s_nop 0
	global_load_lds_dwordx4 v136, s[60:61]
	s_waitcnt vmcnt(8)
	s_waitcnt lgkmcnt(0)
	s_barrier
	s_setprio 1
	s_waitcnt lgkmcnt(0)
	v_mfma_f32_16x16x32_bf16 v[126:129], v[148:151], v[194:197], v[126:129]
	v_mfma_f32_16x16x32_bf16 v[126:129], v[166:169], v[202:205], v[126:129]
	v_mfma_f32_16x16x32_bf16 v[122:125], v[174:177], v[202:205], v[122:125]
	v_mfma_f32_16x16x32_bf16 v[122:125], v[170:173], v[194:197], v[122:125]
	v_mfma_f32_16x16x32_bf16 v[106:109], v[170:173], v[206:209], v[106:109]
	v_mfma_f32_16x16x32_bf16 v[106:109], v[174:177], v[210:213], v[106:109]
	v_mfma_f32_16x16x32_bf16 v[110:113], v[166:169], v[210:213], v[110:113]
	v_mfma_f32_16x16x32_bf16 v[110:113], v[148:151], v[206:209], v[110:113]
	v_mfma_f32_16x16x32_bf16 v[94:97], v[148:151], v[214:217], v[94:97]
	v_mfma_f32_16x16x32_bf16 v[94:97], v[166:169], v[218:221], v[94:97]
	v_mfma_f32_16x16x32_bf16 v[90:93], v[174:177], v[218:221], v[90:93]
	v_mfma_f32_16x16x32_bf16 v[90:93], v[170:173], v[214:217], v[90:93]
	v_mfma_f32_16x16x32_bf16 v[74:77], v[170:173], v[222:225], v[74:77]
	v_mfma_f32_16x16x32_bf16 v[74:77], v[174:177], v[226:229], v[74:77]
	v_mfma_f32_16x16x32_bf16 v[78:81], v[166:169], v[226:229], v[78:81]
	v_mfma_f32_16x16x32_bf16 v[78:81], v[148:151], v[222:225], v[78:81]
	s_setprio 0
	s_setprio 1
	v_mfma_f32_16x16x32_bf16 v[118:121], v[178:181], v[194:197], v[118:121]
	v_mfma_f32_16x16x32_bf16 v[118:121], v[182:185], v[202:205], v[118:121]
	v_mfma_f32_16x16x32_bf16 v[114:117], v[190:193], v[202:205], v[114:117]
	v_mfma_f32_16x16x32_bf16 v[114:117], v[186:189], v[194:197], v[114:117]
	v_mfma_f32_16x16x32_bf16 v[98:101], v[186:189], v[206:209], v[98:101]
	v_mfma_f32_16x16x32_bf16 v[98:101], v[190:193], v[210:213], v[98:101]
	v_mfma_f32_16x16x32_bf16 v[102:105], v[182:185], v[210:213], v[102:105]
	v_mfma_f32_16x16x32_bf16 v[102:105], v[178:181], v[206:209], v[102:105]
	v_mfma_f32_16x16x32_bf16 v[86:89], v[178:181], v[214:217], v[86:89]
	v_mfma_f32_16x16x32_bf16 v[86:89], v[182:185], v[218:221], v[86:89]
	v_mfma_f32_16x16x32_bf16 v[82:85], v[190:193], v[218:221], v[82:85]
	v_mfma_f32_16x16x32_bf16 v[82:85], v[186:189], v[214:217], v[82:85]
	v_mfma_f32_16x16x32_bf16 v[66:69], v[186:189], v[222:225], v[66:69]
	v_mfma_f32_16x16x32_bf16 v[66:69], v[190:193], v[226:229], v[66:69]
	v_mfma_f32_16x16x32_bf16 v[70:73], v[182:185], v[226:229], v[70:73]
	v_mfma_f32_16x16x32_bf16 v[70:73], v[178:181], v[222:225], v[70:73]
	s_setprio 0
	s_barrier
	s_add_i32 s36, s36, s64
	v_lshl_add_u64 v[152:153], v[152:153], 0, s[20:21]
	s_mov_b32 m0, s36
	ds_read_b128 v[194:197], v158 offset:49152
	ds_read_b128 v[202:205], v158 offset:50176
	ds_read_b128 v[206:209], v158 offset:51200
	ds_read_b128 v[210:213], v158 offset:52224
	ds_read_b128 v[214:217], v158 offset:53248
	ds_read_b128 v[218:221], v158 offset:54272
	ds_read_b128 v[222:225], v158 offset:55296
	ds_read_b128 v[226:229], v158 offset:56320
	global_load_lds_dwordx4 v[152:153], off
	s_add_i32 m0, s36, 0x2000
	s_add_u32 s58, s58, 0x2b0080
	v_lshl_add_u64 v[152:153], v[160:161], 0, s[20:21]
	s_addc_u32 s59, s59, 0
	s_add_i32 s36, s37, s64
	global_load_lds_dwordx4 v[152:153], off
	s_mov_b32 m0, s36
	s_nop 0
	global_load_lds_dwordx4 v134, s[58:59]
	s_add_i32 m0, s36, 0x2000
	s_nop 0
	global_load_lds_dwordx4 v138, s[58:59]
	v_lshl_add_u64 v[152:153], v[198:199], 0, s[20:21]
	s_mov_b32 m0, s73
	s_nop 0
	global_load_lds_dwordx4 v[152:153], off
	v_lshl_add_u64 v[152:153], v[230:231], 0, s[20:21]
	s_mov_b32 m0, s74
	s_nop 0
	global_load_lds_dwordx4 v[152:153], off
	s_waitcnt vmcnt(8)
	s_waitcnt lgkmcnt(0)
	s_barrier
	s_setprio 1
	s_waitcnt lgkmcnt(0)
	v_mfma_f32_16x16x32_bf16 v[62:65], v[148:151], v[194:197], v[62:65]
	v_mfma_f32_16x16x32_bf16 v[62:65], v[166:169], v[202:205], v[62:65]
	v_mfma_f32_16x16x32_bf16 v[58:61], v[174:177], v[202:205], v[58:61]
	v_mfma_f32_16x16x32_bf16 v[58:61], v[170:173], v[194:197], v[58:61]
	v_mfma_f32_16x16x32_bf16 v[42:45], v[170:173], v[206:209], v[42:45]
	v_mfma_f32_16x16x32_bf16 v[42:45], v[174:177], v[210:213], v[42:45]
	v_mfma_f32_16x16x32_bf16 v[46:49], v[166:169], v[210:213], v[46:49]
	v_mfma_f32_16x16x32_bf16 v[46:49], v[148:151], v[206:209], v[46:49]
	v_mfma_f32_16x16x32_bf16 v[30:33], v[148:151], v[214:217], v[30:33]
	v_mfma_f32_16x16x32_bf16 v[30:33], v[166:169], v[218:221], v[30:33]
	v_mfma_f32_16x16x32_bf16 v[26:29], v[174:177], v[218:221], v[26:29]
	v_mfma_f32_16x16x32_bf16 v[26:29], v[170:173], v[214:217], v[26:29]
	v_mfma_f32_16x16x32_bf16 v[10:13], v[170:173], v[222:225], v[10:13]
	v_mfma_f32_16x16x32_bf16 v[10:13], v[174:177], v[226:229], v[10:13]
	v_mfma_f32_16x16x32_bf16 v[14:17], v[166:169], v[226:229], v[14:17]
	v_mfma_f32_16x16x32_bf16 v[14:17], v[148:151], v[222:225], v[14:17]
	s_setprio 0
	s_setprio 1
	v_mfma_f32_16x16x32_bf16 v[54:57], v[178:181], v[194:197], v[54:57]
	v_mfma_f32_16x16x32_bf16 v[54:57], v[182:185], v[202:205], v[54:57]
	v_mfma_f32_16x16x32_bf16 v[50:53], v[190:193], v[202:205], v[50:53]
	v_mfma_f32_16x16x32_bf16 v[50:53], v[186:189], v[194:197], v[50:53]
	v_mfma_f32_16x16x32_bf16 v[34:37], v[186:189], v[206:209], v[34:37]
	v_mfma_f32_16x16x32_bf16 v[34:37], v[190:193], v[210:213], v[34:37]
	v_mfma_f32_16x16x32_bf16 v[38:41], v[182:185], v[210:213], v[38:41]
	v_mfma_f32_16x16x32_bf16 v[38:41], v[178:181], v[206:209], v[38:41]
	v_mfma_f32_16x16x32_bf16 v[22:25], v[178:181], v[214:217], v[22:25]
	v_mfma_f32_16x16x32_bf16 v[22:25], v[182:185], v[218:221], v[22:25]
	v_mfma_f32_16x16x32_bf16 v[18:21], v[190:193], v[218:221], v[18:21]
	v_mfma_f32_16x16x32_bf16 v[18:21], v[186:189], v[214:217], v[18:21]
	v_mfma_f32_16x16x32_bf16 v[2:5], v[186:189], v[222:225], v[2:5]
	v_mfma_f32_16x16x32_bf16 v[2:5], v[190:193], v[226:229], v[2:5]
	v_mfma_f32_16x16x32_bf16 v[6:9], v[182:185], v[226:229], v[6:9]
	v_mfma_f32_16x16x32_bf16 v[6:9], v[178:181], v[222:225], v[6:9]
	s_setprio 0
	s_barrier
	s_add_u32 s56, s56, 0x100
	s_addc_u32 s57, s57, 0
	s_add_u32 s90, s90, 0x100
	s_addc_u32 s91, s91, 0
	s_cmp_ge_i32 s92, s39
	s_mov_b32 s58, s92
	s_cbranch_scc0 .LBB0_1902
	s_and_b64 vcc, exec, s[24:25]
	s_cbranch_vccz .LBB0_1905

.LBB0_2138:
	ds_read_b128 v[146:149], v157
	ds_read_b128 v[164:167], v157 offset:1024
	ds_read_b128 v[168:171], v157 offset:2048
	ds_read_b128 v[172:175], v157 offset:3072
	ds_read_b128 v[176:179], v158
	ds_read_b128 v[180:183], v158 offset:1024
	ds_read_b128 v[184:187], v158 offset:2048
	ds_read_b128 v[188:191], v158 offset:3072
	s_add_u32 s24, s22, 0xfff00080
	s_addc_u32 s25, s23, -1
	s_cmp_eq_u32 s54, 60
	s_cselect_b32 s35, s15, s25
	s_cselect_b32 s34, s50, s24
	s_cselect_b32 s25, s13, s53
	s_cselect_b32 s24, s51, s52
	s_add_i32 m0, s21, 0xc000
	ds_read_b128 v[192:195], v159
	ds_read_b128 v[196:199], v159 offset:1024
	ds_read_b128 v[200:203], v159 offset:2048
	ds_read_b128 v[204:207], v159 offset:3072
	ds_read_b128 v[208:211], v159 offset:4096
	ds_read_b128 v[212:215], v159 offset:5120
	ds_read_b128 v[216:219], v159 offset:6144
	ds_read_b128 v[220:223], v159 offset:7168
	global_load_lds_dwordx4 v138, s[22:23]
	s_add_i32 m0, s21, 0xe000
	s_nop 0
	global_load_lds_dwordx4 v140, s[22:23]
	s_waitcnt vmcnt(8)
	s_waitcnt lgkmcnt(0)
	s_barrier
	s_setprio 1
	s_waitcnt lgkmcnt(0)
	v_mfma_f32_16x16x32_bf16 v[126:129], v[146:149], v[192:195], v[126:129]
	v_mfma_f32_16x16x32_bf16 v[126:129], v[164:167], v[196:199], v[126:129]
	v_mfma_f32_16x16x32_bf16 v[122:125], v[172:175], v[196:199], v[122:125]
	v_mfma_f32_16x16x32_bf16 v[122:125], v[168:171], v[192:195], v[122:125]
	v_mfma_f32_16x16x32_bf16 v[106:109], v[168:171], v[200:203], v[106:109]
	v_mfma_f32_16x16x32_bf16 v[106:109], v[172:175], v[204:207], v[106:109]
	v_mfma_f32_16x16x32_bf16 v[110:113], v[164:167], v[204:207], v[110:113]
	v_mfma_f32_16x16x32_bf16 v[110:113], v[146:149], v[200:203], v[110:113]
	v_mfma_f32_16x16x32_bf16 v[94:97], v[146:149], v[208:211], v[94:97]
	v_mfma_f32_16x16x32_bf16 v[94:97], v[164:167], v[212:215], v[94:97]
	v_mfma_f32_16x16x32_bf16 v[90:93], v[172:175], v[212:215], v[90:93]
	v_mfma_f32_16x16x32_bf16 v[90:93], v[168:171], v[208:211], v[90:93]
	v_mfma_f32_16x16x32_bf16 v[74:77], v[168:171], v[216:219], v[74:77]
	v_mfma_f32_16x16x32_bf16 v[74:77], v[172:175], v[220:223], v[74:77]
	v_mfma_f32_16x16x32_bf16 v[78:81], v[164:167], v[220:223], v[78:81]
	v_mfma_f32_16x16x32_bf16 v[78:81], v[146:149], v[216:219], v[78:81]
	s_setprio 0
	s_setprio 1
	v_mfma_f32_16x16x32_bf16 v[118:121], v[176:179], v[192:195], v[118:121]
	v_mfma_f32_16x16x32_bf16 v[118:121], v[180:183], v[196:199], v[118:121]
	v_mfma_f32_16x16x32_bf16 v[114:117], v[188:191], v[196:199], v[114:117]
	v_mfma_f32_16x16x32_bf16 v[114:117], v[184:187], v[192:195], v[114:117]
	v_mfma_f32_16x16x32_bf16 v[98:101], v[184:187], v[200:203], v[98:101]
	v_mfma_f32_16x16x32_bf16 v[98:101], v[188:191], v[204:207], v[98:101]
	v_mfma_f32_16x16x32_bf16 v[102:105], v[180:183], v[204:207], v[102:105]
	v_mfma_f32_16x16x32_bf16 v[102:105], v[176:179], v[200:203], v[102:105]
	v_mfma_f32_16x16x32_bf16 v[86:89], v[176:179], v[208:211], v[86:89]
	v_mfma_f32_16x16x32_bf16 v[86:89], v[180:183], v[212:215], v[86:89]
	v_mfma_f32_16x16x32_bf16 v[82:85], v[188:191], v[212:215], v[82:85]
	v_mfma_f32_16x16x32_bf16 v[82:85], v[184:187], v[208:211], v[82:85]
	v_mfma_f32_16x16x32_bf16 v[66:69], v[184:187], v[216:219], v[66:69]
	v_mfma_f32_16x16x32_bf16 v[66:69], v[188:191], v[220:223], v[66:69]
	v_mfma_f32_16x16x32_bf16 v[70:73], v[180:183], v[220:223], v[70:73]
	v_mfma_f32_16x16x32_bf16 v[70:73], v[176:179], v[216:219], v[70:73]
	s_setprio 0
	s_barrier
	s_add_i32 s55, s47, s27
	v_lshl_add_u64 v[150:151], s[24:25], 0, v[134:135]
	s_mov_b32 m0, s55
	ds_read_b128 v[192:195], v159 offset:16384
	ds_read_b128 v[196:199], v159 offset:17408
	ds_read_b128 v[200:203], v159 offset:18432
	ds_read_b128 v[204:207], v159 offset:19456
	ds_read_b128 v[208:211], v159 offset:20480
	ds_read_b128 v[212:215], v159 offset:21504
	ds_read_b128 v[216:219], v159 offset:22528
	ds_read_b128 v[220:223], v159 offset:23552
	global_load_lds_dwordx4 v[150:151], off
	s_add_i32 m0, s55, 0x2000
	s_add_u32 s56, s24, 0x100000
	v_lshl_add_u64 v[160:161], s[24:25], 0, v[130:131]
	s_addc_u32 s57, s25, 0
	s_add_i32 s55, s48, s27
	global_load_lds_dwordx4 v[160:161], off
	s_mov_b32 m0, s55
	v_lshl_add_u64 v[226:227], s[34:35], 0, v[132:133]
	global_load_lds_dwordx4 v134, s[56:57]
	s_add_i32 m0, s55, 0x2000
	s_nop 0
	global_load_lds_dwordx4 v130, s[56:57]
	v_lshl_add_u64 v[224:225], s[34:35], 0, v[136:137]
	s_mov_b32 m0, s21
	s_nop 0
	global_load_lds_dwordx4 v[224:225], off
	s_mov_b32 m0, s40
	s_nop 0
	global_load_lds_dwordx4 v[226:227], off
	s_waitcnt vmcnt(8)
	s_waitcnt lgkmcnt(0)
	s_barrier
	s_setprio 1
	s_waitcnt lgkmcnt(0)
	v_mfma_f32_16x16x32_bf16 v[62:65], v[146:149], v[192:195], v[62:65]
	v_mfma_f32_16x16x32_bf16 v[62:65], v[164:167], v[196:199], v[62:65]
	v_mfma_f32_16x16x32_bf16 v[58:61], v[172:175], v[196:199], v[58:61]
	v_mfma_f32_16x16x32_bf16 v[58:61], v[168:171], v[192:195], v[58:61]
	v_mfma_f32_16x16x32_bf16 v[42:45], v[168:171], v[200:203], v[42:45]
	v_mfma_f32_16x16x32_bf16 v[42:45], v[172:175], v[204:207], v[42:45]
	v_mfma_f32_16x16x32_bf16 v[46:49], v[164:167], v[204:207], v[46:49]
	v_mfma_f32_16x16x32_bf16 v[46:49], v[146:149], v[200:203], v[46:49]
	v_mfma_f32_16x16x32_bf16 v[30:33], v[146:149], v[208:211], v[30:33]
	v_mfma_f32_16x16x32_bf16 v[30:33], v[164:167], v[212:215], v[30:33]
	v_mfma_f32_16x16x32_bf16 v[26:29], v[172:175], v[212:215], v[26:29]
	v_mfma_f32_16x16x32_bf16 v[26:29], v[168:171], v[208:211], v[26:29]
	v_mfma_f32_16x16x32_bf16 v[10:13], v[168:171], v[216:219], v[10:13]
	v_mfma_f32_16x16x32_bf16 v[10:13], v[172:175], v[220:223], v[10:13]
	v_mfma_f32_16x16x32_bf16 v[14:17], v[164:167], v[220:223], v[14:17]
	v_mfma_f32_16x16x32_bf16 v[14:17], v[146:149], v[216:219], v[14:17]
	s_setprio 0
	s_setprio 1
	v_mfma_f32_16x16x32_bf16 v[54:57], v[176:179], v[192:195], v[54:57]
	v_mfma_f32_16x16x32_bf16 v[54:57], v[180:183], v[196:199], v[54:57]
	v_mfma_f32_16x16x32_bf16 v[50:53], v[188:191], v[196:199], v[50:53]
	v_mfma_f32_16x16x32_bf16 v[50:53], v[184:187], v[192:195], v[50:53]
	v_mfma_f32_16x16x32_bf16 v[34:37], v[184:187], v[200:203], v[34:37]
	v_mfma_f32_16x16x32_bf16 v[34:37], v[188:191], v[204:207], v[34:37]
	v_mfma_f32_16x16x32_bf16 v[38:41], v[180:183], v[204:207], v[38:41]
	v_mfma_f32_16x16x32_bf16 v[38:41], v[176:179], v[200:203], v[38:41]
	v_mfma_f32_16x16x32_bf16 v[22:25], v[176:179], v[208:211], v[22:25]
	v_mfma_f32_16x16x32_bf16 v[22:25], v[180:183], v[212:215], v[22:25]
	v_mfma_f32_16x16x32_bf16 v[18:21], v[188:191], v[212:215], v[18:21]
	v_mfma_f32_16x16x32_bf16 v[18:21], v[184:187], v[208:211], v[18:21]
	v_mfma_f32_16x16x32_bf16 v[2:5], v[184:187], v[216:219], v[2:5]
	v_mfma_f32_16x16x32_bf16 v[2:5], v[188:191], v[220:223], v[2:5]
	v_mfma_f32_16x16x32_bf16 v[6:9], v[180:183], v[220:223], v[6:9]
	v_mfma_f32_16x16x32_bf16 v[6:9], v[176:179], v[216:219], v[6:9]
	s_setprio 0
	s_barrier
	s_add_i32 s55, 0, 0x18000
	v_add_u32_e32 v162, s55, v155
	s_add_i32 s56, 0, 0x1c000
	ds_read_b128 v[146:149], v162
	ds_read_b128 v[164:167], v162 offset:1024
	ds_read_b128 v[168:171], v162 offset:2048
	ds_read_b128 v[172:175], v162 offset:3072
	v_add_u32_e32 v162, s56, v155
	ds_read_b128 v[176:179], v162
	ds_read_b128 v[180:183], v162 offset:1024
	ds_read_b128 v[184:187], v162 offset:2048
	ds_read_b128 v[188:191], v162 offset:3072
	s_add_u32 s34, s34, 0x100000
	s_addc_u32 s35, s35, 0
	s_mov_b32 m0, s41
	ds_read_b128 v[192:195], v159 offset:32768
	ds_read_b128 v[196:199], v159 offset:33792
	ds_read_b128 v[200:203], v159 offset:34816
	ds_read_b128 v[204:207], v159 offset:35840
	ds_read_b128 v[208:211], v159 offset:36864
	ds_read_b128 v[212:215], v159 offset:37888
	ds_read_b128 v[216:219], v159 offset:38912
	ds_read_b128 v[220:223], v159 offset:39936
	global_load_lds_dwordx4 v136, s[34:35]
	s_mov_b32 m0, s42
	s_nop 0
	global_load_lds_dwordx4 v132, s[34:35]
	s_waitcnt vmcnt(8)
	s_waitcnt lgkmcnt(0)
	s_barrier
	s_setprio 1
	s_waitcnt lgkmcnt(0)
	v_mfma_f32_16x16x32_bf16 v[126:129], v[146:149], v[192:195], v[126:129]
	v_mfma_f32_16x16x32_bf16 v[126:129], v[164:167], v[196:199], v[126:129]
	v_mfma_f32_16x16x32_bf16 v[122:125], v[172:175], v[196:199], v[122:125]
	v_mfma_f32_16x16x32_bf16 v[122:125], v[168:171], v[192:195], v[122:125]
	v_mfma_f32_16x16x32_bf16 v[106:109], v[168:171], v[200:203], v[106:109]
	v_mfma_f32_16x16x32_bf16 v[106:109], v[172:175], v[204:207], v[106:109]
	v_mfma_f32_16x16x32_bf16 v[110:113], v[164:167], v[204:207], v[110:113]
	v_mfma_f32_16x16x32_bf16 v[110:113], v[146:149], v[200:203], v[110:113]
	v_mfma_f32_16x16x32_bf16 v[94:97], v[146:149], v[208:211], v[94:97]
	v_mfma_f32_16x16x32_bf16 v[94:97], v[164:167], v[212:215], v[94:97]
	v_mfma_f32_16x16x32_bf16 v[90:93], v[172:175], v[212:215], v[90:93]
	v_mfma_f32_16x16x32_bf16 v[90:93], v[168:171], v[208:211], v[90:93]
	v_mfma_f32_16x16x32_bf16 v[74:77], v[168:171], v[216:219], v[74:77]
	v_mfma_f32_16x16x32_bf16 v[74:77], v[172:175], v[220:223], v[74:77]
	v_mfma_f32_16x16x32_bf16 v[78:81], v[164:167], v[220:223], v[78:81]
	v_mfma_f32_16x16x32_bf16 v[78:81], v[146:149], v[216:219], v[78:81]
	s_setprio 0
	s_setprio 1
	v_mfma_f32_16x16x32_bf16 v[118:121], v[176:179], v[192:195], v[118:121]
	v_mfma_f32_16x16x32_bf16 v[118:121], v[180:183], v[196:199], v[118:121]
	v_mfma_f32_16x16x32_bf16 v[114:117], v[188:191], v[196:199], v[114:117]
	v_mfma_f32_16x16x32_bf16 v[114:117], v[184:187], v[192:195], v[114:117]
	v_mfma_f32_16x16x32_bf16 v[98:101], v[184:187], v[200:203], v[98:101]
	v_mfma_f32_16x16x32_bf16 v[98:101], v[188:191], v[204:207], v[98:101]
	v_mfma_f32_16x16x32_bf16 v[102:105], v[180:183], v[204:207], v[102:105]
	v_mfma_f32_16x16x32_bf16 v[102:105], v[176:179], v[200:203], v[102:105]
	v_mfma_f32_16x16x32_bf16 v[86:89], v[176:179], v[208:211], v[86:89]
	v_mfma_f32_16x16x32_bf16 v[86:89], v[180:183], v[212:215], v[86:89]
	v_mfma_f32_16x16x32_bf16 v[82:85], v[188:191], v[212:215], v[82:85]
	v_mfma_f32_16x16x32_bf16 v[82:85], v[184:187], v[208:211], v[82:85]
	v_mfma_f32_16x16x32_bf16 v[66:69], v[184:187], v[216:219], v[66:69]
	v_mfma_f32_16x16x32_bf16 v[66:69], v[188:191], v[220:223], v[66:69]
	v_mfma_f32_16x16x32_bf16 v[70:73], v[180:183], v[220:223], v[70:73]
	v_mfma_f32_16x16x32_bf16 v[70:73], v[176:179], v[216:219], v[70:73]
	s_setprio 0
	s_barrier
	s_add_i32 s34, s55, s27
	v_lshl_add_u64 v[150:151], v[150:151], 0, s[8:9]
	s_mov_b32 m0, s34
	ds_read_b128 v[192:195], v159 offset:49152
	ds_read_b128 v[196:199], v159 offset:50176
	ds_read_b128 v[200:203], v159 offset:51200
	ds_read_b128 v[204:207], v159 offset:52224
	ds_read_b128 v[208:211], v159 offset:53248
	ds_read_b128 v[212:215], v159 offset:54272
	ds_read_b128 v[216:219], v159 offset:55296
	ds_read_b128 v[220:223], v159 offset:56320
	global_load_lds_dwordx4 v[150:151], off
	s_add_i32 m0, s34, 0x2000
	s_add_u32 s24, s24, 0x100080
	v_lshl_add_u64 v[150:151], v[160:161], 0, s[8:9]
	s_addc_u32 s25, s25, 0
	s_add_i32 s34, s56, s27
	global_load_lds_dwordx4 v[150:151], off
	s_mov_b32 m0, s34
	s_nop 0
	global_load_lds_dwordx4 v134, s[24:25]
	s_add_i32 m0, s34, 0x2000
	s_nop 0
	global_load_lds_dwordx4 v130, s[24:25]
	v_lshl_add_u64 v[150:151], v[224:225], 0, s[8:9]
	s_mov_b32 m0, s44
	s_nop 0
	global_load_lds_dwordx4 v[150:151], off
	v_lshl_add_u64 v[150:151], v[226:227], 0, s[8:9]
	s_mov_b32 m0, s45
	s_nop 0
	global_load_lds_dwordx4 v[150:151], off
	s_waitcnt vmcnt(8)
	s_waitcnt lgkmcnt(0)
	s_barrier
	s_setprio 1
	s_waitcnt lgkmcnt(0)
	v_mfma_f32_16x16x32_bf16 v[62:65], v[146:149], v[192:195], v[62:65]
	v_mfma_f32_16x16x32_bf16 v[62:65], v[164:167], v[196:199], v[62:65]
	v_mfma_f32_16x16x32_bf16 v[58:61], v[172:175], v[196:199], v[58:61]
	v_mfma_f32_16x16x32_bf16 v[58:61], v[168:171], v[192:195], v[58:61]
	v_mfma_f32_16x16x32_bf16 v[42:45], v[168:171], v[200:203], v[42:45]
	v_mfma_f32_16x16x32_bf16 v[42:45], v[172:175], v[204:207], v[42:45]
	v_mfma_f32_16x16x32_bf16 v[46:49], v[164:167], v[204:207], v[46:49]
	v_mfma_f32_16x16x32_bf16 v[46:49], v[146:149], v[200:203], v[46:49]
	v_mfma_f32_16x16x32_bf16 v[30:33], v[146:149], v[208:211], v[30:33]
	v_mfma_f32_16x16x32_bf16 v[30:33], v[164:167], v[212:215], v[30:33]
	v_mfma_f32_16x16x32_bf16 v[26:29], v[172:175], v[212:215], v[26:29]
	v_mfma_f32_16x16x32_bf16 v[26:29], v[168:171], v[208:211], v[26:29]
	v_mfma_f32_16x16x32_bf16 v[10:13], v[168:171], v[216:219], v[10:13]
	v_mfma_f32_16x16x32_bf16 v[10:13], v[172:175], v[220:223], v[10:13]
	v_mfma_f32_16x16x32_bf16 v[14:17], v[164:167], v[220:223], v[14:17]
	v_mfma_f32_16x16x32_bf16 v[14:17], v[146:149], v[216:219], v[14:17]
	s_setprio 0
	s_setprio 1
	v_mfma_f32_16x16x32_bf16 v[54:57], v[176:179], v[192:195], v[54:57]
	v_mfma_f32_16x16x32_bf16 v[54:57], v[180:183], v[196:199], v[54:57]
	v_mfma_f32_16x16x32_bf16 v[50:53], v[188:191], v[196:199], v[50:53]
	v_mfma_f32_16x16x32_bf16 v[50:53], v[184:187], v[192:195], v[50:53]
	v_mfma_f32_16x16x32_bf16 v[34:37], v[184:187], v[200:203], v[34:37]
	v_mfma_f32_16x16x32_bf16 v[34:37], v[188:191], v[204:207], v[34:37]
	v_mfma_f32_16x16x32_bf16 v[38:41], v[180:183], v[204:207], v[38:41]
	v_mfma_f32_16x16x32_bf16 v[38:41], v[176:179], v[200:203], v[38:41]
	v_mfma_f32_16x16x32_bf16 v[22:25], v[176:179], v[208:211], v[22:25]
	v_mfma_f32_16x16x32_bf16 v[22:25], v[180:183], v[212:215], v[22:25]
	v_mfma_f32_16x16x32_bf16 v[18:21], v[188:191], v[212:215], v[18:21]
	v_mfma_f32_16x16x32_bf16 v[18:21], v[184:187], v[208:211], v[18:21]
	v_mfma_f32_16x16x32_bf16 v[2:5], v[184:187], v[216:219], v[2:5]
	v_mfma_f32_16x16x32_bf16 v[2:5], v[188:191], v[220:223], v[2:5]
	v_mfma_f32_16x16x32_bf16 v[6:9], v[180:183], v[220:223], v[6:9]
	v_mfma_f32_16x16x32_bf16 v[6:9], v[176:179], v[216:219], v[6:9]
	s_setprio 0
	s_barrier
	s_add_i32 s54, s54, 2
	s_add_u32 s22, s22, 0x100
	s_addc_u32 s23, s23, 0
	s_add_u32 s52, s52, 0x100
	s_addc_u32 s53, s53, 0
	s_cmp_gt_u32 s54, 61
	s_cbranch_scc0 .LBB0_2138
	s_and_b64 vcc, exec, s[10:11]
	s_cbranch_vccz .LBB0_2141
	s_barrier

.LBB0_2158:
	ds_read_b128 v[146:149], v157
	ds_read_b128 v[164:167], v157 offset:1024
	ds_read_b128 v[168:171], v157 offset:2048
	ds_read_b128 v[172:175], v157 offset:3072
	ds_read_b128 v[176:179], v158
	ds_read_b128 v[180:183], v158 offset:1024
	ds_read_b128 v[184:187], v158 offset:2048
	ds_read_b128 v[188:191], v158 offset:3072
	s_add_u32 s26, s24, 0xfff00080
	s_addc_u32 s27, s25, -1
	s_cmp_eq_u32 s52, 60
	s_cselect_b32 s35, s17, s27
	s_cselect_b32 s34, s48, s26
	s_cselect_b32 s27, s15, s51
	s_cselect_b32 s26, s49, s50
	s_add_i32 m0, s23, 0xc000
	ds_read_b128 v[192:195], v159
	ds_read_b128 v[196:199], v159 offset:1024
	ds_read_b128 v[200:203], v159 offset:2048
	ds_read_b128 v[204:207], v159 offset:3072
	ds_read_b128 v[208:211], v159 offset:4096
	ds_read_b128 v[212:215], v159 offset:5120
	ds_read_b128 v[216:219], v159 offset:6144
	ds_read_b128 v[220:223], v159 offset:7168
	global_load_lds_dwordx4 v138, s[24:25]
	s_add_i32 m0, s23, 0xe000
	s_nop 0
	global_load_lds_dwordx4 v140, s[24:25]
	s_waitcnt vmcnt(8)
	s_waitcnt lgkmcnt(0)
	s_barrier
	s_setprio 1
	s_waitcnt lgkmcnt(0)
	v_mfma_f32_16x16x32_bf16 v[126:129], v[146:149], v[192:195], v[126:129]
	v_mfma_f32_16x16x32_bf16 v[126:129], v[164:167], v[196:199], v[126:129]
	v_mfma_f32_16x16x32_bf16 v[122:125], v[172:175], v[196:199], v[122:125]
	v_mfma_f32_16x16x32_bf16 v[122:125], v[168:171], v[192:195], v[122:125]
	v_mfma_f32_16x16x32_bf16 v[106:109], v[168:171], v[200:203], v[106:109]
	v_mfma_f32_16x16x32_bf16 v[106:109], v[172:175], v[204:207], v[106:109]
	v_mfma_f32_16x16x32_bf16 v[110:113], v[164:167], v[204:207], v[110:113]
	v_mfma_f32_16x16x32_bf16 v[110:113], v[146:149], v[200:203], v[110:113]
	v_mfma_f32_16x16x32_bf16 v[94:97], v[146:149], v[208:211], v[94:97]
	v_mfma_f32_16x16x32_bf16 v[94:97], v[164:167], v[212:215], v[94:97]
	v_mfma_f32_16x16x32_bf16 v[90:93], v[172:175], v[212:215], v[90:93]
	v_mfma_f32_16x16x32_bf16 v[90:93], v[168:171], v[208:211], v[90:93]
	v_mfma_f32_16x16x32_bf16 v[74:77], v[168:171], v[216:219], v[74:77]
	v_mfma_f32_16x16x32_bf16 v[74:77], v[172:175], v[220:223], v[74:77]
	v_mfma_f32_16x16x32_bf16 v[78:81], v[164:167], v[220:223], v[78:81]
	v_mfma_f32_16x16x32_bf16 v[78:81], v[146:149], v[216:219], v[78:81]
	s_setprio 0
	s_setprio 1
	v_mfma_f32_16x16x32_bf16 v[118:121], v[176:179], v[192:195], v[118:121]
	v_mfma_f32_16x16x32_bf16 v[118:121], v[180:183], v[196:199], v[118:121]
	v_mfma_f32_16x16x32_bf16 v[114:117], v[188:191], v[196:199], v[114:117]
	v_mfma_f32_16x16x32_bf16 v[114:117], v[184:187], v[192:195], v[114:117]
	v_mfma_f32_16x16x32_bf16 v[98:101], v[184:187], v[200:203], v[98:101]
	v_mfma_f32_16x16x32_bf16 v[98:101], v[188:191], v[204:207], v[98:101]
	v_mfma_f32_16x16x32_bf16 v[102:105], v[180:183], v[204:207], v[102:105]
	v_mfma_f32_16x16x32_bf16 v[102:105], v[176:179], v[200:203], v[102:105]
	v_mfma_f32_16x16x32_bf16 v[86:89], v[176:179], v[208:211], v[86:89]
	v_mfma_f32_16x16x32_bf16 v[86:89], v[180:183], v[212:215], v[86:89]
	v_mfma_f32_16x16x32_bf16 v[82:85], v[188:191], v[212:215], v[82:85]
	v_mfma_f32_16x16x32_bf16 v[82:85], v[184:187], v[208:211], v[82:85]
	v_mfma_f32_16x16x32_bf16 v[66:69], v[184:187], v[216:219], v[66:69]
	v_mfma_f32_16x16x32_bf16 v[66:69], v[188:191], v[220:223], v[66:69]
	v_mfma_f32_16x16x32_bf16 v[70:73], v[180:183], v[220:223], v[70:73]
	v_mfma_f32_16x16x32_bf16 v[70:73], v[176:179], v[216:219], v[70:73]
	s_setprio 0
	s_barrier
	s_add_i32 s53, s45, s38
	v_lshl_add_u64 v[150:151], s[26:27], 0, v[132:133]
	s_mov_b32 m0, s53
	ds_read_b128 v[192:195], v159 offset:16384
	ds_read_b128 v[196:199], v159 offset:17408
	ds_read_b128 v[200:203], v159 offset:18432
	ds_read_b128 v[204:207], v159 offset:19456
	ds_read_b128 v[208:211], v159 offset:20480
	ds_read_b128 v[212:215], v159 offset:21504
	ds_read_b128 v[216:219], v159 offset:22528
	ds_read_b128 v[220:223], v159 offset:23552
	global_load_lds_dwordx4 v[150:151], off
	s_add_i32 m0, s53, 0x2000
	s_add_u32 s54, s26, 0x100000
	v_lshl_add_u64 v[160:161], s[26:27], 0, v[134:135]
	s_addc_u32 s55, s27, 0
	s_add_i32 s53, s46, s38
	global_load_lds_dwordx4 v[160:161], off
	s_mov_b32 m0, s53
	v_lshl_add_u64 v[226:227], s[34:35], 0, v[136:137]
	global_load_lds_dwordx4 v132, s[54:55]
	s_add_i32 m0, s53, 0x2000
	s_nop 0
	global_load_lds_dwordx4 v134, s[54:55]
	v_lshl_add_u64 v[224:225], s[34:35], 0, v[130:131]
	s_mov_b32 m0, s23
	s_nop 0
	global_load_lds_dwordx4 v[224:225], off
	s_mov_b32 m0, s40
	s_nop 0
	global_load_lds_dwordx4 v[226:227], off
	s_waitcnt vmcnt(8)
	s_waitcnt lgkmcnt(0)
	s_barrier
	s_setprio 1
	s_waitcnt lgkmcnt(0)
	v_mfma_f32_16x16x32_bf16 v[62:65], v[146:149], v[192:195], v[62:65]
	v_mfma_f32_16x16x32_bf16 v[62:65], v[164:167], v[196:199], v[62:65]
	v_mfma_f32_16x16x32_bf16 v[58:61], v[172:175], v[196:199], v[58:61]
	v_mfma_f32_16x16x32_bf16 v[58:61], v[168:171], v[192:195], v[58:61]
	v_mfma_f32_16x16x32_bf16 v[42:45], v[168:171], v[200:203], v[42:45]
	v_mfma_f32_16x16x32_bf16 v[42:45], v[172:175], v[204:207], v[42:45]
	v_mfma_f32_16x16x32_bf16 v[46:49], v[164:167], v[204:207], v[46:49]
	v_mfma_f32_16x16x32_bf16 v[46:49], v[146:149], v[200:203], v[46:49]
	v_mfma_f32_16x16x32_bf16 v[30:33], v[146:149], v[208:211], v[30:33]
	v_mfma_f32_16x16x32_bf16 v[30:33], v[164:167], v[212:215], v[30:33]
	v_mfma_f32_16x16x32_bf16 v[26:29], v[172:175], v[212:215], v[26:29]
	v_mfma_f32_16x16x32_bf16 v[26:29], v[168:171], v[208:211], v[26:29]
	v_mfma_f32_16x16x32_bf16 v[10:13], v[168:171], v[216:219], v[10:13]
	v_mfma_f32_16x16x32_bf16 v[10:13], v[172:175], v[220:223], v[10:13]
	v_mfma_f32_16x16x32_bf16 v[14:17], v[164:167], v[220:223], v[14:17]
	v_mfma_f32_16x16x32_bf16 v[14:17], v[146:149], v[216:219], v[14:17]
	s_setprio 0
	s_setprio 1
	v_mfma_f32_16x16x32_bf16 v[54:57], v[176:179], v[192:195], v[54:57]
	v_mfma_f32_16x16x32_bf16 v[54:57], v[180:183], v[196:199], v[54:57]
	v_mfma_f32_16x16x32_bf16 v[50:53], v[188:191], v[196:199], v[50:53]
	v_mfma_f32_16x16x32_bf16 v[50:53], v[184:187], v[192:195], v[50:53]
	v_mfma_f32_16x16x32_bf16 v[34:37], v[184:187], v[200:203], v[34:37]
	v_mfma_f32_16x16x32_bf16 v[34:37], v[188:191], v[204:207], v[34:37]
	v_mfma_f32_16x16x32_bf16 v[38:41], v[180:183], v[204:207], v[38:41]
	v_mfma_f32_16x16x32_bf16 v[38:41], v[176:179], v[200:203], v[38:41]
	v_mfma_f32_16x16x32_bf16 v[22:25], v[176:179], v[208:211], v[22:25]
	v_mfma_f32_16x16x32_bf16 v[22:25], v[180:183], v[212:215], v[22:25]
	v_mfma_f32_16x16x32_bf16 v[18:21], v[188:191], v[212:215], v[18:21]
	v_mfma_f32_16x16x32_bf16 v[18:21], v[184:187], v[208:211], v[18:21]
	v_mfma_f32_16x16x32_bf16 v[2:5], v[184:187], v[216:219], v[2:5]
	v_mfma_f32_16x16x32_bf16 v[2:5], v[188:191], v[220:223], v[2:5]
	v_mfma_f32_16x16x32_bf16 v[6:9], v[180:183], v[220:223], v[6:9]
	v_mfma_f32_16x16x32_bf16 v[6:9], v[176:179], v[216:219], v[6:9]
	s_setprio 0
	s_barrier
	s_add_i32 s53, 0, 0x18000
	v_add_u32_e32 v162, s53, v155
	s_add_i32 s54, 0, 0x1c000
	ds_read_b128 v[146:149], v162
	ds_read_b128 v[164:167], v162 offset:1024
	ds_read_b128 v[168:171], v162 offset:2048
	ds_read_b128 v[172:175], v162 offset:3072
	v_add_u32_e32 v162, s54, v155
	ds_read_b128 v[176:179], v162
	ds_read_b128 v[180:183], v162 offset:1024
	ds_read_b128 v[184:187], v162 offset:2048
	ds_read_b128 v[188:191], v162 offset:3072
	s_add_u32 s34, s34, 0x100000
	s_addc_u32 s35, s35, 0
	s_mov_b32 m0, s41
	ds_read_b128 v[192:195], v159 offset:32768
	ds_read_b128 v[196:199], v159 offset:33792
	ds_read_b128 v[200:203], v159 offset:34816
	ds_read_b128 v[204:207], v159 offset:35840
	ds_read_b128 v[208:211], v159 offset:36864
	ds_read_b128 v[212:215], v159 offset:37888
	ds_read_b128 v[216:219], v159 offset:38912
	ds_read_b128 v[220:223], v159 offset:39936
	global_load_lds_dwordx4 v130, s[34:35]
	s_mov_b32 m0, s42
	s_nop 0
	global_load_lds_dwordx4 v136, s[34:35]
	s_waitcnt vmcnt(8)
	s_waitcnt lgkmcnt(0)
	s_barrier
	s_setprio 1
	s_waitcnt lgkmcnt(0)
	v_mfma_f32_16x16x32_bf16 v[126:129], v[146:149], v[192:195], v[126:129]
	v_mfma_f32_16x16x32_bf16 v[126:129], v[164:167], v[196:199], v[126:129]
	v_mfma_f32_16x16x32_bf16 v[122:125], v[172:175], v[196:199], v[122:125]
	v_mfma_f32_16x16x32_bf16 v[122:125], v[168:171], v[192:195], v[122:125]
	v_mfma_f32_16x16x32_bf16 v[106:109], v[168:171], v[200:203], v[106:109]
	v_mfma_f32_16x16x32_bf16 v[106:109], v[172:175], v[204:207], v[106:109]
	v_mfma_f32_16x16x32_bf16 v[110:113], v[164:167], v[204:207], v[110:113]
	v_mfma_f32_16x16x32_bf16 v[110:113], v[146:149], v[200:203], v[110:113]
	v_mfma_f32_16x16x32_bf16 v[94:97], v[146:149], v[208:211], v[94:97]
	v_mfma_f32_16x16x32_bf16 v[94:97], v[164:167], v[212:215], v[94:97]
	v_mfma_f32_16x16x32_bf16 v[90:93], v[172:175], v[212:215], v[90:93]
	v_mfma_f32_16x16x32_bf16 v[90:93], v[168:171], v[208:211], v[90:93]
	v_mfma_f32_16x16x32_bf16 v[74:77], v[168:171], v[216:219], v[74:77]
	v_mfma_f32_16x16x32_bf16 v[74:77], v[172:175], v[220:223], v[74:77]
	v_mfma_f32_16x16x32_bf16 v[78:81], v[164:167], v[220:223], v[78:81]
	v_mfma_f32_16x16x32_bf16 v[78:81], v[146:149], v[216:219], v[78:81]
	s_setprio 0
	s_setprio 1
	v_mfma_f32_16x16x32_bf16 v[118:121], v[176:179], v[192:195], v[118:121]
	v_mfma_f32_16x16x32_bf16 v[118:121], v[180:183], v[196:199], v[118:121]
	v_mfma_f32_16x16x32_bf16 v[114:117], v[188:191], v[196:199], v[114:117]
	v_mfma_f32_16x16x32_bf16 v[114:117], v[184:187], v[192:195], v[114:117]
	v_mfma_f32_16x16x32_bf16 v[98:101], v[184:187], v[200:203], v[98:101]
	v_mfma_f32_16x16x32_bf16 v[98:101], v[188:191], v[204:207], v[98:101]
	v_mfma_f32_16x16x32_bf16 v[102:105], v[180:183], v[204:207], v[102:105]
	v_mfma_f32_16x16x32_bf16 v[102:105], v[176:179], v[200:203], v[102:105]
	v_mfma_f32_16x16x32_bf16 v[86:89], v[176:179], v[208:211], v[86:89]
	v_mfma_f32_16x16x32_bf16 v[86:89], v[180:183], v[212:215], v[86:89]
	v_mfma_f32_16x16x32_bf16 v[82:85], v[188:191], v[212:215], v[82:85]
	v_mfma_f32_16x16x32_bf16 v[82:85], v[184:187], v[208:211], v[82:85]
	v_mfma_f32_16x16x32_bf16 v[66:69], v[184:187], v[216:219], v[66:69]
	v_mfma_f32_16x16x32_bf16 v[66:69], v[188:191], v[220:223], v[66:69]
	v_mfma_f32_16x16x32_bf16 v[70:73], v[180:183], v[220:223], v[70:73]
	v_mfma_f32_16x16x32_bf16 v[70:73], v[176:179], v[216:219], v[70:73]
	s_setprio 0
	s_barrier
	s_add_i32 s34, s53, s38
	v_lshl_add_u64 v[150:151], v[150:151], 0, s[10:11]
	s_mov_b32 m0, s34
	ds_read_b128 v[192:195], v159 offset:49152
	ds_read_b128 v[196:199], v159 offset:50176
	ds_read_b128 v[200:203], v159 offset:51200
	ds_read_b128 v[204:207], v159 offset:52224
	ds_read_b128 v[208:211], v159 offset:53248
	ds_read_b128 v[212:215], v159 offset:54272
	ds_read_b128 v[216:219], v159 offset:55296
	ds_read_b128 v[220:223], v159 offset:56320
	global_load_lds_dwordx4 v[150:151], off
	s_add_i32 m0, s34, 0x2000
	s_add_u32 s26, s26, 0x100080
	v_lshl_add_u64 v[150:151], v[160:161], 0, s[10:11]
	s_addc_u32 s27, s27, 0
	s_add_i32 s34, s54, s38
	global_load_lds_dwordx4 v[150:151], off
	s_mov_b32 m0, s34
	s_nop 0
	global_load_lds_dwordx4 v132, s[26:27]
	s_add_i32 m0, s34, 0x2000
	s_nop 0
	global_load_lds_dwordx4 v134, s[26:27]
	v_lshl_add_u64 v[150:151], v[224:225], 0, s[10:11]
	s_mov_b32 m0, s43
	s_nop 0
	global_load_lds_dwordx4 v[150:151], off
	v_lshl_add_u64 v[150:151], v[226:227], 0, s[10:11]
	s_mov_b32 m0, s44
	s_nop 0
	global_load_lds_dwordx4 v[150:151], off
	s_waitcnt vmcnt(8)
	s_waitcnt lgkmcnt(0)
	s_barrier
	s_setprio 1
	s_waitcnt lgkmcnt(0)
	v_mfma_f32_16x16x32_bf16 v[62:65], v[146:149], v[192:195], v[62:65]
	v_mfma_f32_16x16x32_bf16 v[62:65], v[164:167], v[196:199], v[62:65]
	v_mfma_f32_16x16x32_bf16 v[58:61], v[172:175], v[196:199], v[58:61]
	v_mfma_f32_16x16x32_bf16 v[58:61], v[168:171], v[192:195], v[58:61]
	v_mfma_f32_16x16x32_bf16 v[42:45], v[168:171], v[200:203], v[42:45]
	v_mfma_f32_16x16x32_bf16 v[42:45], v[172:175], v[204:207], v[42:45]
	v_mfma_f32_16x16x32_bf16 v[46:49], v[164:167], v[204:207], v[46:49]
	v_mfma_f32_16x16x32_bf16 v[46:49], v[146:149], v[200:203], v[46:49]
	v_mfma_f32_16x16x32_bf16 v[30:33], v[146:149], v[208:211], v[30:33]
	v_mfma_f32_16x16x32_bf16 v[30:33], v[164:167], v[212:215], v[30:33]
	v_mfma_f32_16x16x32_bf16 v[26:29], v[172:175], v[212:215], v[26:29]
	v_mfma_f32_16x16x32_bf16 v[26:29], v[168:171], v[208:211], v[26:29]
	v_mfma_f32_16x16x32_bf16 v[10:13], v[168:171], v[216:219], v[10:13]
	v_mfma_f32_16x16x32_bf16 v[10:13], v[172:175], v[220:223], v[10:13]
	v_mfma_f32_16x16x32_bf16 v[14:17], v[164:167], v[220:223], v[14:17]
	v_mfma_f32_16x16x32_bf16 v[14:17], v[146:149], v[216:219], v[14:17]
	s_setprio 0
	s_setprio 1
	v_mfma_f32_16x16x32_bf16 v[54:57], v[176:179], v[192:195], v[54:57]
	v_mfma_f32_16x16x32_bf16 v[54:57], v[180:183], v[196:199], v[54:57]
	v_mfma_f32_16x16x32_bf16 v[50:53], v[188:191], v[196:199], v[50:53]
	v_mfma_f32_16x16x32_bf16 v[50:53], v[184:187], v[192:195], v[50:53]
	v_mfma_f32_16x16x32_bf16 v[34:37], v[184:187], v[200:203], v[34:37]
	v_mfma_f32_16x16x32_bf16 v[34:37], v[188:191], v[204:207], v[34:37]
	v_mfma_f32_16x16x32_bf16 v[38:41], v[180:183], v[204:207], v[38:41]
	v_mfma_f32_16x16x32_bf16 v[38:41], v[176:179], v[200:203], v[38:41]
	v_mfma_f32_16x16x32_bf16 v[22:25], v[176:179], v[208:211], v[22:25]
	v_mfma_f32_16x16x32_bf16 v[22:25], v[180:183], v[212:215], v[22:25]
	v_mfma_f32_16x16x32_bf16 v[18:21], v[188:191], v[212:215], v[18:21]
	v_mfma_f32_16x16x32_bf16 v[18:21], v[184:187], v[208:211], v[18:21]
	v_mfma_f32_16x16x32_bf16 v[2:5], v[184:187], v[216:219], v[2:5]
	v_mfma_f32_16x16x32_bf16 v[2:5], v[188:191], v[220:223], v[2:5]
	v_mfma_f32_16x16x32_bf16 v[6:9], v[180:183], v[220:223], v[6:9]
	v_mfma_f32_16x16x32_bf16 v[6:9], v[176:179], v[216:219], v[6:9]
	s_setprio 0
	s_barrier
	s_add_i32 s52, s52, 2
	s_add_u32 s24, s24, 0x100
	s_addc_u32 s25, s25, 0
	s_add_u32 s50, s50, 0x100
	s_addc_u32 s51, s51, 0
	s_cmp_gt_u32 s52, 61
	s_cbranch_scc0 .LBB0_2158
	s_and_b64 vcc, exec, s[12:13]
	s_cbranch_vccz .LBB0_2161
	s_barrier
